# compute-segment critical path: redundant lgkmcnt ladder waits (already covered by the pre-barrier lgkmcnt(0)) removed from MFMA segments; back-edge SALU kept after the barrier (off the compute tail)
# baseline (speedup 1.0000x reference)
; #define PG8_STAGE(bufoff, gbase, voff) do { _Pragma("unroll") for (int _i = 0; _i < 2; ++_i) { \
;         const unsigned _m0 = ldsu + (unsigned)(bufoff) + ldsw + (unsigned)(_i * 8192); \
;         asm volatile("s_mov_b32 m0, %2\n\ts_nop 0\n\tglobal_load_lds_dwordx4 %0, %1" :: "v"((voff)[_i]), "s"((const char*)(gbase)), "s"(_m0) : "memory"); } } while (0)
; #define PG8_LDA(dst, b, h) do { _Pragma("unroll") for (int m = 0; m < 4; ++m) _Pragma("unroll") for (int k = 0; k < 2; ++k) dst[m][k] = *(const LAS bf16x8*)(lds + PG8_SA(b, h) + aoff + m * 2048 + k * 1024); } while (0)
; #define PG8_LDB(dst, b, h) do { _Pragma("unroll") for (int n = 0; n < 2; ++n) _Pragma("unroll") for (int k = 0; k < 2; ++k) dst[n][k] = *(const LAS bf16x8*)(lds + bbase[b][h] + n * 2048 + k * 1024); } while (0)
; #define PG8_WAIT_V(n) asm volatile("s_waitcnt vmcnt(" #n ")" ::: "memory")
; #define PG8_WAIT_L(n) asm volatile("s_waitcnt lgkmcnt(" #n ")" ::: "memory")
; #define PG8_BAR __builtin_amdgcn_s_barrier()
; #define PG8_SCHED __builtin_amdgcn_sched_barrier(0)
; template <class Epi>
; __device__ __forceinline__ void gemm_phase(LAS unsigned char* lds, const Gemm g, const StaticOrder& S, const Epi& E) {
;     ...
;         for (int t = 0; t < nt; t += 2) {
;             const bool last = (t == nt - 2);
;             const char* a2 = last ? nA : cA + (size_t)(t + 2) * kstep; const char* b2 = last ? nB : cB + (size_t)(t + 2) * kstep;
;             const char* a3 = a2 + kstep; const char* b3 = b2 + kstep;
;             const char* b1 = cB + (size_t)(t + 1) * kstep;
;             PG8_LDB(B0, 0, 0); PG8_SCHED; PG8_LDA(At, 0, 0); PG8_LDA(At2, 0, 1); PG8_STAGE(PG8_SB(1, 1), b1 + hstepB, voffB);
;             PG8_WAIT_V(8); PG8_WAIT_L(0); PG8_BAR; PG8_MMA2B(0, At, At2, B0); PG8_BAR; PG8_SCHED;
;             PG8_LDB(B0, 0, 1); PG8_STAGE(PG8_SB(0, 0), b2, voffB); PG8_STAGE(PG8_SA(0, 0), a2, voffA); PG8_STAGE(PG8_SA(0, 1), a2 + hstepA, voffA);
;             PG8_WAIT_V(8); PG8_WAIT_L(0); PG8_BAR; PG8_MMA2B(1, At, At2, B0); PG8_BAR; PG8_SCHED;
.LBB0_233:
	ds_read_b128 v[130:133], v142
	ds_read_b128 v[148:151], v142 offset:1024
	ds_read_b128 v[152:155], v142 offset:2048
	ds_read_b128 v[156:159], v142 offset:3072
	s_add_u32 s8, s4, 0x100
	s_addc_u32 s9, s5, 0
	s_cmp_eq_u32 s62, 12
	s_cselect_b32 s10, s58, s60
	s_cselect_b32 s11, s15, s61
	s_cselect_b32 s80, s59, s8
	s_cselect_b32 s81, s13, s9
	s_add_u32 s38, s10, 0x80
	s_addc_u32 s39, s11, 0
	ds_read_b128 v[166:169], v143
	ds_read_b128 v[178:181], v143 offset:1024
	ds_read_b128 v[182:185], v143 offset:2048
	ds_read_b128 v[186:189], v143 offset:3072
	ds_read_b128 v[190:193], v143 offset:4096
	ds_read_b128 v[194:197], v143 offset:5120
	ds_read_b128 v[198:201], v143 offset:6144
	ds_read_b128 v[202:205], v143 offset:7168
	ds_read_b128 v[214:217], v143 offset:16384
	ds_read_b128 v[218:221], v143 offset:17408
	ds_read_b128 v[222:225], v143 offset:18432
	ds_read_b128 v[226:229], v143 offset:19456
	ds_read_b128 v[230:233], v143 offset:20480
	ds_read_b128 v[234:237], v143 offset:21504
	ds_read_b128 v[238:241], v143 offset:22528
	ds_read_b128 v[242:245], v143 offset:23552
	s_add_u32 s4, s4, 0x40080
	s_addc_u32 s5, s5, 0
	s_mov_b32 m0, s84
	s_nop 0
	global_load_lds_dwordx4 v137, s[4:5]
	s_mov_b32 m0, s85
	s_nop 0
	global_load_lds_dwordx4 v139, s[4:5]
	s_waitcnt vmcnt(8)
	s_waitcnt lgkmcnt(0)
	s_barrier
	v_mfma_f32_16x16x32_bf16 v[124:127], v[130:133], v[166:169], v[124:127]
	v_mfma_f32_16x16x32_bf16 v[120:123], v[152:155], v[166:169], v[120:123]
	v_mfma_f32_16x16x32_bf16 v[108:111], v[130:133], v[182:185], v[108:111]
	v_mfma_f32_16x16x32_bf16 v[104:107], v[152:155], v[182:185], v[104:107]
	v_mfma_f32_16x16x32_bf16 v[92:95], v[130:133], v[190:193], v[92:95]
	v_mfma_f32_16x16x32_bf16 v[88:91], v[152:155], v[190:193], v[88:91]
	v_mfma_f32_16x16x32_bf16 v[76:79], v[130:133], v[198:201], v[76:79]
	v_mfma_f32_16x16x32_bf16 v[72:75], v[152:155], v[198:201], v[72:75]
	v_mfma_f32_16x16x32_bf16 v[60:63], v[130:133], v[214:217], v[60:63]
	v_mfma_f32_16x16x32_bf16 v[56:59], v[152:155], v[214:217], v[56:59]
	v_mfma_f32_16x16x32_bf16 v[44:47], v[130:133], v[222:225], v[44:47]
	v_mfma_f32_16x16x32_bf16 v[40:43], v[152:155], v[222:225], v[40:43]
	v_mfma_f32_16x16x32_bf16 v[28:31], v[130:133], v[230:233], v[28:31]
	v_mfma_f32_16x16x32_bf16 v[24:27], v[152:155], v[230:233], v[24:27]
	v_mfma_f32_16x16x32_bf16 v[12:15], v[130:133], v[238:241], v[12:15]
	v_mfma_f32_16x16x32_bf16 v[8:11], v[152:155], v[238:241], v[8:11]
	v_mfma_f32_16x16x32_bf16 v[124:127], v[148:151], v[178:181], v[124:127]
	v_mfma_f32_16x16x32_bf16 v[120:123], v[156:159], v[178:181], v[120:123]
	v_mfma_f32_16x16x32_bf16 v[108:111], v[148:151], v[186:189], v[108:111]
	v_mfma_f32_16x16x32_bf16 v[104:107], v[156:159], v[186:189], v[104:107]
	v_mfma_f32_16x16x32_bf16 v[92:95], v[148:151], v[194:197], v[92:95]
	v_mfma_f32_16x16x32_bf16 v[88:91], v[156:159], v[194:197], v[88:91]
	v_mfma_f32_16x16x32_bf16 v[76:79], v[148:151], v[202:205], v[76:79]
	v_mfma_f32_16x16x32_bf16 v[72:75], v[156:159], v[202:205], v[72:75]
	v_mfma_f32_16x16x32_bf16 v[60:63], v[148:151], v[218:221], v[60:63]
	v_mfma_f32_16x16x32_bf16 v[56:59], v[156:159], v[218:221], v[56:59]
	v_mfma_f32_16x16x32_bf16 v[44:47], v[148:151], v[226:229], v[44:47]
	v_mfma_f32_16x16x32_bf16 v[40:43], v[156:159], v[226:229], v[40:43]
	v_mfma_f32_16x16x32_bf16 v[28:31], v[148:151], v[234:237], v[28:31]
	v_mfma_f32_16x16x32_bf16 v[24:27], v[156:159], v[234:237], v[24:27]
	v_mfma_f32_16x16x32_bf16 v[12:15], v[148:151], v[242:245], v[12:15]
	v_mfma_f32_16x16x32_bf16 v[8:11], v[156:159], v[242:245], v[8:11]
	s_barrier
	ds_read_b128 v[130:133], v144
	ds_read_b128 v[148:151], v144 offset:1024
	ds_read_b128 v[152:155], v144 offset:2048
	ds_read_b128 v[156:159], v144 offset:3072
	s_mov_b32 m0, s29
	s_nop 0
	global_load_lds_dwordx4 v137, s[80:81]
	s_mov_b32 m0, s37
	s_nop 0
	global_load_lds_dwordx4 v139, s[80:81]
	s_mov_b32 m0, s28
	s_nop 0
	global_load_lds_dwordx4 v136, s[10:11]
	s_mov_b32 m0, s47
	s_nop 0
	global_load_lds_dwordx4 v138, s[10:11]
	s_add_u32 s4, s10, 0x40000
	s_addc_u32 s5, s11, 0
	s_mov_b32 m0, s48
	s_nop 0
	global_load_lds_dwordx4 v136, s[4:5]
	s_mov_b32 m0, s49
	s_nop 0
	global_load_lds_dwordx4 v138, s[4:5]
	s_waitcnt vmcnt(8)
	s_waitcnt lgkmcnt(0)
	s_barrier
	v_mfma_f32_16x16x32_bf16 v[116:119], v[130:133], v[166:169], v[116:119]
	v_mfma_f32_16x16x32_bf16 v[112:115], v[152:155], v[166:169], v[112:115]
	v_mfma_f32_16x16x32_bf16 v[100:103], v[130:133], v[182:185], v[100:103]
	v_mfma_f32_16x16x32_bf16 v[96:99], v[152:155], v[182:185], v[96:99]
	v_mfma_f32_16x16x32_bf16 v[84:87], v[130:133], v[190:193], v[84:87]
	v_mfma_f32_16x16x32_bf16 v[80:83], v[152:155], v[190:193], v[80:83]
	v_mfma_f32_16x16x32_bf16 v[68:71], v[130:133], v[198:201], v[68:71]
	v_mfma_f32_16x16x32_bf16 v[64:67], v[152:155], v[198:201], v[64:67]
	v_mfma_f32_16x16x32_bf16 v[52:55], v[130:133], v[214:217], v[52:55]
	v_mfma_f32_16x16x32_bf16 v[48:51], v[152:155], v[214:217], v[48:51]
	v_mfma_f32_16x16x32_bf16 v[36:39], v[130:133], v[222:225], v[36:39]
	v_mfma_f32_16x16x32_bf16 v[32:35], v[152:155], v[222:225], v[32:35]
	v_mfma_f32_16x16x32_bf16 v[20:23], v[130:133], v[230:233], v[20:23]
	v_mfma_f32_16x16x32_bf16 v[16:19], v[152:155], v[230:233], v[16:19]
	v_mfma_f32_16x16x32_bf16 v[4:7], v[130:133], v[238:241], v[4:7]
	v_mfma_f32_16x16x32_bf16 v[0:3], v[152:155], v[238:241], v[0:3]
	v_mfma_f32_16x16x32_bf16 v[116:119], v[148:151], v[178:181], v[116:119]
	v_mfma_f32_16x16x32_bf16 v[112:115], v[156:159], v[178:181], v[112:115]
	v_mfma_f32_16x16x32_bf16 v[100:103], v[148:151], v[186:189], v[100:103]
	v_mfma_f32_16x16x32_bf16 v[96:99], v[156:159], v[186:189], v[96:99]
	v_mfma_f32_16x16x32_bf16 v[84:87], v[148:151], v[194:197], v[84:87]
	v_mfma_f32_16x16x32_bf16 v[80:83], v[156:159], v[194:197], v[80:83]
	v_mfma_f32_16x16x32_bf16 v[68:71], v[148:151], v[202:205], v[68:71]
	v_mfma_f32_16x16x32_bf16 v[64:67], v[156:159], v[202:205], v[64:67]
	v_mfma_f32_16x16x32_bf16 v[52:55], v[148:151], v[218:221], v[52:55]
	v_mfma_f32_16x16x32_bf16 v[48:51], v[156:159], v[218:221], v[48:51]
	v_mfma_f32_16x16x32_bf16 v[36:39], v[148:151], v[226:229], v[36:39]
	v_mfma_f32_16x16x32_bf16 v[32:35], v[156:159], v[226:229], v[32:35]
	v_mfma_f32_16x16x32_bf16 v[20:23], v[148:151], v[234:237], v[20:23]
	v_mfma_f32_16x16x32_bf16 v[16:19], v[156:159], v[234:237], v[16:19]
	v_mfma_f32_16x16x32_bf16 v[4:7], v[148:151], v[242:245], v[4:7]
	v_mfma_f32_16x16x32_bf16 v[0:3], v[156:159], v[242:245], v[0:3]
	s_barrier
; #define PG8_STAGE(bufoff, gbase, voff) do { _Pragma("unroll") for (int _i = 0; _i < 2; ++_i) { \
;         const unsigned _m0 = ldsu + (unsigned)(bufoff) + ldsw + (unsigned)(_i * 8192); \
;         asm volatile("s_mov_b32 m0, %2\n\ts_nop 0\n\tglobal_load_lds_dwordx4 %0, %1" :: "v"((voff)[_i]), "s"((const char*)(gbase)), "s"(_m0) : "memory"); } } while (0)
; #define PG8_LDA(dst, b, h) do { _Pragma("unroll") for (int m = 0; m < 4; ++m) _Pragma("unroll") for (int k = 0; k < 2; ++k) dst[m][k] = *(const LAS bf16x8*)(lds + PG8_SA(b, h) + aoff + m * 2048 + k * 1024); } while (0)
; #define PG8_LDB(dst, b, h) do { _Pragma("unroll") for (int n = 0; n < 2; ++n) _Pragma("unroll") for (int k = 0; k < 2; ++k) dst[n][k] = *(const LAS bf16x8*)(lds + bbase[b][h] + n * 2048 + k * 1024); } while (0)
; #define PG8_WAIT_V(n) asm volatile("s_waitcnt vmcnt(" #n ")" ::: "memory")
; #define PG8_WAIT_L(n) asm volatile("s_waitcnt lgkmcnt(" #n ")" ::: "memory")
; #define PG8_BAR __builtin_amdgcn_s_barrier()
; #define PG8_SCHED __builtin_amdgcn_sched_barrier(0)
; template <class Epi>
; __device__ __forceinline__ void gemm_phase(LAS unsigned char* lds, const Gemm g, const StaticOrder& S, const Epi& E) {
;     ...
;             PG8_LDB(B0, 1, 0); PG8_SCHED; PG8_LDA(At, 1, 0); PG8_LDA(At2, 1, 1); PG8_STAGE(PG8_SB(0, 1), b2 + hstepB, voffB);
;             PG8_WAIT_V(8); PG8_WAIT_L(0); PG8_BAR; PG8_MMA2B(0, At, At2, B0); PG8_BAR; PG8_SCHED;
;             PG8_LDB(B0, 1, 1); PG8_STAGE(PG8_SB(1, 0), b3, voffB); PG8_STAGE(PG8_SA(1, 0), a3, voffA); PG8_STAGE(PG8_SA(1, 1), a3 + hstepA, voffA);
;             PG8_WAIT_V(8); PG8_WAIT_L(0); PG8_BAR; PG8_MMA2B(1, At, At2, B0); PG8_BAR; PG8_SCHED;
;         }
;         if (wr == 0) PG8_BAR;
	ds_read_b128 v[130:133], v145
	ds_read_b128 v[148:151], v145 offset:1024
	ds_read_b128 v[152:155], v145 offset:2048
	ds_read_b128 v[156:159], v145 offset:3072
	ds_read_b128 v[166:169], v143 offset:32768
	ds_read_b128 v[178:181], v143 offset:33792
	ds_read_b128 v[182:185], v143 offset:34816
	ds_read_b128 v[186:189], v143 offset:35840
	ds_read_b128 v[190:193], v143 offset:36864
	ds_read_b128 v[194:197], v143 offset:37888
	ds_read_b128 v[198:201], v143 offset:38912
	ds_read_b128 v[202:205], v143 offset:39936
	ds_read_b128 v[214:217], v143 offset:49152
	ds_read_b128 v[218:221], v143 offset:50176
	ds_read_b128 v[222:225], v143 offset:51200
	ds_read_b128 v[226:229], v143 offset:52224
	ds_read_b128 v[230:233], v143 offset:53248
	ds_read_b128 v[234:237], v143 offset:54272
	ds_read_b128 v[238:241], v143 offset:55296
	ds_read_b128 v[242:245], v143 offset:56320
	s_add_u32 s4, s80, 0x40000
	s_addc_u32 s5, s81, 0
	s_mov_b32 m0, s50
	s_nop 0
	global_load_lds_dwordx4 v137, s[4:5]
	s_mov_b32 m0, s51
	s_nop 0
	global_load_lds_dwordx4 v139, s[4:5]
	s_waitcnt vmcnt(8)
	s_waitcnt lgkmcnt(0)
	s_barrier
	v_mfma_f32_16x16x32_bf16 v[124:127], v[130:133], v[166:169], v[124:127]
	v_mfma_f32_16x16x32_bf16 v[120:123], v[152:155], v[166:169], v[120:123]
	v_mfma_f32_16x16x32_bf16 v[108:111], v[130:133], v[182:185], v[108:111]
	v_mfma_f32_16x16x32_bf16 v[104:107], v[152:155], v[182:185], v[104:107]
	v_mfma_f32_16x16x32_bf16 v[92:95], v[130:133], v[190:193], v[92:95]
	v_mfma_f32_16x16x32_bf16 v[88:91], v[152:155], v[190:193], v[88:91]
	v_mfma_f32_16x16x32_bf16 v[76:79], v[130:133], v[198:201], v[76:79]
	v_mfma_f32_16x16x32_bf16 v[72:75], v[152:155], v[198:201], v[72:75]
	v_mfma_f32_16x16x32_bf16 v[60:63], v[130:133], v[214:217], v[60:63]
	v_mfma_f32_16x16x32_bf16 v[56:59], v[152:155], v[214:217], v[56:59]
	v_mfma_f32_16x16x32_bf16 v[44:47], v[130:133], v[222:225], v[44:47]
	v_mfma_f32_16x16x32_bf16 v[40:43], v[152:155], v[222:225], v[40:43]
	v_mfma_f32_16x16x32_bf16 v[28:31], v[130:133], v[230:233], v[28:31]
	v_mfma_f32_16x16x32_bf16 v[24:27], v[152:155], v[230:233], v[24:27]
	v_mfma_f32_16x16x32_bf16 v[12:15], v[130:133], v[238:241], v[12:15]
	v_mfma_f32_16x16x32_bf16 v[8:11], v[152:155], v[238:241], v[8:11]
	v_mfma_f32_16x16x32_bf16 v[124:127], v[148:151], v[178:181], v[124:127]
	v_mfma_f32_16x16x32_bf16 v[120:123], v[156:159], v[178:181], v[120:123]
	v_mfma_f32_16x16x32_bf16 v[108:111], v[148:151], v[186:189], v[108:111]
	v_mfma_f32_16x16x32_bf16 v[104:107], v[156:159], v[186:189], v[104:107]
	v_mfma_f32_16x16x32_bf16 v[92:95], v[148:151], v[194:197], v[92:95]
	v_mfma_f32_16x16x32_bf16 v[88:91], v[156:159], v[194:197], v[88:91]
	v_mfma_f32_16x16x32_bf16 v[76:79], v[148:151], v[202:205], v[76:79]
	v_mfma_f32_16x16x32_bf16 v[72:75], v[156:159], v[202:205], v[72:75]
	v_mfma_f32_16x16x32_bf16 v[60:63], v[148:151], v[218:221], v[60:63]
	v_mfma_f32_16x16x32_bf16 v[56:59], v[156:159], v[218:221], v[56:59]
	v_mfma_f32_16x16x32_bf16 v[44:47], v[148:151], v[226:229], v[44:47]
	v_mfma_f32_16x16x32_bf16 v[40:43], v[156:159], v[226:229], v[40:43]
	v_mfma_f32_16x16x32_bf16 v[28:31], v[148:151], v[234:237], v[28:31]
	v_mfma_f32_16x16x32_bf16 v[24:27], v[156:159], v[234:237], v[24:27]
	v_mfma_f32_16x16x32_bf16 v[12:15], v[148:151], v[242:245], v[12:15]
	v_mfma_f32_16x16x32_bf16 v[8:11], v[156:159], v[242:245], v[8:11]
	s_barrier
	s_add_u32 s4, s80, 0x80
	ds_read_b128 v[130:133], v146
	ds_read_b128 v[148:151], v146 offset:1024
	ds_read_b128 v[152:155], v146 offset:2048
	ds_read_b128 v[156:159], v146 offset:3072
	s_addc_u32 s5, s81, 0
	s_mov_b32 m0, s52
	s_nop 0
	global_load_lds_dwordx4 v137, s[4:5]
	s_mov_b32 m0, s53
	s_nop 0
	global_load_lds_dwordx4 v139, s[4:5]
	s_mov_b32 m0, s54
	s_nop 0
	global_load_lds_dwordx4 v136, s[38:39]
	s_mov_b32 m0, s55
	s_nop 0
	global_load_lds_dwordx4 v138, s[38:39]
	s_add_u32 s4, s10, 0x40080
	s_addc_u32 s5, s11, 0
	s_mov_b32 m0, s82
	s_nop 0
	global_load_lds_dwordx4 v136, s[4:5]
	s_mov_b32 m0, s83
	s_nop 0
	global_load_lds_dwordx4 v138, s[4:5]
	s_waitcnt vmcnt(8)
	s_waitcnt lgkmcnt(0)
	s_barrier
	v_mfma_f32_16x16x32_bf16 v[116:119], v[130:133], v[166:169], v[116:119]
	v_mfma_f32_16x16x32_bf16 v[112:115], v[152:155], v[166:169], v[112:115]
	v_mfma_f32_16x16x32_bf16 v[100:103], v[130:133], v[182:185], v[100:103]
	v_mfma_f32_16x16x32_bf16 v[96:99], v[152:155], v[182:185], v[96:99]
	v_mfma_f32_16x16x32_bf16 v[84:87], v[130:133], v[190:193], v[84:87]
	v_mfma_f32_16x16x32_bf16 v[80:83], v[152:155], v[190:193], v[80:83]
	v_mfma_f32_16x16x32_bf16 v[68:71], v[130:133], v[198:201], v[68:71]
	v_mfma_f32_16x16x32_bf16 v[64:67], v[152:155], v[198:201], v[64:67]
	v_mfma_f32_16x16x32_bf16 v[52:55], v[130:133], v[214:217], v[52:55]
	v_mfma_f32_16x16x32_bf16 v[48:51], v[152:155], v[214:217], v[48:51]
	v_mfma_f32_16x16x32_bf16 v[36:39], v[130:133], v[222:225], v[36:39]
	v_mfma_f32_16x16x32_bf16 v[32:35], v[152:155], v[222:225], v[32:35]
	v_mfma_f32_16x16x32_bf16 v[20:23], v[130:133], v[230:233], v[20:23]
	v_mfma_f32_16x16x32_bf16 v[16:19], v[152:155], v[230:233], v[16:19]
	v_mfma_f32_16x16x32_bf16 v[4:7], v[130:133], v[238:241], v[4:7]
	v_mfma_f32_16x16x32_bf16 v[0:3], v[152:155], v[238:241], v[0:3]
	v_mfma_f32_16x16x32_bf16 v[116:119], v[148:151], v[178:181], v[116:119]
	v_mfma_f32_16x16x32_bf16 v[112:115], v[156:159], v[178:181], v[112:115]
	v_mfma_f32_16x16x32_bf16 v[100:103], v[148:151], v[186:189], v[100:103]
	v_mfma_f32_16x16x32_bf16 v[96:99], v[156:159], v[186:189], v[96:99]
	v_mfma_f32_16x16x32_bf16 v[84:87], v[148:151], v[194:197], v[84:87]
	v_mfma_f32_16x16x32_bf16 v[80:83], v[156:159], v[194:197], v[80:83]
	v_mfma_f32_16x16x32_bf16 v[68:71], v[148:151], v[202:205], v[68:71]
	v_mfma_f32_16x16x32_bf16 v[64:67], v[156:159], v[202:205], v[64:67]
	v_mfma_f32_16x16x32_bf16 v[52:55], v[148:151], v[218:221], v[52:55]
	v_mfma_f32_16x16x32_bf16 v[48:51], v[156:159], v[218:221], v[48:51]
	v_mfma_f32_16x16x32_bf16 v[36:39], v[148:151], v[226:229], v[36:39]
	v_mfma_f32_16x16x32_bf16 v[32:35], v[156:159], v[226:229], v[32:35]
	v_mfma_f32_16x16x32_bf16 v[20:23], v[148:151], v[234:237], v[20:23]
	v_mfma_f32_16x16x32_bf16 v[16:19], v[156:159], v[234:237], v[16:19]
	v_mfma_f32_16x16x32_bf16 v[4:7], v[148:151], v[242:245], v[4:7]
	v_mfma_f32_16x16x32_bf16 v[0:3], v[156:159], v[242:245], v[0:3]
	s_barrier
	s_add_i32 s62, s62, 2
	s_add_u32 s60, s60, 0x100
	s_addc_u32 s61, s61, 0
	s_cmp_gt_u32 s62, 13
	s_mov_b64 s[4:5], s[8:9]
	s_cbranch_scc0 .LBB0_233
	s_and_b64 vcc, exec, s[2:3]
	s_cbranch_vccz .LBB0_236
	s_barrier

; #define PG8_STAGE(bufoff, gbase, voff) do { _Pragma("unroll") for (int _i = 0; _i < 2; ++_i) { \
;         const unsigned _m0 = ldsu + (unsigned)(bufoff) + ldsw + (unsigned)(_i * 8192); \
;         asm volatile("s_mov_b32 m0, %2\n\ts_nop 0\n\tglobal_load_lds_dwordx4 %0, %1" :: "v"((voff)[_i]), "s"((const char*)(gbase)), "s"(_m0) : "memory"); } } while (0)
; #define PG8_LDA(dst, b, h) do { _Pragma("unroll") for (int m = 0; m < 4; ++m) _Pragma("unroll") for (int k = 0; k < 2; ++k) dst[m][k] = *(const LAS bf16x8*)(lds + PG8_SA(b, h) + aoff + m * 2048 + k * 1024); } while (0)
; #define PG8_LDB(dst, b, h) do { _Pragma("unroll") for (int n = 0; n < 2; ++n) _Pragma("unroll") for (int k = 0; k < 2; ++k) dst[n][k] = *(const LAS bf16x8*)(lds + bbase[b][h] + n * 2048 + k * 1024); } while (0)
; #define PG8_WAIT_V(n) asm volatile("s_waitcnt vmcnt(" #n ")" ::: "memory")
; #define PG8_WAIT_L(n) asm volatile("s_waitcnt lgkmcnt(" #n ")" ::: "memory")
; #define PG8_BAR __builtin_amdgcn_s_barrier()
; #define PG8_SCHED __builtin_amdgcn_sched_barrier(0)
; template <class Epi>
; __device__ __forceinline__ void gemm_phase(LAS unsigned char* lds, const Gemm g, const StaticOrder& S, const Epi& E) {
;     ...
;         for (int t = 0; t < nt; t += 2) {
;             const bool last = (t == nt - 2);
;             const char* a2 = last ? nA : cA + (size_t)(t + 2) * kstep; const char* b2 = last ? nB : cB + (size_t)(t + 2) * kstep;
;             const char* a3 = a2 + kstep; const char* b3 = b2 + kstep;
;             const char* b1 = cB + (size_t)(t + 1) * kstep;
;             PG8_LDB(B0, 0, 0); PG8_SCHED; PG8_LDA(At, 0, 0); PG8_LDA(At2, 0, 1); PG8_STAGE(PG8_SB(1, 1), b1 + hstepB, voffB);
;             PG8_WAIT_V(8); PG8_WAIT_L(0); PG8_BAR; PG8_MMA2B(0, At, At2, B0); PG8_BAR; PG8_SCHED;
;             PG8_LDB(B0, 0, 1); PG8_STAGE(PG8_SB(0, 0), b2, voffB); PG8_STAGE(PG8_SA(0, 0), a2, voffA); PG8_STAGE(PG8_SA(0, 1), a2 + hstepA, voffA);
;             PG8_WAIT_V(8); PG8_WAIT_L(0); PG8_BAR; PG8_MMA2B(1, At, At2, B0); PG8_BAR; PG8_SCHED;
.LBB0_487:
	s_add_i32 s69, s68, 2
	s_add_u32 s6, s88, 0x80
	ds_read_b128 v[140:143], v134
	ds_read_b128 v[144:147], v134 offset:1024
	ds_read_b128 v[148:151], v134 offset:2048
	ds_read_b128 v[152:155], v134 offset:3072
	s_addc_u32 s7, s89, 0
	s_cmp_eq_u32 s62, s68
	s_cselect_b32 s80, s17, s95
	s_cselect_b32 s81, s15, s96
	s_cselect_b32 s90, s87, s6
	s_cselect_b32 s91, s86, s7
	s_add_u32 s82, s80, 0x80
	s_addc_u32 s83, s81, 0
	s_add_u32 s84, s90, 0x80
	s_addc_u32 s85, s91, 0
	ds_read_b128 v[156:159], v135
	ds_read_b128 v[166:169], v135 offset:1024
	ds_read_b128 v[178:181], v135 offset:2048
	ds_read_b128 v[182:185], v135 offset:3072
	ds_read_b128 v[186:189], v135 offset:4096
	ds_read_b128 v[190:193], v135 offset:5120
	ds_read_b128 v[194:197], v135 offset:6144
	ds_read_b128 v[198:201], v135 offset:7168
	ds_read_b128 v[202:205], v135 offset:16384
	ds_read_b128 v[214:217], v135 offset:17408
	ds_read_b128 v[218:221], v135 offset:18432
	ds_read_b128 v[222:225], v135 offset:19456
	ds_read_b128 v[226:229], v135 offset:20480
	ds_read_b128 v[230:233], v135 offset:21504
	ds_read_b128 v[234:237], v135 offset:22528
	ds_read_b128 v[238:241], v135 offset:23552
	s_add_u32 s6, s88, 0x20000
	s_addc_u32 s7, s89, 0
	s_mov_b32 m0, s63
	s_nop 0
	global_load_lds_dwordx4 v129, s[6:7]
	s_mov_b32 m0, s64
	s_nop 0
	global_load_lds_dwordx4 v131, s[6:7]
	s_waitcnt vmcnt(8)
	s_waitcnt lgkmcnt(0)
	s_barrier
	v_mfma_f32_16x16x32_bf16 v[120:123], v[140:143], v[156:159], v[120:123]
	v_mfma_f32_16x16x32_bf16 v[124:127], v[148:151], v[156:159], v[124:127]
	v_mfma_f32_16x16x32_bf16 v[108:111], v[140:143], v[178:181], v[108:111]
	v_mfma_f32_16x16x32_bf16 v[104:107], v[148:151], v[178:181], v[104:107]
	v_mfma_f32_16x16x32_bf16 v[92:95], v[140:143], v[186:189], v[92:95]
	v_mfma_f32_16x16x32_bf16 v[88:91], v[148:151], v[186:189], v[88:91]
	v_mfma_f32_16x16x32_bf16 v[76:79], v[140:143], v[194:197], v[76:79]
	v_mfma_f32_16x16x32_bf16 v[72:75], v[148:151], v[194:197], v[72:75]
	v_mfma_f32_16x16x32_bf16 v[60:63], v[140:143], v[202:205], v[60:63]
	v_mfma_f32_16x16x32_bf16 v[56:59], v[148:151], v[202:205], v[56:59]
	v_mfma_f32_16x16x32_bf16 v[44:47], v[140:143], v[218:221], v[44:47]
	v_mfma_f32_16x16x32_bf16 v[40:43], v[148:151], v[218:221], v[40:43]
	v_mfma_f32_16x16x32_bf16 v[28:31], v[140:143], v[226:229], v[28:31]
	v_mfma_f32_16x16x32_bf16 v[24:27], v[148:151], v[226:229], v[24:27]
	v_mfma_f32_16x16x32_bf16 v[12:15], v[140:143], v[234:237], v[12:15]
	v_mfma_f32_16x16x32_bf16 v[8:11], v[148:151], v[234:237], v[8:11]
	v_mfma_f32_16x16x32_bf16 v[120:123], v[144:147], v[166:169], v[120:123]
	v_mfma_f32_16x16x32_bf16 v[124:127], v[152:155], v[166:169], v[124:127]
	v_mfma_f32_16x16x32_bf16 v[108:111], v[144:147], v[182:185], v[108:111]
	v_mfma_f32_16x16x32_bf16 v[104:107], v[152:155], v[182:185], v[104:107]
	v_mfma_f32_16x16x32_bf16 v[92:95], v[144:147], v[190:193], v[92:95]
	v_mfma_f32_16x16x32_bf16 v[88:91], v[152:155], v[190:193], v[88:91]
	v_mfma_f32_16x16x32_bf16 v[76:79], v[144:147], v[198:201], v[76:79]
	v_mfma_f32_16x16x32_bf16 v[72:75], v[152:155], v[198:201], v[72:75]
	v_mfma_f32_16x16x32_bf16 v[60:63], v[144:147], v[214:217], v[60:63]
	v_mfma_f32_16x16x32_bf16 v[56:59], v[152:155], v[214:217], v[56:59]
	v_mfma_f32_16x16x32_bf16 v[44:47], v[144:147], v[222:225], v[44:47]
	v_mfma_f32_16x16x32_bf16 v[40:43], v[152:155], v[222:225], v[40:43]
	v_mfma_f32_16x16x32_bf16 v[28:31], v[144:147], v[230:233], v[28:31]
	v_mfma_f32_16x16x32_bf16 v[24:27], v[152:155], v[230:233], v[24:27]
	v_mfma_f32_16x16x32_bf16 v[12:15], v[144:147], v[238:241], v[12:15]
	v_mfma_f32_16x16x32_bf16 v[8:11], v[152:155], v[238:241], v[8:11]
	s_barrier
	ds_read_b128 v[140:143], v136
	ds_read_b128 v[144:147], v136 offset:1024
	ds_read_b128 v[148:151], v136 offset:2048
	ds_read_b128 v[152:155], v136 offset:3072
	s_mov_b32 m0, s48
	s_nop 0
	global_load_lds_dwordx4 v129, s[90:91]
	s_mov_b32 m0, s49
	s_nop 0
	global_load_lds_dwordx4 v131, s[90:91]
	s_mov_b32 m0, s47
	s_nop 0
	global_load_lds_dwordx4 v128, s[80:81]
	s_mov_b32 m0, s50
	s_nop 0
	global_load_lds_dwordx4 v130, s[80:81]
	s_add_u32 s6, s80, 0x20000
	s_addc_u32 s7, s81, 0
	s_mov_b32 m0, s52
	s_nop 0
	global_load_lds_dwordx4 v128, s[6:7]
	s_mov_b32 m0, s53
	s_nop 0
	global_load_lds_dwordx4 v130, s[6:7]
	s_waitcnt vmcnt(8)
	s_waitcnt lgkmcnt(0)
	s_barrier
	v_mfma_f32_16x16x32_bf16 v[116:119], v[140:143], v[156:159], v[116:119]
	v_mfma_f32_16x16x32_bf16 v[112:115], v[148:151], v[156:159], v[112:115]
	v_mfma_f32_16x16x32_bf16 v[100:103], v[140:143], v[178:181], v[100:103]
	v_mfma_f32_16x16x32_bf16 v[96:99], v[148:151], v[178:181], v[96:99]
	v_mfma_f32_16x16x32_bf16 v[84:87], v[140:143], v[186:189], v[84:87]
	v_mfma_f32_16x16x32_bf16 v[80:83], v[148:151], v[186:189], v[80:83]
	v_mfma_f32_16x16x32_bf16 v[68:71], v[140:143], v[194:197], v[68:71]
	v_mfma_f32_16x16x32_bf16 v[64:67], v[148:151], v[194:197], v[64:67]
	v_mfma_f32_16x16x32_bf16 v[52:55], v[140:143], v[202:205], v[52:55]
	v_mfma_f32_16x16x32_bf16 v[48:51], v[148:151], v[202:205], v[48:51]
	v_mfma_f32_16x16x32_bf16 v[36:39], v[140:143], v[218:221], v[36:39]
	v_mfma_f32_16x16x32_bf16 v[32:35], v[148:151], v[218:221], v[32:35]
	v_mfma_f32_16x16x32_bf16 v[20:23], v[140:143], v[226:229], v[20:23]
	v_mfma_f32_16x16x32_bf16 v[16:19], v[148:151], v[226:229], v[16:19]
	v_mfma_f32_16x16x32_bf16 v[4:7], v[140:143], v[234:237], v[4:7]
	v_mfma_f32_16x16x32_bf16 v[0:3], v[148:151], v[234:237], v[0:3]
	v_mfma_f32_16x16x32_bf16 v[116:119], v[144:147], v[166:169], v[116:119]
	v_mfma_f32_16x16x32_bf16 v[112:115], v[152:155], v[166:169], v[112:115]
	v_mfma_f32_16x16x32_bf16 v[100:103], v[144:147], v[182:185], v[100:103]
	v_mfma_f32_16x16x32_bf16 v[96:99], v[152:155], v[182:185], v[96:99]
	v_mfma_f32_16x16x32_bf16 v[84:87], v[144:147], v[190:193], v[84:87]
	v_mfma_f32_16x16x32_bf16 v[80:83], v[152:155], v[190:193], v[80:83]
	v_mfma_f32_16x16x32_bf16 v[68:71], v[144:147], v[198:201], v[68:71]
	v_mfma_f32_16x16x32_bf16 v[64:67], v[152:155], v[198:201], v[64:67]
	v_mfma_f32_16x16x32_bf16 v[52:55], v[144:147], v[214:217], v[52:55]
	v_mfma_f32_16x16x32_bf16 v[48:51], v[152:155], v[214:217], v[48:51]
	v_mfma_f32_16x16x32_bf16 v[36:39], v[144:147], v[222:225], v[36:39]
	v_mfma_f32_16x16x32_bf16 v[32:35], v[152:155], v[222:225], v[32:35]
	v_mfma_f32_16x16x32_bf16 v[20:23], v[144:147], v[230:233], v[20:23]
	v_mfma_f32_16x16x32_bf16 v[16:19], v[152:155], v[230:233], v[16:19]
	v_mfma_f32_16x16x32_bf16 v[4:7], v[144:147], v[238:241], v[4:7]
	v_mfma_f32_16x16x32_bf16 v[0:3], v[152:155], v[238:241], v[0:3]
	s_barrier
; #define PG8_STAGE(bufoff, gbase, voff) do { _Pragma("unroll") for (int _i = 0; _i < 2; ++_i) { \
;         const unsigned _m0 = ldsu + (unsigned)(bufoff) + ldsw + (unsigned)(_i * 8192); \
;         asm volatile("s_mov_b32 m0, %2\n\ts_nop 0\n\tglobal_load_lds_dwordx4 %0, %1" :: "v"((voff)[_i]), "s"((const char*)(gbase)), "s"(_m0) : "memory"); } } while (0)
; #define PG8_LDA(dst, b, h) do { _Pragma("unroll") for (int m = 0; m < 4; ++m) _Pragma("unroll") for (int k = 0; k < 2; ++k) dst[m][k] = *(const LAS bf16x8*)(lds + PG8_SA(b, h) + aoff + m * 2048 + k * 1024); } while (0)
; #define PG8_LDB(dst, b, h) do { _Pragma("unroll") for (int n = 0; n < 2; ++n) _Pragma("unroll") for (int k = 0; k < 2; ++k) dst[n][k] = *(const LAS bf16x8*)(lds + bbase[b][h] + n * 2048 + k * 1024); } while (0)
; #define PG8_WAIT_V(n) asm volatile("s_waitcnt vmcnt(" #n ")" ::: "memory")
; #define PG8_WAIT_L(n) asm volatile("s_waitcnt lgkmcnt(" #n ")" ::: "memory")
; #define PG8_BAR __builtin_amdgcn_s_barrier()
; #define PG8_SCHED __builtin_amdgcn_sched_barrier(0)
; template <class Epi>
; __device__ __forceinline__ void gemm_phase(LAS unsigned char* lds, const Gemm g, const StaticOrder& S, const Epi& E) {
;     ...
;             PG8_LDB(B0, 1, 0); PG8_SCHED; PG8_LDA(At, 1, 0); PG8_LDA(At2, 1, 1); PG8_STAGE(PG8_SB(0, 1), b2 + hstepB, voffB);
;             PG8_WAIT_V(8); PG8_WAIT_L(0); PG8_BAR; PG8_MMA2B(0, At, At2, B0); PG8_BAR; PG8_SCHED;
;             PG8_LDB(B0, 1, 1); PG8_STAGE(PG8_SB(1, 0), b3, voffB); PG8_STAGE(PG8_SA(1, 0), a3, voffA); PG8_STAGE(PG8_SA(1, 1), a3 + hstepA, voffA);
;             PG8_WAIT_V(8); PG8_WAIT_L(0); PG8_BAR; PG8_MMA2B(1, At, At2, B0); PG8_BAR; PG8_SCHED;
;         }
	ds_read_b128 v[140:143], v137
	ds_read_b128 v[144:147], v137 offset:1024
	ds_read_b128 v[148:151], v137 offset:2048
	ds_read_b128 v[152:155], v137 offset:3072
	ds_read_b128 v[156:159], v135 offset:32768
	ds_read_b128 v[166:169], v135 offset:33792
	ds_read_b128 v[178:181], v135 offset:34816
	ds_read_b128 v[182:185], v135 offset:35840
	ds_read_b128 v[186:189], v135 offset:36864
	ds_read_b128 v[190:193], v135 offset:37888
	ds_read_b128 v[194:197], v135 offset:38912
	ds_read_b128 v[198:201], v135 offset:39936
	ds_read_b128 v[202:205], v135 offset:49152
	ds_read_b128 v[214:217], v135 offset:50176
	ds_read_b128 v[218:221], v135 offset:51200
	ds_read_b128 v[222:225], v135 offset:52224
	ds_read_b128 v[226:229], v135 offset:53248
	ds_read_b128 v[230:233], v135 offset:54272
	ds_read_b128 v[234:237], v135 offset:55296
	ds_read_b128 v[238:241], v135 offset:56320
	s_add_u32 s6, s90, 0x20000
	s_addc_u32 s7, s91, 0
	s_mov_b32 m0, s54
	s_nop 0
	global_load_lds_dwordx4 v129, s[6:7]
	s_mov_b32 m0, s55
	s_nop 0
	global_load_lds_dwordx4 v131, s[6:7]
	s_waitcnt vmcnt(8)
	s_waitcnt lgkmcnt(0)
	s_barrier
	v_mfma_f32_16x16x32_bf16 v[120:123], v[140:143], v[156:159], v[120:123]
	v_mfma_f32_16x16x32_bf16 v[124:127], v[148:151], v[156:159], v[124:127]
	v_mfma_f32_16x16x32_bf16 v[108:111], v[140:143], v[178:181], v[108:111]
	v_mfma_f32_16x16x32_bf16 v[104:107], v[148:151], v[178:181], v[104:107]
	v_mfma_f32_16x16x32_bf16 v[92:95], v[140:143], v[186:189], v[92:95]
	v_mfma_f32_16x16x32_bf16 v[88:91], v[148:151], v[186:189], v[88:91]
	v_mfma_f32_16x16x32_bf16 v[76:79], v[140:143], v[194:197], v[76:79]
	v_mfma_f32_16x16x32_bf16 v[72:75], v[148:151], v[194:197], v[72:75]
	v_mfma_f32_16x16x32_bf16 v[60:63], v[140:143], v[202:205], v[60:63]
	v_mfma_f32_16x16x32_bf16 v[56:59], v[148:151], v[202:205], v[56:59]
	v_mfma_f32_16x16x32_bf16 v[44:47], v[140:143], v[218:221], v[44:47]
	v_mfma_f32_16x16x32_bf16 v[40:43], v[148:151], v[218:221], v[40:43]
	v_mfma_f32_16x16x32_bf16 v[28:31], v[140:143], v[226:229], v[28:31]
	v_mfma_f32_16x16x32_bf16 v[24:27], v[148:151], v[226:229], v[24:27]
	v_mfma_f32_16x16x32_bf16 v[12:15], v[140:143], v[234:237], v[12:15]
	v_mfma_f32_16x16x32_bf16 v[8:11], v[148:151], v[234:237], v[8:11]
	v_mfma_f32_16x16x32_bf16 v[120:123], v[144:147], v[166:169], v[120:123]
	v_mfma_f32_16x16x32_bf16 v[124:127], v[152:155], v[166:169], v[124:127]
	v_mfma_f32_16x16x32_bf16 v[108:111], v[144:147], v[182:185], v[108:111]
	v_mfma_f32_16x16x32_bf16 v[104:107], v[152:155], v[182:185], v[104:107]
	v_mfma_f32_16x16x32_bf16 v[92:95], v[144:147], v[190:193], v[92:95]
	v_mfma_f32_16x16x32_bf16 v[88:91], v[152:155], v[190:193], v[88:91]
	v_mfma_f32_16x16x32_bf16 v[76:79], v[144:147], v[198:201], v[76:79]
	v_mfma_f32_16x16x32_bf16 v[72:75], v[152:155], v[198:201], v[72:75]
	v_mfma_f32_16x16x32_bf16 v[60:63], v[144:147], v[214:217], v[60:63]
	v_mfma_f32_16x16x32_bf16 v[56:59], v[152:155], v[214:217], v[56:59]
	v_mfma_f32_16x16x32_bf16 v[44:47], v[144:147], v[222:225], v[44:47]
	v_mfma_f32_16x16x32_bf16 v[40:43], v[152:155], v[222:225], v[40:43]
	v_mfma_f32_16x16x32_bf16 v[28:31], v[144:147], v[230:233], v[28:31]
	v_mfma_f32_16x16x32_bf16 v[24:27], v[152:155], v[230:233], v[24:27]
	v_mfma_f32_16x16x32_bf16 v[12:15], v[144:147], v[238:241], v[12:15]
	v_mfma_f32_16x16x32_bf16 v[8:11], v[152:155], v[238:241], v[8:11]
	s_barrier
	ds_read_b128 v[140:143], v138
	ds_read_b128 v[144:147], v138 offset:1024
	ds_read_b128 v[148:151], v138 offset:2048
	ds_read_b128 v[152:155], v138 offset:3072
	s_mov_b32 m0, s56
	s_nop 0
	global_load_lds_dwordx4 v129, s[84:85]
	s_mov_b32 m0, s57
	s_nop 0
	global_load_lds_dwordx4 v131, s[84:85]
	s_mov_b32 m0, s58
	s_nop 0
	global_load_lds_dwordx4 v128, s[82:83]
	s_mov_b32 m0, s59
	s_nop 0
	global_load_lds_dwordx4 v130, s[82:83]
	s_add_u32 s6, s80, 0x20080
	s_addc_u32 s7, s81, 0
	s_mov_b32 m0, s60
	s_nop 0
	global_load_lds_dwordx4 v128, s[6:7]
	s_mov_b32 m0, s61
	s_nop 0
	global_load_lds_dwordx4 v130, s[6:7]
	s_waitcnt vmcnt(8)
	s_waitcnt lgkmcnt(0)
	s_barrier
	v_mfma_f32_16x16x32_bf16 v[116:119], v[140:143], v[156:159], v[116:119]
	v_mfma_f32_16x16x32_bf16 v[112:115], v[148:151], v[156:159], v[112:115]
	v_mfma_f32_16x16x32_bf16 v[100:103], v[140:143], v[178:181], v[100:103]
	v_mfma_f32_16x16x32_bf16 v[96:99], v[148:151], v[178:181], v[96:99]
	v_mfma_f32_16x16x32_bf16 v[84:87], v[140:143], v[186:189], v[84:87]
	v_mfma_f32_16x16x32_bf16 v[80:83], v[148:151], v[186:189], v[80:83]
	v_mfma_f32_16x16x32_bf16 v[68:71], v[140:143], v[194:197], v[68:71]
	v_mfma_f32_16x16x32_bf16 v[64:67], v[148:151], v[194:197], v[64:67]
	v_mfma_f32_16x16x32_bf16 v[52:55], v[140:143], v[202:205], v[52:55]
	v_mfma_f32_16x16x32_bf16 v[48:51], v[148:151], v[202:205], v[48:51]
	v_mfma_f32_16x16x32_bf16 v[36:39], v[140:143], v[218:221], v[36:39]
	v_mfma_f32_16x16x32_bf16 v[32:35], v[148:151], v[218:221], v[32:35]
	v_mfma_f32_16x16x32_bf16 v[20:23], v[140:143], v[226:229], v[20:23]
	v_mfma_f32_16x16x32_bf16 v[16:19], v[148:151], v[226:229], v[16:19]
	v_mfma_f32_16x16x32_bf16 v[4:7], v[140:143], v[234:237], v[4:7]
	v_mfma_f32_16x16x32_bf16 v[0:3], v[148:151], v[234:237], v[0:3]
	v_mfma_f32_16x16x32_bf16 v[116:119], v[144:147], v[166:169], v[116:119]
	v_mfma_f32_16x16x32_bf16 v[112:115], v[152:155], v[166:169], v[112:115]
	v_mfma_f32_16x16x32_bf16 v[100:103], v[144:147], v[182:185], v[100:103]
	v_mfma_f32_16x16x32_bf16 v[96:99], v[152:155], v[182:185], v[96:99]
	v_mfma_f32_16x16x32_bf16 v[84:87], v[144:147], v[190:193], v[84:87]
	v_mfma_f32_16x16x32_bf16 v[80:83], v[152:155], v[190:193], v[80:83]
	v_mfma_f32_16x16x32_bf16 v[68:71], v[144:147], v[198:201], v[68:71]
	v_mfma_f32_16x16x32_bf16 v[64:67], v[152:155], v[198:201], v[64:67]
	v_mfma_f32_16x16x32_bf16 v[52:55], v[144:147], v[214:217], v[52:55]
	v_mfma_f32_16x16x32_bf16 v[48:51], v[152:155], v[214:217], v[48:51]
	v_mfma_f32_16x16x32_bf16 v[36:39], v[144:147], v[222:225], v[36:39]
	v_mfma_f32_16x16x32_bf16 v[32:35], v[152:155], v[222:225], v[32:35]
	v_mfma_f32_16x16x32_bf16 v[20:23], v[144:147], v[230:233], v[20:23]
	v_mfma_f32_16x16x32_bf16 v[16:19], v[152:155], v[230:233], v[16:19]
	v_mfma_f32_16x16x32_bf16 v[4:7], v[144:147], v[238:241], v[4:7]
	v_mfma_f32_16x16x32_bf16 v[0:3], v[152:155], v[238:241], v[0:3]
	s_barrier
	s_add_u32 s88, s88, 0x100
	s_addc_u32 s89, s89, 0
	s_add_u32 s95, s95, 0x100
	s_addc_u32 s96, s96, 0
	s_cmp_ge_i32 s69, s28
	s_mov_b32 s68, s69
	s_cbranch_scc0 .LBB0_487
	v_readlane_b32 s96, v252, 29
	v_readlane_b32 s97, v252, 30
	v_readlane_b32 s89, v255, 4
	v_readlane_b32 s95, v255, 2

; #define PG8_STAGE(bufoff, gbase, voff) do { _Pragma("unroll") for (int _i = 0; _i < 2; ++_i) { \
;         const unsigned _m0 = ldsu + (unsigned)(bufoff) + ldsw + (unsigned)(_i * 8192); \
;         asm volatile("s_mov_b32 m0, %2\n\ts_nop 0\n\tglobal_load_lds_dwordx4 %0, %1" :: "v"((voff)[_i]), "s"((const char*)(gbase)), "s"(_m0) : "memory"); } } while (0)
; #define PG8_LDA(dst, b, h) do { _Pragma("unroll") for (int m = 0; m < 4; ++m) _Pragma("unroll") for (int k = 0; k < 2; ++k) dst[m][k] = *(const LAS bf16x8*)(lds + PG8_SA(b, h) + aoff + m * 2048 + k * 1024); } while (0)
; #define PG8_LDB(dst, b, h) do { _Pragma("unroll") for (int n = 0; n < 2; ++n) _Pragma("unroll") for (int k = 0; k < 2; ++k) dst[n][k] = *(const LAS bf16x8*)(lds + bbase[b][h] + n * 2048 + k * 1024); } while (0)
; #define PG8_WAIT_V(n) asm volatile("s_waitcnt vmcnt(" #n ")" ::: "memory")
; #define PG8_WAIT_L(n) asm volatile("s_waitcnt lgkmcnt(" #n ")" ::: "memory")
; #define PG8_BAR __builtin_amdgcn_s_barrier()
; #define PG8_SCHED __builtin_amdgcn_sched_barrier(0)
; template <class Epi>
; __device__ __forceinline__ void gemm_phase(LAS unsigned char* lds, const Gemm g, const StaticOrder& S, const Epi& E) {
;     ...
;         for (int t = 0; t < nt; t += 2) {
;             const bool last = (t == nt - 2);
;             const char* a2 = last ? nA : cA + (size_t)(t + 2) * kstep; const char* b2 = last ? nB : cB + (size_t)(t + 2) * kstep;
;             const char* a3 = a2 + kstep; const char* b3 = b2 + kstep;
;             const char* b1 = cB + (size_t)(t + 1) * kstep;
;             PG8_LDB(B0, 0, 0); PG8_SCHED; PG8_LDA(At, 0, 0); PG8_LDA(At2, 0, 1); PG8_STAGE(PG8_SB(1, 1), b1 + hstepB, voffB);
;             PG8_WAIT_V(8); PG8_WAIT_L(0); PG8_BAR; PG8_MMA2B(0, At, At2, B0); PG8_BAR; PG8_SCHED;
;             PG8_LDB(B0, 0, 1); PG8_STAGE(PG8_SB(0, 0), b2, voffB); PG8_STAGE(PG8_SA(0, 0), a2, voffA); PG8_STAGE(PG8_SA(0, 1), a2 + hstepA, voffA);
;             PG8_WAIT_V(8); PG8_WAIT_L(0); PG8_BAR; PG8_MMA2B(1, At, At2, B0); PG8_BAR; PG8_SCHED;
.LBB0_509:
	s_add_i32 s63, s4, 2
	s_add_u32 s38, s59, 0x80
	ds_read_b128 v[128:131], v144
	ds_read_b128 v[132:135], v144 offset:1024
	ds_read_b128 v[150:153], v144 offset:2048
	ds_read_b128 v[154:157], v144 offset:3072
	s_addc_u32 s39, s60, 0
	s_cmp_eq_u32 s51, s4
	s_cselect_b32 s4, s15, s61
	s_cselect_b32 s5, s13, s62
	s_cselect_b32 s82, s58, s38
	s_cselect_b32 s83, s57, s39
	s_add_u32 s38, s4, 0x80
	s_addc_u32 s39, s5, 0
	s_add_u32 s80, s82, 0x80
	s_addc_u32 s81, s83, 0
	ds_read_b128 v[166:169], v145
	ds_read_b128 v[178:181], v145 offset:1024
	ds_read_b128 v[182:185], v145 offset:2048
	ds_read_b128 v[186:189], v145 offset:3072
	ds_read_b128 v[190:193], v145 offset:4096
	ds_read_b128 v[194:197], v145 offset:5120
	ds_read_b128 v[198:201], v145 offset:6144
	ds_read_b128 v[202:205], v145 offset:7168
	ds_read_b128 v[214:217], v145 offset:16384
	ds_read_b128 v[218:221], v145 offset:17408
	ds_read_b128 v[222:225], v145 offset:18432
	ds_read_b128 v[226:229], v145 offset:19456
	ds_read_b128 v[230:233], v145 offset:20480
	ds_read_b128 v[234:237], v145 offset:21504
	ds_read_b128 v[238:241], v145 offset:22528
	ds_read_b128 v[242:245], v145 offset:23552
	s_add_u32 s64, s59, 0x20000
	s_addc_u32 s65, s60, 0
	s_mov_b32 m0, s52
	s_nop 0
	global_load_lds_dwordx4 v141, s[64:65]
	s_mov_b32 m0, s53
	s_nop 0
	global_load_lds_dwordx4 v143, s[64:65]
	s_waitcnt vmcnt(8)
	s_waitcnt lgkmcnt(0)
	s_barrier
	v_mfma_f32_16x16x32_bf16 v[120:123], v[128:131], v[166:169], v[120:123]
	v_mfma_f32_16x16x32_bf16 v[124:127], v[150:153], v[166:169], v[124:127]
	v_mfma_f32_16x16x32_bf16 v[108:111], v[128:131], v[182:185], v[108:111]
	v_mfma_f32_16x16x32_bf16 v[104:107], v[150:153], v[182:185], v[104:107]
	v_mfma_f32_16x16x32_bf16 v[92:95], v[128:131], v[190:193], v[92:95]
	v_mfma_f32_16x16x32_bf16 v[88:91], v[150:153], v[190:193], v[88:91]
	v_mfma_f32_16x16x32_bf16 v[76:79], v[128:131], v[198:201], v[76:79]
	v_mfma_f32_16x16x32_bf16 v[72:75], v[150:153], v[198:201], v[72:75]
	v_mfma_f32_16x16x32_bf16 v[60:63], v[128:131], v[214:217], v[60:63]
	v_mfma_f32_16x16x32_bf16 v[56:59], v[150:153], v[214:217], v[56:59]
	v_mfma_f32_16x16x32_bf16 v[44:47], v[128:131], v[222:225], v[44:47]
	v_mfma_f32_16x16x32_bf16 v[40:43], v[150:153], v[222:225], v[40:43]
	v_mfma_f32_16x16x32_bf16 v[28:31], v[128:131], v[230:233], v[28:31]
	v_mfma_f32_16x16x32_bf16 v[24:27], v[150:153], v[230:233], v[24:27]
	v_mfma_f32_16x16x32_bf16 v[12:15], v[128:131], v[238:241], v[12:15]
	v_mfma_f32_16x16x32_bf16 v[8:11], v[150:153], v[238:241], v[8:11]
	v_mfma_f32_16x16x32_bf16 v[120:123], v[132:135], v[178:181], v[120:123]
	v_mfma_f32_16x16x32_bf16 v[124:127], v[154:157], v[178:181], v[124:127]
	v_mfma_f32_16x16x32_bf16 v[108:111], v[132:135], v[186:189], v[108:111]
	v_mfma_f32_16x16x32_bf16 v[104:107], v[154:157], v[186:189], v[104:107]
	v_mfma_f32_16x16x32_bf16 v[92:95], v[132:135], v[194:197], v[92:95]
	v_mfma_f32_16x16x32_bf16 v[88:91], v[154:157], v[194:197], v[88:91]
	v_mfma_f32_16x16x32_bf16 v[76:79], v[132:135], v[202:205], v[76:79]
	v_mfma_f32_16x16x32_bf16 v[72:75], v[154:157], v[202:205], v[72:75]
	v_mfma_f32_16x16x32_bf16 v[60:63], v[132:135], v[218:221], v[60:63]
	v_mfma_f32_16x16x32_bf16 v[56:59], v[154:157], v[218:221], v[56:59]
	v_mfma_f32_16x16x32_bf16 v[44:47], v[132:135], v[226:229], v[44:47]
	v_mfma_f32_16x16x32_bf16 v[40:43], v[154:157], v[226:229], v[40:43]
	v_mfma_f32_16x16x32_bf16 v[28:31], v[132:135], v[234:237], v[28:31]
	v_mfma_f32_16x16x32_bf16 v[24:27], v[154:157], v[234:237], v[24:27]
	v_mfma_f32_16x16x32_bf16 v[12:15], v[132:135], v[242:245], v[12:15]
	v_mfma_f32_16x16x32_bf16 v[8:11], v[154:157], v[242:245], v[8:11]
	s_barrier
	ds_read_b128 v[128:131], v146
	ds_read_b128 v[132:135], v146 offset:1024
	ds_read_b128 v[150:153], v146 offset:2048
	ds_read_b128 v[154:157], v146 offset:3072
	s_mov_b32 m0, s85
	s_nop 0
	global_load_lds_dwordx4 v141, s[82:83]
	s_mov_b32 m0, s86
	s_nop 0
	global_load_lds_dwordx4 v143, s[82:83]
	s_mov_b32 m0, s84
	s_nop 0
	global_load_lds_dwordx4 v140, s[4:5]
	s_mov_b32 m0, s87
	s_nop 0
	global_load_lds_dwordx4 v142, s[4:5]
	s_add_u32 s64, s4, 0x20000
	s_addc_u32 s65, s5, 0
	s_mov_b32 m0, s88
	s_nop 0
	global_load_lds_dwordx4 v140, s[64:65]
	s_mov_b32 m0, s89
	s_nop 0
	global_load_lds_dwordx4 v142, s[64:65]
	s_waitcnt vmcnt(8)
	s_waitcnt lgkmcnt(0)
	s_barrier
	v_mfma_f32_16x16x32_bf16 v[116:119], v[128:131], v[166:169], v[116:119]
	v_mfma_f32_16x16x32_bf16 v[112:115], v[150:153], v[166:169], v[112:115]
	v_mfma_f32_16x16x32_bf16 v[100:103], v[128:131], v[182:185], v[100:103]
	v_mfma_f32_16x16x32_bf16 v[96:99], v[150:153], v[182:185], v[96:99]
	v_mfma_f32_16x16x32_bf16 v[84:87], v[128:131], v[190:193], v[84:87]
	v_mfma_f32_16x16x32_bf16 v[80:83], v[150:153], v[190:193], v[80:83]
	v_mfma_f32_16x16x32_bf16 v[68:71], v[128:131], v[198:201], v[68:71]
	v_mfma_f32_16x16x32_bf16 v[64:67], v[150:153], v[198:201], v[64:67]
	v_mfma_f32_16x16x32_bf16 v[52:55], v[128:131], v[214:217], v[52:55]
	v_mfma_f32_16x16x32_bf16 v[48:51], v[150:153], v[214:217], v[48:51]
	v_mfma_f32_16x16x32_bf16 v[36:39], v[128:131], v[222:225], v[36:39]
	v_mfma_f32_16x16x32_bf16 v[32:35], v[150:153], v[222:225], v[32:35]
	v_mfma_f32_16x16x32_bf16 v[20:23], v[128:131], v[230:233], v[20:23]
	v_mfma_f32_16x16x32_bf16 v[16:19], v[150:153], v[230:233], v[16:19]
	v_mfma_f32_16x16x32_bf16 v[4:7], v[128:131], v[238:241], v[4:7]
	v_mfma_f32_16x16x32_bf16 v[0:3], v[150:153], v[238:241], v[0:3]
	v_mfma_f32_16x16x32_bf16 v[116:119], v[132:135], v[178:181], v[116:119]
	v_mfma_f32_16x16x32_bf16 v[112:115], v[154:157], v[178:181], v[112:115]
	v_mfma_f32_16x16x32_bf16 v[100:103], v[132:135], v[186:189], v[100:103]
	v_mfma_f32_16x16x32_bf16 v[96:99], v[154:157], v[186:189], v[96:99]
	v_mfma_f32_16x16x32_bf16 v[84:87], v[132:135], v[194:197], v[84:87]
	v_mfma_f32_16x16x32_bf16 v[80:83], v[154:157], v[194:197], v[80:83]
	v_mfma_f32_16x16x32_bf16 v[68:71], v[132:135], v[202:205], v[68:71]
	v_mfma_f32_16x16x32_bf16 v[64:67], v[154:157], v[202:205], v[64:67]
	v_mfma_f32_16x16x32_bf16 v[52:55], v[132:135], v[218:221], v[52:55]
	v_mfma_f32_16x16x32_bf16 v[48:51], v[154:157], v[218:221], v[48:51]
	v_mfma_f32_16x16x32_bf16 v[36:39], v[132:135], v[226:229], v[36:39]
	v_mfma_f32_16x16x32_bf16 v[32:35], v[154:157], v[226:229], v[32:35]
	v_mfma_f32_16x16x32_bf16 v[20:23], v[132:135], v[234:237], v[20:23]
	v_mfma_f32_16x16x32_bf16 v[16:19], v[154:157], v[234:237], v[16:19]
	v_mfma_f32_16x16x32_bf16 v[4:7], v[132:135], v[242:245], v[4:7]
	v_mfma_f32_16x16x32_bf16 v[0:3], v[154:157], v[242:245], v[0:3]
	s_barrier
; #define PG8_STAGE(bufoff, gbase, voff) do { _Pragma("unroll") for (int _i = 0; _i < 2; ++_i) { \
;         const unsigned _m0 = ldsu + (unsigned)(bufoff) + ldsw + (unsigned)(_i * 8192); \
;         asm volatile("s_mov_b32 m0, %2\n\ts_nop 0\n\tglobal_load_lds_dwordx4 %0, %1" :: "v"((voff)[_i]), "s"((const char*)(gbase)), "s"(_m0) : "memory"); } } while (0)
; #define PG8_LDA(dst, b, h) do { _Pragma("unroll") for (int m = 0; m < 4; ++m) _Pragma("unroll") for (int k = 0; k < 2; ++k) dst[m][k] = *(const LAS bf16x8*)(lds + PG8_SA(b, h) + aoff + m * 2048 + k * 1024); } while (0)
; #define PG8_LDB(dst, b, h) do { _Pragma("unroll") for (int n = 0; n < 2; ++n) _Pragma("unroll") for (int k = 0; k < 2; ++k) dst[n][k] = *(const LAS bf16x8*)(lds + bbase[b][h] + n * 2048 + k * 1024); } while (0)
; #define PG8_WAIT_V(n) asm volatile("s_waitcnt vmcnt(" #n ")" ::: "memory")
; #define PG8_WAIT_L(n) asm volatile("s_waitcnt lgkmcnt(" #n ")" ::: "memory")
; #define PG8_BAR __builtin_amdgcn_s_barrier()
; #define PG8_SCHED __builtin_amdgcn_sched_barrier(0)
; template <class Epi>
; __device__ __forceinline__ void gemm_phase(LAS unsigned char* lds, const Gemm g, const StaticOrder& S, const Epi& E) {
;     ...
;             PG8_LDB(B0, 1, 0); PG8_SCHED; PG8_LDA(At, 1, 0); PG8_LDA(At2, 1, 1); PG8_STAGE(PG8_SB(0, 1), b2 + hstepB, voffB);
;             PG8_WAIT_V(8); PG8_WAIT_L(0); PG8_BAR; PG8_MMA2B(0, At, At2, B0); PG8_BAR; PG8_SCHED;
;             PG8_LDB(B0, 1, 1); PG8_STAGE(PG8_SB(1, 0), b3, voffB); PG8_STAGE(PG8_SA(1, 0), a3, voffA); PG8_STAGE(PG8_SA(1, 1), a3 + hstepA, voffA);
;             PG8_WAIT_V(8); PG8_WAIT_L(0); PG8_BAR; PG8_MMA2B(1, At, At2, B0); PG8_BAR; PG8_SCHED;
;         }
	ds_read_b128 v[128:131], v147
	ds_read_b128 v[132:135], v147 offset:1024
	ds_read_b128 v[150:153], v147 offset:2048
	ds_read_b128 v[154:157], v147 offset:3072
	ds_read_b128 v[166:169], v145 offset:32768
	ds_read_b128 v[178:181], v145 offset:33792
	ds_read_b128 v[182:185], v145 offset:34816
	ds_read_b128 v[186:189], v145 offset:35840
	ds_read_b128 v[190:193], v145 offset:36864
	ds_read_b128 v[194:197], v145 offset:37888
	ds_read_b128 v[198:201], v145 offset:38912
	ds_read_b128 v[202:205], v145 offset:39936
	ds_read_b128 v[214:217], v145 offset:49152
	ds_read_b128 v[218:221], v145 offset:50176
	ds_read_b128 v[222:225], v145 offset:51200
	ds_read_b128 v[226:229], v145 offset:52224
	ds_read_b128 v[230:233], v145 offset:53248
	ds_read_b128 v[234:237], v145 offset:54272
	ds_read_b128 v[238:241], v145 offset:55296
	ds_read_b128 v[242:245], v145 offset:56320
	s_add_u32 s64, s82, 0x20000
	s_addc_u32 s65, s83, 0
	s_mov_b32 m0, s90
	s_nop 0
	global_load_lds_dwordx4 v141, s[64:65]
	s_mov_b32 m0, s91
	s_nop 0
	global_load_lds_dwordx4 v143, s[64:65]
	s_waitcnt vmcnt(8)
	s_waitcnt lgkmcnt(0)
	s_barrier
	v_mfma_f32_16x16x32_bf16 v[120:123], v[128:131], v[166:169], v[120:123]
	v_mfma_f32_16x16x32_bf16 v[124:127], v[150:153], v[166:169], v[124:127]
	v_mfma_f32_16x16x32_bf16 v[108:111], v[128:131], v[182:185], v[108:111]
	v_mfma_f32_16x16x32_bf16 v[104:107], v[150:153], v[182:185], v[104:107]
	v_mfma_f32_16x16x32_bf16 v[92:95], v[128:131], v[190:193], v[92:95]
	v_mfma_f32_16x16x32_bf16 v[88:91], v[150:153], v[190:193], v[88:91]
	v_mfma_f32_16x16x32_bf16 v[76:79], v[128:131], v[198:201], v[76:79]
	v_mfma_f32_16x16x32_bf16 v[72:75], v[150:153], v[198:201], v[72:75]
	v_mfma_f32_16x16x32_bf16 v[60:63], v[128:131], v[214:217], v[60:63]
	v_mfma_f32_16x16x32_bf16 v[56:59], v[150:153], v[214:217], v[56:59]
	v_mfma_f32_16x16x32_bf16 v[44:47], v[128:131], v[222:225], v[44:47]
	v_mfma_f32_16x16x32_bf16 v[40:43], v[150:153], v[222:225], v[40:43]
	v_mfma_f32_16x16x32_bf16 v[28:31], v[128:131], v[230:233], v[28:31]
	v_mfma_f32_16x16x32_bf16 v[24:27], v[150:153], v[230:233], v[24:27]
	v_mfma_f32_16x16x32_bf16 v[12:15], v[128:131], v[238:241], v[12:15]
	v_mfma_f32_16x16x32_bf16 v[8:11], v[150:153], v[238:241], v[8:11]
	v_mfma_f32_16x16x32_bf16 v[120:123], v[132:135], v[178:181], v[120:123]
	v_mfma_f32_16x16x32_bf16 v[124:127], v[154:157], v[178:181], v[124:127]
	v_mfma_f32_16x16x32_bf16 v[108:111], v[132:135], v[186:189], v[108:111]
	v_mfma_f32_16x16x32_bf16 v[104:107], v[154:157], v[186:189], v[104:107]
	v_mfma_f32_16x16x32_bf16 v[92:95], v[132:135], v[194:197], v[92:95]
	v_mfma_f32_16x16x32_bf16 v[88:91], v[154:157], v[194:197], v[88:91]
	v_mfma_f32_16x16x32_bf16 v[76:79], v[132:135], v[202:205], v[76:79]
	v_mfma_f32_16x16x32_bf16 v[72:75], v[154:157], v[202:205], v[72:75]
	v_mfma_f32_16x16x32_bf16 v[60:63], v[132:135], v[218:221], v[60:63]
	v_mfma_f32_16x16x32_bf16 v[56:59], v[154:157], v[218:221], v[56:59]
	v_mfma_f32_16x16x32_bf16 v[44:47], v[132:135], v[226:229], v[44:47]
	v_mfma_f32_16x16x32_bf16 v[40:43], v[154:157], v[226:229], v[40:43]
	v_mfma_f32_16x16x32_bf16 v[28:31], v[132:135], v[234:237], v[28:31]
	v_mfma_f32_16x16x32_bf16 v[24:27], v[154:157], v[234:237], v[24:27]
	v_mfma_f32_16x16x32_bf16 v[12:15], v[132:135], v[242:245], v[12:15]
	v_mfma_f32_16x16x32_bf16 v[8:11], v[154:157], v[242:245], v[8:11]
	s_barrier
	ds_read_b128 v[128:131], v148
	ds_read_b128 v[132:135], v148 offset:1024
	ds_read_b128 v[150:153], v148 offset:2048
	ds_read_b128 v[154:157], v148 offset:3072
	s_mov_b32 m0, s97
	s_nop 0
	global_load_lds_dwordx4 v141, s[80:81]
	s_mov_b32 m0, s37
	s_nop 0
	global_load_lds_dwordx4 v143, s[80:81]
	s_mov_b32 m0, s95
	s_nop 0
	global_load_lds_dwordx4 v140, s[38:39]
	s_mov_b32 m0, s48
	s_nop 0
	global_load_lds_dwordx4 v142, s[38:39]
	s_add_u32 s4, s4, 0x20080
	s_addc_u32 s5, s5, 0
	s_mov_b32 m0, s49
	s_nop 0
	global_load_lds_dwordx4 v140, s[4:5]
	s_mov_b32 m0, s50
	s_nop 0
	global_load_lds_dwordx4 v142, s[4:5]
	s_waitcnt vmcnt(8)
	s_waitcnt lgkmcnt(0)
	s_barrier
	v_mfma_f32_16x16x32_bf16 v[116:119], v[128:131], v[166:169], v[116:119]
	v_mfma_f32_16x16x32_bf16 v[112:115], v[150:153], v[166:169], v[112:115]
	v_mfma_f32_16x16x32_bf16 v[100:103], v[128:131], v[182:185], v[100:103]
	v_mfma_f32_16x16x32_bf16 v[96:99], v[150:153], v[182:185], v[96:99]
	v_mfma_f32_16x16x32_bf16 v[84:87], v[128:131], v[190:193], v[84:87]
	v_mfma_f32_16x16x32_bf16 v[80:83], v[150:153], v[190:193], v[80:83]
	v_mfma_f32_16x16x32_bf16 v[68:71], v[128:131], v[198:201], v[68:71]
	v_mfma_f32_16x16x32_bf16 v[64:67], v[150:153], v[198:201], v[64:67]
	v_mfma_f32_16x16x32_bf16 v[52:55], v[128:131], v[214:217], v[52:55]
	v_mfma_f32_16x16x32_bf16 v[48:51], v[150:153], v[214:217], v[48:51]
	v_mfma_f32_16x16x32_bf16 v[36:39], v[128:131], v[222:225], v[36:39]
	v_mfma_f32_16x16x32_bf16 v[32:35], v[150:153], v[222:225], v[32:35]
	v_mfma_f32_16x16x32_bf16 v[20:23], v[128:131], v[230:233], v[20:23]
	v_mfma_f32_16x16x32_bf16 v[16:19], v[150:153], v[230:233], v[16:19]
	v_mfma_f32_16x16x32_bf16 v[4:7], v[128:131], v[238:241], v[4:7]
	v_mfma_f32_16x16x32_bf16 v[0:3], v[150:153], v[238:241], v[0:3]
	v_mfma_f32_16x16x32_bf16 v[116:119], v[132:135], v[178:181], v[116:119]
	v_mfma_f32_16x16x32_bf16 v[112:115], v[154:157], v[178:181], v[112:115]
	v_mfma_f32_16x16x32_bf16 v[100:103], v[132:135], v[186:189], v[100:103]
	v_mfma_f32_16x16x32_bf16 v[96:99], v[154:157], v[186:189], v[96:99]
	v_mfma_f32_16x16x32_bf16 v[84:87], v[132:135], v[194:197], v[84:87]
	v_mfma_f32_16x16x32_bf16 v[80:83], v[154:157], v[194:197], v[80:83]
	v_mfma_f32_16x16x32_bf16 v[68:71], v[132:135], v[202:205], v[68:71]
	v_mfma_f32_16x16x32_bf16 v[64:67], v[154:157], v[202:205], v[64:67]
	v_mfma_f32_16x16x32_bf16 v[52:55], v[132:135], v[218:221], v[52:55]
	v_mfma_f32_16x16x32_bf16 v[48:51], v[154:157], v[218:221], v[48:51]
	v_mfma_f32_16x16x32_bf16 v[36:39], v[132:135], v[226:229], v[36:39]
	v_mfma_f32_16x16x32_bf16 v[32:35], v[154:157], v[226:229], v[32:35]
	v_mfma_f32_16x16x32_bf16 v[20:23], v[132:135], v[234:237], v[20:23]
	v_mfma_f32_16x16x32_bf16 v[16:19], v[154:157], v[234:237], v[16:19]
	v_mfma_f32_16x16x32_bf16 v[4:7], v[132:135], v[242:245], v[4:7]
	v_mfma_f32_16x16x32_bf16 v[0:3], v[154:157], v[242:245], v[0:3]
	s_barrier
	s_add_u32 s59, s59, 0x100
	s_addc_u32 s60, s60, 0
	s_add_u32 s61, s61, 0x100
	s_addc_u32 s62, s62, 0
	s_cmp_ge_i32 s63, s28
	s_mov_b32 s4, s63
	s_cbranch_scc0 .LBB0_509
	v_readlane_b32 s60, v252, 25
	v_readlane_b32 s62, v252, 27
	v_readlane_b32 s64, v252, 9
	v_readlane_b32 s61, v252, 26
	v_readlane_b32 s63, v252, 28
	v_readlane_b32 s65, v252, 10

; #define PG8_STAGE(bufoff, gbase, voff) do { _Pragma("unroll") for (int _i = 0; _i < 2; ++_i) { \
;         const unsigned _m0 = ldsu + (unsigned)(bufoff) + ldsw + (unsigned)(_i * 8192); \
;         asm volatile("s_mov_b32 m0, %2\n\ts_nop 0\n\tglobal_load_lds_dwordx4 %0, %1" :: "v"((voff)[_i]), "s"((const char*)(gbase)), "s"(_m0) : "memory"); } } while (0)
; #define PG8_LDA(dst, b, h) do { _Pragma("unroll") for (int m = 0; m < 4; ++m) _Pragma("unroll") for (int k = 0; k < 2; ++k) dst[m][k] = *(const LAS bf16x8*)(lds + PG8_SA(b, h) + aoff + m * 2048 + k * 1024); } while (0)
; #define PG8_LDB(dst, b, h) do { _Pragma("unroll") for (int n = 0; n < 2; ++n) _Pragma("unroll") for (int k = 0; k < 2; ++k) dst[n][k] = *(const LAS bf16x8*)(lds + bbase[b][h] + n * 2048 + k * 1024); } while (0)
; #define PG8_WAIT_V(n) asm volatile("s_waitcnt vmcnt(" #n ")" ::: "memory")
; #define PG8_WAIT_L(n) asm volatile("s_waitcnt lgkmcnt(" #n ")" ::: "memory")
; #define PG8_BAR __builtin_amdgcn_s_barrier()
; #define PG8_SCHED __builtin_amdgcn_sched_barrier(0)
; template <class Epi>
; __device__ __forceinline__ void gemm_phase(LAS unsigned char* lds, const Gemm g, const StaticOrder& S, const Epi& E) {
;     ...
;         for (int t = 0; t < nt; t += 2) {
;             const bool last = (t == nt - 2);
;             const char* a2 = last ? nA : cA + (size_t)(t + 2) * kstep; const char* b2 = last ? nB : cB + (size_t)(t + 2) * kstep;
;             const char* a3 = a2 + kstep; const char* b3 = b2 + kstep;
;             const char* b1 = cB + (size_t)(t + 1) * kstep;
;             PG8_LDB(B0, 0, 0); PG8_SCHED; PG8_LDA(At, 0, 0); PG8_LDA(At2, 0, 1); PG8_STAGE(PG8_SB(1, 1), b1 + hstepB, voffB);
;             PG8_WAIT_V(8); PG8_WAIT_L(0); PG8_BAR; PG8_MMA2B(0, At, At2, B0); PG8_BAR; PG8_SCHED;
;             PG8_LDB(B0, 0, 1); PG8_STAGE(PG8_SB(0, 0), b2, voffB); PG8_STAGE(PG8_SA(0, 0), a2, voffA); PG8_STAGE(PG8_SA(0, 1), a2 + hstepA, voffA);
;             PG8_WAIT_V(8); PG8_WAIT_L(0); PG8_BAR; PG8_MMA2B(1, At, At2, B0); PG8_BAR; PG8_SCHED;
.LBB0_584:
	ds_read_b128 v[128:131], v155
	ds_read_b128 v[132:135], v155 offset:1024
	ds_read_b128 v[136:139], v155 offset:2048
	ds_read_b128 v[140:143], v155 offset:3072
	s_add_u32 s10, s8, 0x100
	s_addc_u32 s11, s9, 0
	s_cmp_eq_u32 s68, 12
	s_cselect_b32 s84, s67, s87
	s_cselect_b32 s85, s43, s88
	s_cselect_b32 s90, s86, s10
	s_cselect_b32 s91, s39, s11
	s_add_u32 s96, s84, 0x80
	s_addc_u32 s97, s85, 0
	ds_read_b128 v[144:147], v156
	ds_read_b128 v[178:181], v156 offset:1024
	ds_read_b128 v[182:185], v156 offset:2048
	ds_read_b128 v[186:189], v156 offset:3072
	ds_read_b128 v[190:193], v156 offset:4096
	ds_read_b128 v[194:197], v156 offset:5120
	ds_read_b128 v[198:201], v156 offset:6144
	ds_read_b128 v[202:205], v156 offset:7168
	ds_read_b128 v[214:217], v156 offset:16384
	ds_read_b128 v[218:221], v156 offset:17408
	ds_read_b128 v[222:225], v156 offset:18432
	ds_read_b128 v[226:229], v156 offset:19456
	ds_read_b128 v[230:233], v156 offset:20480
	ds_read_b128 v[234:237], v156 offset:21504
	ds_read_b128 v[238:241], v156 offset:22528
	ds_read_b128 v[242:245], v156 offset:23552
	s_add_u32 s8, s8, 0x40080
	s_addc_u32 s9, s9, 0
	s_mov_b32 m0, s61
	s_nop 0
	global_load_lds_dwordx4 v151, s[8:9]
	s_mov_b32 m0, s64
	s_nop 0
	global_load_lds_dwordx4 v153, s[8:9]
	s_waitcnt vmcnt(8)
	s_waitcnt lgkmcnt(0)
	s_barrier
	v_mfma_f32_16x16x32_bf16 v[76:79], v[128:131], v[144:147], v[76:79]
	v_mfma_f32_16x16x32_bf16 v[72:75], v[136:139], v[144:147], v[72:75]
	v_mfma_f32_16x16x32_bf16 v[64:67], v[128:131], v[182:185], v[64:67]
	v_mfma_f32_16x16x32_bf16 v[60:63], v[136:139], v[182:185], v[60:63]
	v_mfma_f32_16x16x32_bf16 v[56:59], v[128:131], v[190:193], v[56:59]
	v_mfma_f32_16x16x32_bf16 v[52:55], v[136:139], v[190:193], v[52:55]
	v_mfma_f32_16x16x32_bf16 v[112:115], v[128:131], v[198:201], v[112:115]
	v_mfma_f32_16x16x32_bf16 v[104:107], v[136:139], v[198:201], v[104:107]
	v_mfma_f32_16x16x32_bf16 v[36:39], v[128:131], v[214:217], v[36:39]
	v_mfma_f32_16x16x32_bf16 v[32:35], v[136:139], v[214:217], v[32:35]
	v_mfma_f32_16x16x32_bf16 v[28:31], v[128:131], v[222:225], v[28:31]
	v_mfma_f32_16x16x32_bf16 v[24:27], v[136:139], v[222:225], v[24:27]
	v_mfma_f32_16x16x32_bf16 v[16:19], v[128:131], v[230:233], v[16:19]
	v_mfma_f32_16x16x32_bf16 v[12:15], v[136:139], v[230:233], v[12:15]
	v_mfma_f32_16x16x32_bf16 v[88:91], v[128:131], v[238:241], v[88:91]
	v_mfma_f32_16x16x32_bf16 v[84:87], v[136:139], v[238:241], v[84:87]
	v_mfma_f32_16x16x32_bf16 v[76:79], v[132:135], v[178:181], v[76:79]
	v_mfma_f32_16x16x32_bf16 v[72:75], v[140:143], v[178:181], v[72:75]
	v_mfma_f32_16x16x32_bf16 v[64:67], v[132:135], v[186:189], v[64:67]
	v_mfma_f32_16x16x32_bf16 v[60:63], v[140:143], v[186:189], v[60:63]
	v_mfma_f32_16x16x32_bf16 v[56:59], v[132:135], v[194:197], v[56:59]
	v_mfma_f32_16x16x32_bf16 v[52:55], v[140:143], v[194:197], v[52:55]
	v_mfma_f32_16x16x32_bf16 v[112:115], v[132:135], v[202:205], v[112:115]
	v_mfma_f32_16x16x32_bf16 v[104:107], v[140:143], v[202:205], v[104:107]
	v_mfma_f32_16x16x32_bf16 v[36:39], v[132:135], v[218:221], v[36:39]
	v_mfma_f32_16x16x32_bf16 v[32:35], v[140:143], v[218:221], v[32:35]
	v_mfma_f32_16x16x32_bf16 v[28:31], v[132:135], v[226:229], v[28:31]
	v_mfma_f32_16x16x32_bf16 v[24:27], v[140:143], v[226:229], v[24:27]
	v_mfma_f32_16x16x32_bf16 v[16:19], v[132:135], v[234:237], v[16:19]
	v_mfma_f32_16x16x32_bf16 v[12:15], v[140:143], v[234:237], v[12:15]
	v_mfma_f32_16x16x32_bf16 v[88:91], v[132:135], v[242:245], v[88:91]
	v_mfma_f32_16x16x32_bf16 v[84:87], v[140:143], v[242:245], v[84:87]
	s_barrier
	ds_read_b128 v[128:131], v157
	ds_read_b128 v[132:135], v157 offset:1024
	ds_read_b128 v[136:139], v157 offset:2048
	ds_read_b128 v[140:143], v157 offset:3072
	s_mov_b32 m0, s47
	s_nop 0
	global_load_lds_dwordx4 v151, s[90:91]
	s_mov_b32 m0, s48
	s_nop 0
	global_load_lds_dwordx4 v153, s[90:91]
	s_mov_b32 m0, s37
	s_nop 0
	global_load_lds_dwordx4 v150, s[84:85]
	s_mov_b32 m0, s49
	s_nop 0
	global_load_lds_dwordx4 v152, s[84:85]
	s_add_u32 s8, s84, 0x40000
	s_addc_u32 s9, s85, 0
	s_mov_b32 m0, s50
	s_nop 0
	global_load_lds_dwordx4 v150, s[8:9]
	s_mov_b32 m0, s51
	s_nop 0
	global_load_lds_dwordx4 v152, s[8:9]
	s_waitcnt vmcnt(8)
	s_waitcnt lgkmcnt(0)
	s_barrier
	v_mfma_f32_16x16x32_bf16 v[68:71], v[128:131], v[144:147], v[68:71]
	v_mfma_f32_16x16x32_bf16 v[124:127], v[136:139], v[144:147], v[124:127]
	v_mfma_f32_16x16x32_bf16 v[48:51], v[128:131], v[182:185], v[48:51]
	v_mfma_f32_16x16x32_bf16 v[120:123], v[136:139], v[182:185], v[120:123]
	v_mfma_f32_16x16x32_bf16 v[44:47], v[128:131], v[190:193], v[44:47]
	v_mfma_f32_16x16x32_bf16 v[116:119], v[136:139], v[190:193], v[116:119]
	v_mfma_f32_16x16x32_bf16 v[40:43], v[128:131], v[198:201], v[40:43]
	v_mfma_f32_16x16x32_bf16 v[108:111], v[136:139], v[198:201], v[108:111]
	v_mfma_f32_16x16x32_bf16 v[20:23], v[128:131], v[214:217], v[20:23]
	v_mfma_f32_16x16x32_bf16 v[100:103], v[136:139], v[214:217], v[100:103]
	v_mfma_f32_16x16x32_bf16 v[8:11], v[128:131], v[222:225], v[8:11]
	v_mfma_f32_16x16x32_bf16 v[96:99], v[136:139], v[222:225], v[96:99]
	v_mfma_f32_16x16x32_bf16 v[4:7], v[128:131], v[230:233], v[4:7]
	v_mfma_f32_16x16x32_bf16 v[92:95], v[136:139], v[230:233], v[92:95]
	v_mfma_f32_16x16x32_bf16 v[0:3], v[128:131], v[238:241], v[0:3]
	v_mfma_f32_16x16x32_bf16 v[80:83], v[136:139], v[238:241], v[80:83]
	v_mfma_f32_16x16x32_bf16 v[68:71], v[132:135], v[178:181], v[68:71]
	v_mfma_f32_16x16x32_bf16 v[124:127], v[140:143], v[178:181], v[124:127]
	v_mfma_f32_16x16x32_bf16 v[48:51], v[132:135], v[186:189], v[48:51]
	v_mfma_f32_16x16x32_bf16 v[120:123], v[140:143], v[186:189], v[120:123]
	v_mfma_f32_16x16x32_bf16 v[44:47], v[132:135], v[194:197], v[44:47]
	v_mfma_f32_16x16x32_bf16 v[116:119], v[140:143], v[194:197], v[116:119]
	v_mfma_f32_16x16x32_bf16 v[40:43], v[132:135], v[202:205], v[40:43]
	v_mfma_f32_16x16x32_bf16 v[108:111], v[140:143], v[202:205], v[108:111]
	v_mfma_f32_16x16x32_bf16 v[20:23], v[132:135], v[218:221], v[20:23]
	v_mfma_f32_16x16x32_bf16 v[100:103], v[140:143], v[218:221], v[100:103]
	v_mfma_f32_16x16x32_bf16 v[8:11], v[132:135], v[226:229], v[8:11]
	v_mfma_f32_16x16x32_bf16 v[96:99], v[140:143], v[226:229], v[96:99]
	v_mfma_f32_16x16x32_bf16 v[4:7], v[132:135], v[234:237], v[4:7]
	v_mfma_f32_16x16x32_bf16 v[92:95], v[140:143], v[234:237], v[92:95]
	v_mfma_f32_16x16x32_bf16 v[0:3], v[132:135], v[242:245], v[0:3]
	v_mfma_f32_16x16x32_bf16 v[80:83], v[140:143], v[242:245], v[80:83]
	s_barrier
; #define PG8_STAGE(bufoff, gbase, voff) do { _Pragma("unroll") for (int _i = 0; _i < 2; ++_i) { \
;         const unsigned _m0 = ldsu + (unsigned)(bufoff) + ldsw + (unsigned)(_i * 8192); \
;         asm volatile("s_mov_b32 m0, %2\n\ts_nop 0\n\tglobal_load_lds_dwordx4 %0, %1" :: "v"((voff)[_i]), "s"((const char*)(gbase)), "s"(_m0) : "memory"); } } while (0)
; #define PG8_LDA(dst, b, h) do { _Pragma("unroll") for (int m = 0; m < 4; ++m) _Pragma("unroll") for (int k = 0; k < 2; ++k) dst[m][k] = *(const LAS bf16x8*)(lds + PG8_SA(b, h) + aoff + m * 2048 + k * 1024); } while (0)
; #define PG8_LDB(dst, b, h) do { _Pragma("unroll") for (int n = 0; n < 2; ++n) _Pragma("unroll") for (int k = 0; k < 2; ++k) dst[n][k] = *(const LAS bf16x8*)(lds + bbase[b][h] + n * 2048 + k * 1024); } while (0)
; #define PG8_WAIT_V(n) asm volatile("s_waitcnt vmcnt(" #n ")" ::: "memory")
; #define PG8_WAIT_L(n) asm volatile("s_waitcnt lgkmcnt(" #n ")" ::: "memory")
; #define PG8_BAR __builtin_amdgcn_s_barrier()
; #define PG8_SCHED __builtin_amdgcn_sched_barrier(0)
; template <class Epi>
; __device__ __forceinline__ void gemm_phase(LAS unsigned char* lds, const Gemm g, const StaticOrder& S, const Epi& E) {
;     ...
;             PG8_LDB(B0, 1, 0); PG8_SCHED; PG8_LDA(At, 1, 0); PG8_LDA(At2, 1, 1); PG8_STAGE(PG8_SB(0, 1), b2 + hstepB, voffB);
;             PG8_WAIT_V(8); PG8_WAIT_L(0); PG8_BAR; PG8_MMA2B(0, At, At2, B0); PG8_BAR; PG8_SCHED;
;             PG8_LDB(B0, 1, 1); PG8_STAGE(PG8_SB(1, 0), b3, voffB); PG8_STAGE(PG8_SA(1, 0), a3, voffA); PG8_STAGE(PG8_SA(1, 1), a3 + hstepA, voffA);
;             PG8_WAIT_V(8); PG8_WAIT_L(0); PG8_BAR; PG8_MMA2B(1, At, At2, B0); PG8_BAR; PG8_SCHED;
;         }
;         if (wr == 0) PG8_BAR;
	ds_read_b128 v[128:131], v158
	ds_read_b128 v[132:135], v158 offset:1024
	ds_read_b128 v[136:139], v158 offset:2048
	ds_read_b128 v[140:143], v158 offset:3072
	ds_read_b128 v[144:147], v156 offset:32768
	ds_read_b128 v[178:181], v156 offset:33792
	ds_read_b128 v[182:185], v156 offset:34816
	ds_read_b128 v[186:189], v156 offset:35840
	ds_read_b128 v[190:193], v156 offset:36864
	ds_read_b128 v[194:197], v156 offset:37888
	ds_read_b128 v[198:201], v156 offset:38912
	ds_read_b128 v[202:205], v156 offset:39936
	ds_read_b128 v[214:217], v156 offset:49152
	ds_read_b128 v[218:221], v156 offset:50176
	ds_read_b128 v[222:225], v156 offset:51200
	ds_read_b128 v[226:229], v156 offset:52224
	ds_read_b128 v[230:233], v156 offset:53248
	ds_read_b128 v[234:237], v156 offset:54272
	ds_read_b128 v[238:241], v156 offset:55296
	ds_read_b128 v[242:245], v156 offset:56320
	s_add_u32 s8, s90, 0x40000
	s_addc_u32 s9, s91, 0
	s_mov_b32 m0, s52
	s_nop 0
	global_load_lds_dwordx4 v151, s[8:9]
	s_mov_b32 m0, s53
	s_nop 0
	global_load_lds_dwordx4 v153, s[8:9]
	s_waitcnt vmcnt(8)
	s_waitcnt lgkmcnt(0)
	s_barrier
	v_mfma_f32_16x16x32_bf16 v[76:79], v[128:131], v[144:147], v[76:79]
	v_mfma_f32_16x16x32_bf16 v[72:75], v[136:139], v[144:147], v[72:75]
	v_mfma_f32_16x16x32_bf16 v[64:67], v[128:131], v[182:185], v[64:67]
	v_mfma_f32_16x16x32_bf16 v[60:63], v[136:139], v[182:185], v[60:63]
	v_mfma_f32_16x16x32_bf16 v[56:59], v[128:131], v[190:193], v[56:59]
	v_mfma_f32_16x16x32_bf16 v[52:55], v[136:139], v[190:193], v[52:55]
	v_mfma_f32_16x16x32_bf16 v[112:115], v[128:131], v[198:201], v[112:115]
	v_mfma_f32_16x16x32_bf16 v[104:107], v[136:139], v[198:201], v[104:107]
	v_mfma_f32_16x16x32_bf16 v[36:39], v[128:131], v[214:217], v[36:39]
	v_mfma_f32_16x16x32_bf16 v[32:35], v[136:139], v[214:217], v[32:35]
	v_mfma_f32_16x16x32_bf16 v[28:31], v[128:131], v[222:225], v[28:31]
	v_mfma_f32_16x16x32_bf16 v[24:27], v[136:139], v[222:225], v[24:27]
	v_mfma_f32_16x16x32_bf16 v[16:19], v[128:131], v[230:233], v[16:19]
	v_mfma_f32_16x16x32_bf16 v[12:15], v[136:139], v[230:233], v[12:15]
	v_mfma_f32_16x16x32_bf16 v[88:91], v[128:131], v[238:241], v[88:91]
	v_mfma_f32_16x16x32_bf16 v[84:87], v[136:139], v[238:241], v[84:87]
	v_mfma_f32_16x16x32_bf16 v[76:79], v[132:135], v[178:181], v[76:79]
	v_mfma_f32_16x16x32_bf16 v[72:75], v[140:143], v[178:181], v[72:75]
	v_mfma_f32_16x16x32_bf16 v[64:67], v[132:135], v[186:189], v[64:67]
	v_mfma_f32_16x16x32_bf16 v[60:63], v[140:143], v[186:189], v[60:63]
	v_mfma_f32_16x16x32_bf16 v[56:59], v[132:135], v[194:197], v[56:59]
	v_mfma_f32_16x16x32_bf16 v[52:55], v[140:143], v[194:197], v[52:55]
	v_mfma_f32_16x16x32_bf16 v[112:115], v[132:135], v[202:205], v[112:115]
	v_mfma_f32_16x16x32_bf16 v[104:107], v[140:143], v[202:205], v[104:107]
	v_mfma_f32_16x16x32_bf16 v[36:39], v[132:135], v[218:221], v[36:39]
	v_mfma_f32_16x16x32_bf16 v[32:35], v[140:143], v[218:221], v[32:35]
	v_mfma_f32_16x16x32_bf16 v[28:31], v[132:135], v[226:229], v[28:31]
	v_mfma_f32_16x16x32_bf16 v[24:27], v[140:143], v[226:229], v[24:27]
	v_mfma_f32_16x16x32_bf16 v[16:19], v[132:135], v[234:237], v[16:19]
	v_mfma_f32_16x16x32_bf16 v[12:15], v[140:143], v[234:237], v[12:15]
	v_mfma_f32_16x16x32_bf16 v[88:91], v[132:135], v[242:245], v[88:91]
	v_mfma_f32_16x16x32_bf16 v[84:87], v[140:143], v[242:245], v[84:87]
	s_barrier
	s_add_u32 s8, s90, 0x80
	ds_read_b128 v[128:131], v159
	ds_read_b128 v[132:135], v159 offset:1024
	ds_read_b128 v[136:139], v159 offset:2048
	ds_read_b128 v[140:143], v159 offset:3072
	s_addc_u32 s9, s91, 0
	s_mov_b32 m0, s55
	s_nop 0
	global_load_lds_dwordx4 v151, s[8:9]
	s_mov_b32 m0, s56
	s_nop 0
	global_load_lds_dwordx4 v153, s[8:9]
	s_mov_b32 m0, s57
	s_nop 0
	global_load_lds_dwordx4 v150, s[96:97]
	s_mov_b32 m0, s58
	s_nop 0
	global_load_lds_dwordx4 v152, s[96:97]
	s_add_u32 s8, s84, 0x40080
	s_addc_u32 s9, s85, 0
	s_mov_b32 m0, s59
	s_nop 0
	global_load_lds_dwordx4 v150, s[8:9]
	s_mov_b32 m0, s60
	s_nop 0
	global_load_lds_dwordx4 v152, s[8:9]
	s_waitcnt vmcnt(8)
	s_waitcnt lgkmcnt(0)
	s_barrier
	v_mfma_f32_16x16x32_bf16 v[68:71], v[128:131], v[144:147], v[68:71]
	v_mfma_f32_16x16x32_bf16 v[124:127], v[136:139], v[144:147], v[124:127]
	v_mfma_f32_16x16x32_bf16 v[48:51], v[128:131], v[182:185], v[48:51]
	v_mfma_f32_16x16x32_bf16 v[120:123], v[136:139], v[182:185], v[120:123]
	v_mfma_f32_16x16x32_bf16 v[44:47], v[128:131], v[190:193], v[44:47]
	v_mfma_f32_16x16x32_bf16 v[116:119], v[136:139], v[190:193], v[116:119]
	v_mfma_f32_16x16x32_bf16 v[40:43], v[128:131], v[198:201], v[40:43]
	v_mfma_f32_16x16x32_bf16 v[108:111], v[136:139], v[198:201], v[108:111]
	v_mfma_f32_16x16x32_bf16 v[20:23], v[128:131], v[214:217], v[20:23]
	v_mfma_f32_16x16x32_bf16 v[100:103], v[136:139], v[214:217], v[100:103]
	v_mfma_f32_16x16x32_bf16 v[8:11], v[128:131], v[222:225], v[8:11]
	v_mfma_f32_16x16x32_bf16 v[96:99], v[136:139], v[222:225], v[96:99]
	v_mfma_f32_16x16x32_bf16 v[4:7], v[128:131], v[230:233], v[4:7]
	v_mfma_f32_16x16x32_bf16 v[92:95], v[136:139], v[230:233], v[92:95]
	v_mfma_f32_16x16x32_bf16 v[0:3], v[128:131], v[238:241], v[0:3]
	v_mfma_f32_16x16x32_bf16 v[80:83], v[136:139], v[238:241], v[80:83]
	v_mfma_f32_16x16x32_bf16 v[68:71], v[132:135], v[178:181], v[68:71]
	v_mfma_f32_16x16x32_bf16 v[124:127], v[140:143], v[178:181], v[124:127]
	v_mfma_f32_16x16x32_bf16 v[48:51], v[132:135], v[186:189], v[48:51]
	v_mfma_f32_16x16x32_bf16 v[120:123], v[140:143], v[186:189], v[120:123]
	v_mfma_f32_16x16x32_bf16 v[44:47], v[132:135], v[194:197], v[44:47]
	v_mfma_f32_16x16x32_bf16 v[116:119], v[140:143], v[194:197], v[116:119]
	v_mfma_f32_16x16x32_bf16 v[40:43], v[132:135], v[202:205], v[40:43]
	v_mfma_f32_16x16x32_bf16 v[108:111], v[140:143], v[202:205], v[108:111]
	v_mfma_f32_16x16x32_bf16 v[20:23], v[132:135], v[218:221], v[20:23]
	v_mfma_f32_16x16x32_bf16 v[100:103], v[140:143], v[218:221], v[100:103]
	v_mfma_f32_16x16x32_bf16 v[8:11], v[132:135], v[226:229], v[8:11]
	v_mfma_f32_16x16x32_bf16 v[96:99], v[140:143], v[226:229], v[96:99]
	v_mfma_f32_16x16x32_bf16 v[4:7], v[132:135], v[234:237], v[4:7]
	v_mfma_f32_16x16x32_bf16 v[92:95], v[140:143], v[234:237], v[92:95]
	v_mfma_f32_16x16x32_bf16 v[0:3], v[132:135], v[242:245], v[0:3]
	v_mfma_f32_16x16x32_bf16 v[80:83], v[140:143], v[242:245], v[80:83]
	s_barrier
	s_add_i32 s68, s68, 2
	s_add_u32 s87, s87, 0x100
	s_addc_u32 s88, s88, 0
	s_cmp_gt_u32 s68, 13
	s_mov_b64 s[8:9], s[10:11]
	s_cbranch_scc0 .LBB0_584
	s_and_b64 vcc, exec, s[4:5]
	s_cbranch_vccz .LBB0_587
	s_barrier

; #define PG8_STAGE(bufoff, gbase, voff) do { _Pragma("unroll") for (int _i = 0; _i < 2; ++_i) { \
;         const unsigned _m0 = ldsu + (unsigned)(bufoff) + ldsw + (unsigned)(_i * 8192); \
;         asm volatile("s_mov_b32 m0, %2\n\ts_nop 0\n\tglobal_load_lds_dwordx4 %0, %1" :: "v"((voff)[_i]), "s"((const char*)(gbase)), "s"(_m0) : "memory"); } } while (0)
; #define PG8_LDA(dst, b, h) do { _Pragma("unroll") for (int m = 0; m < 4; ++m) _Pragma("unroll") for (int k = 0; k < 2; ++k) dst[m][k] = *(const LAS bf16x8*)(lds + PG8_SA(b, h) + aoff + m * 2048 + k * 1024); } while (0)
; #define PG8_LDB(dst, b, h) do { _Pragma("unroll") for (int n = 0; n < 2; ++n) _Pragma("unroll") for (int k = 0; k < 2; ++k) dst[n][k] = *(const LAS bf16x8*)(lds + bbase[b][h] + n * 2048 + k * 1024); } while (0)
; #define PG8_WAIT_V(n) asm volatile("s_waitcnt vmcnt(" #n ")" ::: "memory")
; #define PG8_WAIT_L(n) asm volatile("s_waitcnt lgkmcnt(" #n ")" ::: "memory")
; #define PG8_BAR __builtin_amdgcn_s_barrier()
; #define PG8_SCHED __builtin_amdgcn_sched_barrier(0)
; template <class Epi>
; __device__ __forceinline__ void gemm_phase(LAS unsigned char* lds, const Gemm g, const StaticOrder& S, const Epi& E) {
;     ...
;         for (int t = 0; t < nt; t += 2) {
;             const bool last = (t == nt - 2);
;             const char* a2 = last ? nA : cA + (size_t)(t + 2) * kstep; const char* b2 = last ? nB : cB + (size_t)(t + 2) * kstep;
;             const char* a3 = a2 + kstep; const char* b3 = b2 + kstep;
;             const char* b1 = cB + (size_t)(t + 1) * kstep;
;             PG8_LDB(B0, 0, 0); PG8_SCHED; PG8_LDA(At, 0, 0); PG8_LDA(At2, 0, 1); PG8_STAGE(PG8_SB(1, 1), b1 + hstepB, voffB);
;             PG8_WAIT_V(8); PG8_WAIT_L(0); PG8_BAR; PG8_MMA2B(0, At, At2, B0); PG8_BAR; PG8_SCHED;
;             PG8_LDB(B0, 0, 1); PG8_STAGE(PG8_SB(0, 0), b2, voffB); PG8_STAGE(PG8_SA(0, 0), a2, voffA); PG8_STAGE(PG8_SA(0, 1), a2 + hstepA, voffA);
;             PG8_WAIT_V(8); PG8_WAIT_L(0); PG8_BAR; PG8_MMA2B(1, At, At2, B0); PG8_BAR; PG8_SCHED;
.LBB0_662:
	s_add_i32 s85, s38, 2
	s_add_u32 s42, s67, 0x80
	ds_read_b128 v[74:77], v71
	ds_read_b128 v[78:81], v71 offset:1024
	ds_read_b128 v[82:85], v71 offset:2048
	ds_read_b128 v[86:89], v71 offset:3072
	s_addc_u32 s43, s68, 0
	s_cmp_eq_u32 s62, s38
	s_cselect_b32 s38, s10, s69
	s_cselect_b32 s39, s11, s84
	s_cselect_b32 s82, s37, s42
	s_cselect_b32 s83, s13, s43
	s_add_u32 s42, s38, 0x80
	s_addc_u32 s43, s39, 0
	s_add_u32 s80, s82, 0x80
	s_addc_u32 s81, s83, 0
	ds_read_b128 v[90:93], v72
	ds_read_b128 v[94:97], v72 offset:1024
	ds_read_b128 v[98:101], v72 offset:2048
	ds_read_b128 v[102:105], v72 offset:3072
	ds_read_b128 v[106:109], v72 offset:4096
	ds_read_b128 v[110:113], v72 offset:5120
	ds_read_b128 v[114:117], v72 offset:6144
	ds_read_b128 v[118:121], v72 offset:7168
	ds_read_b128 v[122:125], v72 offset:16384
	ds_read_b128 v[126:129], v72 offset:17408
	ds_read_b128 v[130:133], v72 offset:18432
	ds_read_b128 v[134:137], v72 offset:19456
	ds_read_b128 v[138:141], v72 offset:20480
	ds_read_b128 v[142:145], v72 offset:21504
	ds_read_b128 v[146:149], v72 offset:22528
	ds_read_b128 v[150:153], v72 offset:23552
	s_add_u32 s86, s67, 0x10000
	s_addc_u32 s87, s68, 0
	s_mov_b32 m0, s63
	s_nop 0
	global_load_lds_dwordx4 v67, s[86:87]
	s_mov_b32 m0, s64
	s_nop 0
	global_load_lds_dwordx4 v69, s[86:87]
	s_waitcnt vmcnt(8)
	s_waitcnt lgkmcnt(0)
	s_barrier
	v_mfma_f32_16x16x32_bf16 v[60:63], v[74:77], v[90:93], v[60:63]
	v_mfma_f32_16x16x32_bf16 v[56:59], v[82:85], v[90:93], v[56:59]
	v_mfma_f32_16x16x32_bf16 v[52:55], v[74:77], v[98:101], v[52:55]
	v_mfma_f32_16x16x32_bf16 v[48:51], v[82:85], v[98:101], v[48:51]
	v_mfma_f32_16x16x32_bf16 v[44:47], v[74:77], v[106:109], v[44:47]
	v_mfma_f32_16x16x32_bf16 v[40:43], v[82:85], v[106:109], v[40:43]
	v_mfma_f32_16x16x32_bf16 v[36:39], v[74:77], v[114:117], v[36:39]
	v_mfma_f32_16x16x32_bf16 v[32:35], v[82:85], v[114:117], v[32:35]
	v_mfma_f32_16x16x32_bf16 v[28:31], v[74:77], v[122:125], v[28:31]
	v_mfma_f32_16x16x32_bf16 v[24:27], v[82:85], v[122:125], v[24:27]
	v_mfma_f32_16x16x32_bf16 v[20:23], v[74:77], v[130:133], v[20:23]
	v_mfma_f32_16x16x32_bf16 v[16:19], v[82:85], v[130:133], v[16:19]
	v_mfma_f32_16x16x32_bf16 v[12:15], v[74:77], v[138:141], v[12:15]
	v_mfma_f32_16x16x32_bf16 v[8:11], v[82:85], v[138:141], v[8:11]
	v_mfma_f32_16x16x32_bf16 v[4:7], v[74:77], v[146:149], v[4:7]
	v_mfma_f32_16x16x32_bf16 v[0:3], v[82:85], v[146:149], v[0:3]
	v_mfma_f32_16x16x32_bf16 v[60:63], v[78:81], v[94:97], v[60:63]
	v_mfma_f32_16x16x32_bf16 v[56:59], v[86:89], v[94:97], v[56:59]
	v_mfma_f32_16x16x32_bf16 v[52:55], v[78:81], v[102:105], v[52:55]
	v_mfma_f32_16x16x32_bf16 v[48:51], v[86:89], v[102:105], v[48:51]
	v_mfma_f32_16x16x32_bf16 v[44:47], v[78:81], v[110:113], v[44:47]
	v_mfma_f32_16x16x32_bf16 v[40:43], v[86:89], v[110:113], v[40:43]
	v_mfma_f32_16x16x32_bf16 v[36:39], v[78:81], v[118:121], v[36:39]
	v_mfma_f32_16x16x32_bf16 v[32:35], v[86:89], v[118:121], v[32:35]
	v_mfma_f32_16x16x32_bf16 v[28:31], v[78:81], v[126:129], v[28:31]
	v_mfma_f32_16x16x32_bf16 v[24:27], v[86:89], v[126:129], v[24:27]
	v_mfma_f32_16x16x32_bf16 v[20:23], v[78:81], v[134:137], v[20:23]
	v_mfma_f32_16x16x32_bf16 v[16:19], v[86:89], v[134:137], v[16:19]
	v_mfma_f32_16x16x32_bf16 v[12:15], v[78:81], v[142:145], v[12:15]
	v_mfma_f32_16x16x32_bf16 v[8:11], v[86:89], v[142:145], v[8:11]
	v_mfma_f32_16x16x32_bf16 v[4:7], v[78:81], v[150:153], v[4:7]
	v_mfma_f32_16x16x32_bf16 v[0:3], v[86:89], v[150:153], v[0:3]
	s_barrier
	s_mov_b32 m0, s48
	s_nop 0
	global_load_lds_dwordx4 v67, s[82:83]
	s_mov_b32 m0, s49
	s_nop 0
	global_load_lds_dwordx4 v69, s[82:83]
	s_mov_b32 m0, s47
	s_nop 0
	global_load_lds_dwordx4 v66, s[38:39]
	s_mov_b32 m0, s50
	s_nop 0
	global_load_lds_dwordx4 v68, s[38:39]
	s_add_u32 s86, s38, 0x18000
	s_addc_u32 s87, s39, 0
	s_mov_b32 m0, s51
	s_nop 0
	global_load_lds_dwordx4 v66, s[86:87]
	s_mov_b32 m0, s52
	s_nop 0
	global_load_lds_dwordx4 v68, s[86:87]
	s_waitcnt vmcnt(8)
	s_waitcnt lgkmcnt(0)
	s_barrier
; #define PG8_STAGE(bufoff, gbase, voff) do { _Pragma("unroll") for (int _i = 0; _i < 2; ++_i) { \
;         const unsigned _m0 = ldsu + (unsigned)(bufoff) + ldsw + (unsigned)(_i * 8192); \
;         asm volatile("s_mov_b32 m0, %2\n\ts_nop 0\n\tglobal_load_lds_dwordx4 %0, %1" :: "v"((voff)[_i]), "s"((const char*)(gbase)), "s"(_m0) : "memory"); } } while (0)
; #define PG8_LDA(dst, b, h) do { _Pragma("unroll") for (int m = 0; m < 4; ++m) _Pragma("unroll") for (int k = 0; k < 2; ++k) dst[m][k] = *(const LAS bf16x8*)(lds + PG8_SA(b, h) + aoff + m * 2048 + k * 1024); } while (0)
; #define PG8_LDB(dst, b, h) do { _Pragma("unroll") for (int n = 0; n < 2; ++n) _Pragma("unroll") for (int k = 0; k < 2; ++k) dst[n][k] = *(const LAS bf16x8*)(lds + bbase[b][h] + n * 2048 + k * 1024); } while (0)
; #define PG8_WAIT_V(n) asm volatile("s_waitcnt vmcnt(" #n ")" ::: "memory")
; #define PG8_WAIT_L(n) asm volatile("s_waitcnt lgkmcnt(" #n ")" ::: "memory")
; #define PG8_BAR __builtin_amdgcn_s_barrier()
; #define PG8_SCHED __builtin_amdgcn_sched_barrier(0)
; template <class Epi>
; __device__ __forceinline__ void gemm_phase(LAS unsigned char* lds, const Gemm g, const StaticOrder& S, const Epi& E) {
;     ...
;             PG8_LDB(B0, 1, 0); PG8_SCHED; PG8_LDA(At, 1, 0); PG8_LDA(At2, 1, 1); PG8_STAGE(PG8_SB(0, 1), b2 + hstepB, voffB);
;             PG8_WAIT_V(8); PG8_WAIT_L(0); PG8_BAR; PG8_MMA2B(0, At, At2, B0); PG8_BAR; PG8_SCHED;
;             PG8_LDB(B0, 1, 1); PG8_STAGE(PG8_SB(1, 0), b3, voffB); PG8_STAGE(PG8_SA(1, 0), a3, voffA); PG8_STAGE(PG8_SA(1, 1), a3 + hstepA, voffA);
;             PG8_WAIT_V(8); PG8_WAIT_L(0); PG8_BAR; PG8_MMA2B(1, At, At2, B0); PG8_BAR; PG8_SCHED;
;         }
	s_barrier
	ds_read_b128 v[74:77], v73
	ds_read_b128 v[78:81], v73 offset:1024
	ds_read_b128 v[82:85], v73 offset:2048
	ds_read_b128 v[86:89], v73 offset:3072
	ds_read_b128 v[90:93], v72 offset:32768
	ds_read_b128 v[94:97], v72 offset:33792
	ds_read_b128 v[98:101], v72 offset:34816
	ds_read_b128 v[102:105], v72 offset:35840
	ds_read_b128 v[106:109], v72 offset:36864
	ds_read_b128 v[110:113], v72 offset:37888
	ds_read_b128 v[114:117], v72 offset:38912
	ds_read_b128 v[118:121], v72 offset:39936
	ds_read_b128 v[122:125], v72 offset:49152
	ds_read_b128 v[126:129], v72 offset:50176
	ds_read_b128 v[130:133], v72 offset:51200
	ds_read_b128 v[134:137], v72 offset:52224
	ds_read_b128 v[138:141], v72 offset:53248
	ds_read_b128 v[142:145], v72 offset:54272
	ds_read_b128 v[146:149], v72 offset:55296
	ds_read_b128 v[150:153], v72 offset:56320
	s_add_u32 s82, s82, 0x10000
	s_addc_u32 s83, s83, 0
	s_mov_b32 m0, s53
	s_nop 0
	global_load_lds_dwordx4 v67, s[82:83]
	s_mov_b32 m0, s54
	s_nop 0
	global_load_lds_dwordx4 v69, s[82:83]
	s_waitcnt vmcnt(8)
	s_waitcnt lgkmcnt(0)
	s_barrier
	v_mfma_f32_16x16x32_bf16 v[60:63], v[74:77], v[90:93], v[60:63]
	v_mfma_f32_16x16x32_bf16 v[56:59], v[82:85], v[90:93], v[56:59]
	v_mfma_f32_16x16x32_bf16 v[52:55], v[74:77], v[98:101], v[52:55]
	v_mfma_f32_16x16x32_bf16 v[48:51], v[82:85], v[98:101], v[48:51]
	v_mfma_f32_16x16x32_bf16 v[44:47], v[74:77], v[106:109], v[44:47]
	v_mfma_f32_16x16x32_bf16 v[40:43], v[82:85], v[106:109], v[40:43]
	v_mfma_f32_16x16x32_bf16 v[36:39], v[74:77], v[114:117], v[36:39]
	v_mfma_f32_16x16x32_bf16 v[32:35], v[82:85], v[114:117], v[32:35]
	v_mfma_f32_16x16x32_bf16 v[28:31], v[74:77], v[122:125], v[28:31]
	v_mfma_f32_16x16x32_bf16 v[24:27], v[82:85], v[122:125], v[24:27]
	v_mfma_f32_16x16x32_bf16 v[20:23], v[74:77], v[130:133], v[20:23]
	v_mfma_f32_16x16x32_bf16 v[16:19], v[82:85], v[130:133], v[16:19]
	v_mfma_f32_16x16x32_bf16 v[12:15], v[74:77], v[138:141], v[12:15]
	v_mfma_f32_16x16x32_bf16 v[8:11], v[82:85], v[138:141], v[8:11]
	v_mfma_f32_16x16x32_bf16 v[4:7], v[74:77], v[146:149], v[4:7]
	v_mfma_f32_16x16x32_bf16 v[0:3], v[82:85], v[146:149], v[0:3]
	v_mfma_f32_16x16x32_bf16 v[60:63], v[78:81], v[94:97], v[60:63]
	v_mfma_f32_16x16x32_bf16 v[56:59], v[86:89], v[94:97], v[56:59]
	v_mfma_f32_16x16x32_bf16 v[52:55], v[78:81], v[102:105], v[52:55]
	v_mfma_f32_16x16x32_bf16 v[48:51], v[86:89], v[102:105], v[48:51]
	v_mfma_f32_16x16x32_bf16 v[44:47], v[78:81], v[110:113], v[44:47]
	v_mfma_f32_16x16x32_bf16 v[40:43], v[86:89], v[110:113], v[40:43]
	v_mfma_f32_16x16x32_bf16 v[36:39], v[78:81], v[118:121], v[36:39]
	v_mfma_f32_16x16x32_bf16 v[32:35], v[86:89], v[118:121], v[32:35]
	v_mfma_f32_16x16x32_bf16 v[28:31], v[78:81], v[126:129], v[28:31]
	v_mfma_f32_16x16x32_bf16 v[24:27], v[86:89], v[126:129], v[24:27]
	v_mfma_f32_16x16x32_bf16 v[20:23], v[78:81], v[134:137], v[20:23]
	v_mfma_f32_16x16x32_bf16 v[16:19], v[86:89], v[134:137], v[16:19]
	v_mfma_f32_16x16x32_bf16 v[12:15], v[78:81], v[142:145], v[12:15]
	v_mfma_f32_16x16x32_bf16 v[8:11], v[86:89], v[142:145], v[8:11]
	v_mfma_f32_16x16x32_bf16 v[4:7], v[78:81], v[150:153], v[4:7]
	v_mfma_f32_16x16x32_bf16 v[0:3], v[86:89], v[150:153], v[0:3]
	s_barrier
	s_mov_b32 m0, s56
	s_nop 0
	global_load_lds_dwordx4 v67, s[80:81]
	s_mov_b32 m0, s57
	s_nop 0
	global_load_lds_dwordx4 v69, s[80:81]
	s_mov_b32 m0, s58
	s_nop 0
	global_load_lds_dwordx4 v66, s[42:43]
	s_mov_b32 m0, s59
	s_nop 0
	global_load_lds_dwordx4 v68, s[42:43]
	s_add_u32 s38, s38, 0x18080
	s_addc_u32 s39, s39, 0
	s_mov_b32 m0, s60
	s_nop 0
	global_load_lds_dwordx4 v66, s[38:39]
	s_mov_b32 m0, s61
	s_nop 0
	global_load_lds_dwordx4 v68, s[38:39]
	s_waitcnt vmcnt(8)
	s_waitcnt lgkmcnt(0)
	s_barrier
	s_barrier
	s_add_u32 s67, s67, 0x100
	s_addc_u32 s68, s68, 0
	s_add_u32 s69, s69, 0x100
	s_addc_u32 s84, s84, 0
	s_cmp_ge_i32 s85, s55
	s_mov_b32 s38, s85
	s_cbranch_scc0 .LBB0_662

; #define PG8_STAGE(bufoff, gbase, voff) do { _Pragma("unroll") for (int _i = 0; _i < 2; ++_i) { \
;         const unsigned _m0 = ldsu + (unsigned)(bufoff) + ldsw + (unsigned)(_i * 8192); \
;         asm volatile("s_mov_b32 m0, %2\n\ts_nop 0\n\tglobal_load_lds_dwordx4 %0, %1" :: "v"((voff)[_i]), "s"((const char*)(gbase)), "s"(_m0) : "memory"); } } while (0)
; #define PG8_LDA(dst, b, h) do { _Pragma("unroll") for (int m = 0; m < 4; ++m) _Pragma("unroll") for (int k = 0; k < 2; ++k) dst[m][k] = *(const LAS bf16x8*)(lds + PG8_SA(b, h) + aoff + m * 2048 + k * 1024); } while (0)
; #define PG8_LDB(dst, b, h) do { _Pragma("unroll") for (int n = 0; n < 2; ++n) _Pragma("unroll") for (int k = 0; k < 2; ++k) dst[n][k] = *(const LAS bf16x8*)(lds + bbase[b][h] + n * 2048 + k * 1024); } while (0)
; #define PG8_WAIT_V(n) asm volatile("s_waitcnt vmcnt(" #n ")" ::: "memory")
; #define PG8_WAIT_L(n) asm volatile("s_waitcnt lgkmcnt(" #n ")" ::: "memory")
; #define PG8_BAR __builtin_amdgcn_s_barrier()
; #define PG8_SCHED __builtin_amdgcn_sched_barrier(0)
; template <class Epi>
; __device__ __forceinline__ void gemm_phase(LAS unsigned char* lds, const Gemm g, const StaticOrder& S, const Epi& E) {
;     ...
;         for (int t = 0; t < nt; t += 2) {
;             const bool last = (t == nt - 2);
;             const char* a2 = last ? nA : cA + (size_t)(t + 2) * kstep; const char* b2 = last ? nB : cB + (size_t)(t + 2) * kstep;
;             const char* a3 = a2 + kstep; const char* b3 = b2 + kstep;
;             const char* b1 = cB + (size_t)(t + 1) * kstep;
;             PG8_LDB(B0, 0, 0); PG8_SCHED; PG8_LDA(At, 0, 0); PG8_LDA(At2, 0, 1); PG8_STAGE(PG8_SB(1, 1), b1 + hstepB, voffB);
;             PG8_WAIT_V(8); PG8_WAIT_L(0); PG8_BAR; PG8_MMA2B(0, At, At2, B0); PG8_BAR; PG8_SCHED;
;             PG8_LDB(B0, 0, 1); PG8_STAGE(PG8_SB(0, 0), b2, voffB); PG8_STAGE(PG8_SA(0, 0), a2, voffA); PG8_STAGE(PG8_SA(0, 1), a2 + hstepA, voffA);
;             PG8_WAIT_V(8); PG8_WAIT_L(0); PG8_BAR; PG8_MMA2B(1, At, At2, B0); PG8_BAR; PG8_SCHED;
.LBB0_797:
	s_add_i32 s52, s4, 2
	s_add_u32 s38, s1, 0x80
	ds_read_b128 v[128:131], v153
	ds_read_b128 v[132:135], v153 offset:1024
	ds_read_b128 v[142:145], v153 offset:2048
	ds_read_b128 v[178:181], v153 offset:3072
	s_addc_u32 s39, s43, 0
	s_cmp_eq_u32 s47, s4
	s_cselect_b32 s4, s16, s50
	s_cselect_b32 s5, s17, s51
	s_cselect_b32 s82, s10, s38
	s_cselect_b32 s83, s11, s39
	s_add_u32 s38, s4, 0x80
	s_addc_u32 s39, s5, 0
	s_add_u32 s80, s82, 0x80
	s_addc_u32 s81, s83, 0
	ds_read_b128 v[182:185], v154
	ds_read_b128 v[186:189], v154 offset:1024
	ds_read_b128 v[190:193], v154 offset:2048
	ds_read_b128 v[194:197], v154 offset:3072
	ds_read_b128 v[198:201], v154 offset:4096
	ds_read_b128 v[202:205], v154 offset:5120
	ds_read_b128 v[214:217], v154 offset:6144
	ds_read_b128 v[218:221], v154 offset:7168
	ds_read_b128 v[222:225], v154 offset:16384
	ds_read_b128 v[226:229], v154 offset:17408
	ds_read_b128 v[230:233], v154 offset:18432
	ds_read_b128 v[234:237], v154 offset:19456
	ds_read_b128 v[238:241], v154 offset:20480
	ds_read_b128 v[242:245], v154 offset:21504
	ds_read_b128 v[246:249], v154 offset:22528
	ds_read_b128 v[166:169], v154 offset:23552
	s_add_u32 s54, s1, 0x18000
	s_addc_u32 s55, s43, 0
	s_mov_b32 m0, s87
	s_nop 0
	global_load_lds_dwordx4 v147, s[54:55]
	s_mov_b32 m0, s28
	s_nop 0
	global_load_lds_dwordx4 v149, s[54:55]
	s_waitcnt vmcnt(8)
	s_waitcnt lgkmcnt(0)
	s_barrier
	v_mfma_f32_16x16x32_bf16 v[124:127], v[128:131], v[182:185], v[124:127]
	v_mfma_f32_16x16x32_bf16 v[120:123], v[142:145], v[182:185], v[120:123]
	v_mfma_f32_16x16x32_bf16 v[108:111], v[128:131], v[190:193], v[108:111]
	v_mfma_f32_16x16x32_bf16 v[104:107], v[142:145], v[190:193], v[104:107]
	v_mfma_f32_16x16x32_bf16 v[92:95], v[128:131], v[198:201], v[92:95]
	v_mfma_f32_16x16x32_bf16 v[88:91], v[142:145], v[198:201], v[88:91]
	v_mfma_f32_16x16x32_bf16 v[76:79], v[128:131], v[214:217], v[76:79]
	v_mfma_f32_16x16x32_bf16 v[72:75], v[142:145], v[214:217], v[72:75]
	v_mfma_f32_16x16x32_bf16 v[60:63], v[128:131], v[222:225], v[60:63]
	v_mfma_f32_16x16x32_bf16 v[56:59], v[142:145], v[222:225], v[56:59]
	v_mfma_f32_16x16x32_bf16 v[44:47], v[128:131], v[230:233], v[44:47]
	v_mfma_f32_16x16x32_bf16 v[40:43], v[142:145], v[230:233], v[40:43]
	v_mfma_f32_16x16x32_bf16 v[28:31], v[128:131], v[238:241], v[28:31]
	v_mfma_f32_16x16x32_bf16 v[24:27], v[142:145], v[238:241], v[24:27]
	v_mfma_f32_16x16x32_bf16 v[12:15], v[128:131], v[246:249], v[12:15]
	v_mfma_f32_16x16x32_bf16 v[8:11], v[142:145], v[246:249], v[8:11]
	v_mfma_f32_16x16x32_bf16 v[124:127], v[132:135], v[186:189], v[124:127]
	v_mfma_f32_16x16x32_bf16 v[120:123], v[178:181], v[186:189], v[120:123]
	v_mfma_f32_16x16x32_bf16 v[108:111], v[132:135], v[194:197], v[108:111]
	v_mfma_f32_16x16x32_bf16 v[104:107], v[178:181], v[194:197], v[104:107]
	v_mfma_f32_16x16x32_bf16 v[92:95], v[132:135], v[202:205], v[92:95]
	v_mfma_f32_16x16x32_bf16 v[88:91], v[178:181], v[202:205], v[88:91]
	v_mfma_f32_16x16x32_bf16 v[76:79], v[132:135], v[218:221], v[76:79]
	v_mfma_f32_16x16x32_bf16 v[72:75], v[178:181], v[218:221], v[72:75]
	v_mfma_f32_16x16x32_bf16 v[60:63], v[132:135], v[226:229], v[60:63]
	v_mfma_f32_16x16x32_bf16 v[56:59], v[178:181], v[226:229], v[56:59]
	v_mfma_f32_16x16x32_bf16 v[44:47], v[132:135], v[234:237], v[44:47]
	v_mfma_f32_16x16x32_bf16 v[40:43], v[178:181], v[234:237], v[40:43]
	v_mfma_f32_16x16x32_bf16 v[28:31], v[132:135], v[242:245], v[28:31]
	v_mfma_f32_16x16x32_bf16 v[24:27], v[178:181], v[242:245], v[24:27]
	v_mfma_f32_16x16x32_bf16 v[12:15], v[132:135], v[166:169], v[12:15]
	v_mfma_f32_16x16x32_bf16 v[8:11], v[178:181], v[166:169], v[8:11]
	s_barrier
	ds_read_b128 v[128:131], v155
	ds_read_b128 v[132:135], v155 offset:1024
	ds_read_b128 v[142:145], v155 offset:2048
	ds_read_b128 v[178:181], v155 offset:3072
	s_mov_b32 m0, s90
	s_nop 0
	global_load_lds_dwordx4 v147, s[82:83]
	s_mov_b32 m0, s91
	s_nop 0
	global_load_lds_dwordx4 v149, s[82:83]
	s_mov_b32 m0, s85
	s_nop 0
	global_load_lds_dwordx4 v146, s[4:5]
	s_mov_b32 m0, s95
	s_nop 0
	global_load_lds_dwordx4 v148, s[4:5]
	s_add_u32 s54, s4, 0x18000
	s_addc_u32 s55, s5, 0
	s_mov_b32 m0, s96
	s_nop 0
	global_load_lds_dwordx4 v146, s[54:55]
	s_mov_b32 m0, s97
	s_nop 0
	global_load_lds_dwordx4 v148, s[54:55]
	s_waitcnt vmcnt(8)
	s_waitcnt lgkmcnt(0)
	s_barrier
	v_mfma_f32_16x16x32_bf16 v[116:119], v[128:131], v[182:185], v[116:119]
	v_mfma_f32_16x16x32_bf16 v[112:115], v[142:145], v[182:185], v[112:115]
	v_mfma_f32_16x16x32_bf16 v[100:103], v[128:131], v[190:193], v[100:103]
	v_mfma_f32_16x16x32_bf16 v[96:99], v[142:145], v[190:193], v[96:99]
	v_mfma_f32_16x16x32_bf16 v[84:87], v[128:131], v[198:201], v[84:87]
	v_mfma_f32_16x16x32_bf16 v[80:83], v[142:145], v[198:201], v[80:83]
	v_mfma_f32_16x16x32_bf16 v[68:71], v[128:131], v[214:217], v[68:71]
	v_mfma_f32_16x16x32_bf16 v[64:67], v[142:145], v[214:217], v[64:67]
	v_mfma_f32_16x16x32_bf16 v[52:55], v[128:131], v[222:225], v[52:55]
	v_mfma_f32_16x16x32_bf16 v[48:51], v[142:145], v[222:225], v[48:51]
	v_mfma_f32_16x16x32_bf16 v[36:39], v[128:131], v[230:233], v[36:39]
	v_mfma_f32_16x16x32_bf16 v[32:35], v[142:145], v[230:233], v[32:35]
	v_mfma_f32_16x16x32_bf16 v[20:23], v[128:131], v[238:241], v[20:23]
	v_mfma_f32_16x16x32_bf16 v[16:19], v[142:145], v[238:241], v[16:19]
	v_mfma_f32_16x16x32_bf16 v[4:7], v[128:131], v[246:249], v[4:7]
	v_mfma_f32_16x16x32_bf16 v[0:3], v[142:145], v[246:249], v[0:3]
	v_mfma_f32_16x16x32_bf16 v[116:119], v[132:135], v[186:189], v[116:119]
	v_mfma_f32_16x16x32_bf16 v[112:115], v[178:181], v[186:189], v[112:115]
	v_mfma_f32_16x16x32_bf16 v[100:103], v[132:135], v[194:197], v[100:103]
	v_mfma_f32_16x16x32_bf16 v[96:99], v[178:181], v[194:197], v[96:99]
	v_mfma_f32_16x16x32_bf16 v[84:87], v[132:135], v[202:205], v[84:87]
	v_mfma_f32_16x16x32_bf16 v[80:83], v[178:181], v[202:205], v[80:83]
	v_mfma_f32_16x16x32_bf16 v[68:71], v[132:135], v[218:221], v[68:71]
	v_mfma_f32_16x16x32_bf16 v[64:67], v[178:181], v[218:221], v[64:67]
	v_mfma_f32_16x16x32_bf16 v[52:55], v[132:135], v[226:229], v[52:55]
	v_mfma_f32_16x16x32_bf16 v[48:51], v[178:181], v[226:229], v[48:51]
	v_mfma_f32_16x16x32_bf16 v[36:39], v[132:135], v[234:237], v[36:39]
	v_mfma_f32_16x16x32_bf16 v[32:35], v[178:181], v[234:237], v[32:35]
	v_mfma_f32_16x16x32_bf16 v[20:23], v[132:135], v[242:245], v[20:23]
	v_mfma_f32_16x16x32_bf16 v[16:19], v[178:181], v[242:245], v[16:19]
	v_mfma_f32_16x16x32_bf16 v[4:7], v[132:135], v[166:169], v[4:7]
	v_mfma_f32_16x16x32_bf16 v[0:3], v[178:181], v[166:169], v[0:3]
	s_barrier
; #define PG8_STAGE(bufoff, gbase, voff) do { _Pragma("unroll") for (int _i = 0; _i < 2; ++_i) { \
;         const unsigned _m0 = ldsu + (unsigned)(bufoff) + ldsw + (unsigned)(_i * 8192); \
;         asm volatile("s_mov_b32 m0, %2\n\ts_nop 0\n\tglobal_load_lds_dwordx4 %0, %1" :: "v"((voff)[_i]), "s"((const char*)(gbase)), "s"(_m0) : "memory"); } } while (0)
; #define PG8_LDA(dst, b, h) do { _Pragma("unroll") for (int m = 0; m < 4; ++m) _Pragma("unroll") for (int k = 0; k < 2; ++k) dst[m][k] = *(const LAS bf16x8*)(lds + PG8_SA(b, h) + aoff + m * 2048 + k * 1024); } while (0)
; #define PG8_LDB(dst, b, h) do { _Pragma("unroll") for (int n = 0; n < 2; ++n) _Pragma("unroll") for (int k = 0; k < 2; ++k) dst[n][k] = *(const LAS bf16x8*)(lds + bbase[b][h] + n * 2048 + k * 1024); } while (0)
; #define PG8_WAIT_V(n) asm volatile("s_waitcnt vmcnt(" #n ")" ::: "memory")
; #define PG8_WAIT_L(n) asm volatile("s_waitcnt lgkmcnt(" #n ")" ::: "memory")
; #define PG8_BAR __builtin_amdgcn_s_barrier()
; #define PG8_SCHED __builtin_amdgcn_sched_barrier(0)
; template <class Epi>
; __device__ __forceinline__ void gemm_phase(LAS unsigned char* lds, const Gemm g, const StaticOrder& S, const Epi& E) {
;     ...
;             PG8_LDB(B0, 1, 0); PG8_SCHED; PG8_LDA(At, 1, 0); PG8_LDA(At2, 1, 1); PG8_STAGE(PG8_SB(0, 1), b2 + hstepB, voffB);
;             PG8_WAIT_V(8); PG8_WAIT_L(0); PG8_BAR; PG8_MMA2B(0, At, At2, B0); PG8_BAR; PG8_SCHED;
;             PG8_LDB(B0, 1, 1); PG8_STAGE(PG8_SB(1, 0), b3, voffB); PG8_STAGE(PG8_SA(1, 0), a3, voffA); PG8_STAGE(PG8_SA(1, 1), a3 + hstepA, voffA);
;             PG8_WAIT_V(8); PG8_WAIT_L(0); PG8_BAR; PG8_MMA2B(1, At, At2, B0); PG8_BAR; PG8_SCHED;
	ds_read_b128 v[128:131], v156
	ds_read_b128 v[132:135], v156 offset:1024
	ds_read_b128 v[142:145], v156 offset:2048
	ds_read_b128 v[166:169], v156 offset:3072
	ds_read_b128 v[178:181], v154 offset:32768
	ds_read_b128 v[182:185], v154 offset:33792
	ds_read_b128 v[186:189], v154 offset:34816
	ds_read_b128 v[190:193], v154 offset:35840
	ds_read_b128 v[194:197], v154 offset:36864
	ds_read_b128 v[198:201], v154 offset:37888
	ds_read_b128 v[202:205], v154 offset:38912
	ds_read_b128 v[214:217], v154 offset:39936
	ds_read_b128 v[218:221], v154 offset:49152
	ds_read_b128 v[222:225], v154 offset:50176
	ds_read_b128 v[226:229], v154 offset:51200
	ds_read_b128 v[230:233], v154 offset:52224
	ds_read_b128 v[234:237], v154 offset:53248
	ds_read_b128 v[238:241], v154 offset:54272
	ds_read_b128 v[242:245], v154 offset:55296
	ds_read_b128 v[246:249], v154 offset:56320
	s_add_u32 s54, s82, 0x18000
	s_addc_u32 s55, s83, 0
	s_mov_b32 m0, s6
	s_nop 0
	global_load_lds_dwordx4 v147, s[54:55]
	s_mov_b32 m0, s7
	s_nop 0
	global_load_lds_dwordx4 v149, s[54:55]
	s_waitcnt vmcnt(8)
	s_waitcnt lgkmcnt(0)
	s_barrier
	v_mfma_f32_16x16x32_bf16 v[124:127], v[128:131], v[178:181], v[124:127]
	v_mfma_f32_16x16x32_bf16 v[120:123], v[142:145], v[178:181], v[120:123]
	v_mfma_f32_16x16x32_bf16 v[108:111], v[128:131], v[186:189], v[108:111]
	v_mfma_f32_16x16x32_bf16 v[104:107], v[142:145], v[186:189], v[104:107]
	v_mfma_f32_16x16x32_bf16 v[92:95], v[128:131], v[194:197], v[92:95]
	v_mfma_f32_16x16x32_bf16 v[88:91], v[142:145], v[194:197], v[88:91]
	v_mfma_f32_16x16x32_bf16 v[76:79], v[128:131], v[202:205], v[76:79]
	v_mfma_f32_16x16x32_bf16 v[72:75], v[142:145], v[202:205], v[72:75]
	v_mfma_f32_16x16x32_bf16 v[60:63], v[128:131], v[218:221], v[60:63]
	v_mfma_f32_16x16x32_bf16 v[56:59], v[142:145], v[218:221], v[56:59]
	v_mfma_f32_16x16x32_bf16 v[44:47], v[128:131], v[226:229], v[44:47]
	v_mfma_f32_16x16x32_bf16 v[40:43], v[142:145], v[226:229], v[40:43]
	v_mfma_f32_16x16x32_bf16 v[28:31], v[128:131], v[234:237], v[28:31]
	v_mfma_f32_16x16x32_bf16 v[24:27], v[142:145], v[234:237], v[24:27]
	v_mfma_f32_16x16x32_bf16 v[12:15], v[128:131], v[242:245], v[12:15]
	v_mfma_f32_16x16x32_bf16 v[8:11], v[142:145], v[242:245], v[8:11]
	v_mfma_f32_16x16x32_bf16 v[124:127], v[132:135], v[182:185], v[124:127]
	v_mfma_f32_16x16x32_bf16 v[120:123], v[166:169], v[182:185], v[120:123]
	v_mfma_f32_16x16x32_bf16 v[108:111], v[132:135], v[190:193], v[108:111]
	v_mfma_f32_16x16x32_bf16 v[104:107], v[166:169], v[190:193], v[104:107]
	v_mfma_f32_16x16x32_bf16 v[92:95], v[132:135], v[198:201], v[92:95]
	v_mfma_f32_16x16x32_bf16 v[88:91], v[166:169], v[198:201], v[88:91]
	v_mfma_f32_16x16x32_bf16 v[76:79], v[132:135], v[214:217], v[76:79]
	v_mfma_f32_16x16x32_bf16 v[72:75], v[166:169], v[214:217], v[72:75]
	v_mfma_f32_16x16x32_bf16 v[60:63], v[132:135], v[222:225], v[60:63]
	v_mfma_f32_16x16x32_bf16 v[56:59], v[166:169], v[222:225], v[56:59]
	v_mfma_f32_16x16x32_bf16 v[44:47], v[132:135], v[230:233], v[44:47]
	v_mfma_f32_16x16x32_bf16 v[40:43], v[166:169], v[230:233], v[40:43]
	v_mfma_f32_16x16x32_bf16 v[28:31], v[132:135], v[238:241], v[28:31]
	v_mfma_f32_16x16x32_bf16 v[24:27], v[166:169], v[238:241], v[24:27]
	v_mfma_f32_16x16x32_bf16 v[12:15], v[132:135], v[246:249], v[12:15]
	v_mfma_f32_16x16x32_bf16 v[8:11], v[166:169], v[246:249], v[8:11]
	s_barrier
	ds_read_b128 v[128:131], v157
	ds_read_b128 v[132:135], v157 offset:1024
	ds_read_b128 v[142:145], v157 offset:2048
	ds_read_b128 v[166:169], v157 offset:3072
	s_mov_b32 m0, s2
	s_nop 0
	global_load_lds_dwordx4 v147, s[80:81]
	s_mov_b32 m0, s3
	s_nop 0
	global_load_lds_dwordx4 v149, s[80:81]
	s_mov_b32 m0, s88
	s_nop 0
	global_load_lds_dwordx4 v146, s[38:39]
	s_mov_b32 m0, s89
	s_nop 0
	global_load_lds_dwordx4 v148, s[38:39]
	s_add_u32 s4, s4, 0x18080
	s_addc_u32 s5, s5, 0
	s_mov_b32 m0, s37
	s_nop 0
	global_load_lds_dwordx4 v146, s[4:5]
	s_mov_b32 m0, s84
	s_nop 0
	global_load_lds_dwordx4 v148, s[4:5]
	s_waitcnt vmcnt(8)
	s_waitcnt lgkmcnt(0)
	s_barrier
	v_mfma_f32_16x16x32_bf16 v[116:119], v[128:131], v[178:181], v[116:119]
	v_mfma_f32_16x16x32_bf16 v[112:115], v[142:145], v[178:181], v[112:115]
	v_mfma_f32_16x16x32_bf16 v[100:103], v[128:131], v[186:189], v[100:103]
	v_mfma_f32_16x16x32_bf16 v[96:99], v[142:145], v[186:189], v[96:99]
	v_mfma_f32_16x16x32_bf16 v[84:87], v[128:131], v[194:197], v[84:87]
	v_mfma_f32_16x16x32_bf16 v[80:83], v[142:145], v[194:197], v[80:83]
	v_mfma_f32_16x16x32_bf16 v[68:71], v[128:131], v[202:205], v[68:71]
	v_mfma_f32_16x16x32_bf16 v[64:67], v[142:145], v[202:205], v[64:67]
	v_mfma_f32_16x16x32_bf16 v[52:55], v[128:131], v[218:221], v[52:55]
	v_mfma_f32_16x16x32_bf16 v[48:51], v[142:145], v[218:221], v[48:51]
	v_mfma_f32_16x16x32_bf16 v[36:39], v[128:131], v[226:229], v[36:39]
	v_mfma_f32_16x16x32_bf16 v[32:35], v[142:145], v[226:229], v[32:35]
	v_mfma_f32_16x16x32_bf16 v[20:23], v[128:131], v[234:237], v[20:23]
	v_mfma_f32_16x16x32_bf16 v[16:19], v[142:145], v[234:237], v[16:19]
	v_mfma_f32_16x16x32_bf16 v[4:7], v[128:131], v[242:245], v[4:7]
	v_mfma_f32_16x16x32_bf16 v[0:3], v[142:145], v[242:245], v[0:3]
	v_mfma_f32_16x16x32_bf16 v[116:119], v[132:135], v[182:185], v[116:119]
	v_mfma_f32_16x16x32_bf16 v[112:115], v[166:169], v[182:185], v[112:115]
	v_mfma_f32_16x16x32_bf16 v[100:103], v[132:135], v[190:193], v[100:103]
	v_mfma_f32_16x16x32_bf16 v[96:99], v[166:169], v[190:193], v[96:99]
	v_mfma_f32_16x16x32_bf16 v[84:87], v[132:135], v[198:201], v[84:87]
	v_mfma_f32_16x16x32_bf16 v[80:83], v[166:169], v[198:201], v[80:83]
	v_mfma_f32_16x16x32_bf16 v[68:71], v[132:135], v[214:217], v[68:71]
	v_mfma_f32_16x16x32_bf16 v[64:67], v[166:169], v[214:217], v[64:67]
	v_mfma_f32_16x16x32_bf16 v[52:55], v[132:135], v[222:225], v[52:55]
	v_mfma_f32_16x16x32_bf16 v[48:51], v[166:169], v[222:225], v[48:51]
	v_mfma_f32_16x16x32_bf16 v[36:39], v[132:135], v[230:233], v[36:39]
	v_mfma_f32_16x16x32_bf16 v[32:35], v[166:169], v[230:233], v[32:35]
	v_mfma_f32_16x16x32_bf16 v[20:23], v[132:135], v[238:241], v[20:23]
	v_mfma_f32_16x16x32_bf16 v[16:19], v[166:169], v[238:241], v[16:19]
	v_mfma_f32_16x16x32_bf16 v[4:7], v[132:135], v[246:249], v[4:7]
	v_mfma_f32_16x16x32_bf16 v[0:3], v[166:169], v[246:249], v[0:3]
	s_barrier
	s_add_u32 s1, s1, 0x100
	s_addc_u32 s43, s43, 0
	s_add_u32 s50, s50, 0x100
	s_addc_u32 s51, s51, 0
	s_cmp_ge_i32 s52, s86
	s_mov_b32 s4, s52
	s_cbranch_scc0 .LBB0_797
	v_readlane_b32 s52, v252, 7
	v_readlane_b32 s54, v254, 61
	v_readlane_b32 s53, v252, 8
	v_readlane_b32 s55, v254, 62
	v_mov_b32_e32 v246, v141

; #define PG8_STAGE(bufoff, gbase, voff) do { _Pragma("unroll") for (int _i = 0; _i < 2; ++_i) { \
;         const unsigned _m0 = ldsu + (unsigned)(bufoff) + ldsw + (unsigned)(_i * 8192); \
;         asm volatile("s_mov_b32 m0, %2\n\ts_nop 0\n\tglobal_load_lds_dwordx4 %0, %1" :: "v"((voff)[_i]), "s"((const char*)(gbase)), "s"(_m0) : "memory"); } } while (0)
; #define PG8_LDA(dst, b, h) do { _Pragma("unroll") for (int m = 0; m < 4; ++m) _Pragma("unroll") for (int k = 0; k < 2; ++k) dst[m][k] = *(const LAS bf16x8*)(lds + PG8_SA(b, h) + aoff + m * 2048 + k * 1024); } while (0)
; #define PG8_LDB(dst, b, h) do { _Pragma("unroll") for (int n = 0; n < 2; ++n) _Pragma("unroll") for (int k = 0; k < 2; ++k) dst[n][k] = *(const LAS bf16x8*)(lds + bbase[b][h] + n * 2048 + k * 1024); } while (0)
; #define PG8_WAIT_V(n) asm volatile("s_waitcnt vmcnt(" #n ")" ::: "memory")
; #define PG8_WAIT_L(n) asm volatile("s_waitcnt lgkmcnt(" #n ")" ::: "memory")
; #define PG8_BAR __builtin_amdgcn_s_barrier()
; #define PG8_SCHED __builtin_amdgcn_sched_barrier(0)
; template <class Epi>
; __device__ __forceinline__ void gemm_phase(LAS unsigned char* lds, const Gemm g, const StaticOrder& S, const Epi& E) {
;     ...
;         for (int t = 0; t < nt; t += 2) {
;             const bool last = (t == nt - 2);
;             const char* a2 = last ? nA : cA + (size_t)(t + 2) * kstep; const char* b2 = last ? nB : cB + (size_t)(t + 2) * kstep;
;             const char* a3 = a2 + kstep; const char* b3 = b2 + kstep;
;             const char* b1 = cB + (size_t)(t + 1) * kstep;
;             PG8_LDB(B0, 0, 0); PG8_SCHED; PG8_LDA(At, 0, 0); PG8_LDA(At2, 0, 1); PG8_STAGE(PG8_SB(1, 1), b1 + hstepB, voffB);
;             PG8_WAIT_V(8); PG8_WAIT_L(0); PG8_BAR; PG8_MMA2B(0, At, At2, B0); PG8_BAR; PG8_SCHED;
;             PG8_LDB(B0, 0, 1); PG8_STAGE(PG8_SB(0, 0), b2, voffB); PG8_STAGE(PG8_SA(0, 0), a2, voffA); PG8_STAGE(PG8_SA(0, 1), a2 + hstepA, voffA);
;             PG8_WAIT_V(8); PG8_WAIT_L(0); PG8_BAR; PG8_MMA2B(1, At, At2, B0); PG8_BAR; PG8_SCHED;
.LBB0_870:
	ds_read_b128 v[128:131], v140
	ds_read_b128 v[146:149], v140 offset:1024
	ds_read_b128 v[150:153], v140 offset:2048
	ds_read_b128 v[154:157], v140 offset:3072
	s_add_u32 s38, s16, 0x100
	s_addc_u32 s39, s17, 0
	s_cmp_eq_u32 s68, 4
	s_cselect_b32 s42, s65, s67
	s_cselect_b32 s43, s11, s84
	s_cselect_b32 s82, s66, s38
	s_cselect_b32 s83, s9, s39
	s_add_u32 s80, s42, 0x80
	s_addc_u32 s81, s43, 0
	ds_read_b128 v[166:169], v141
	ds_read_b128 v[178:181], v141 offset:1024
	ds_read_b128 v[182:185], v141 offset:2048
	ds_read_b128 v[186:189], v141 offset:3072
	ds_read_b128 v[190:193], v141 offset:4096
	ds_read_b128 v[194:197], v141 offset:5120
	ds_read_b128 v[198:201], v141 offset:6144
	ds_read_b128 v[202:205], v141 offset:7168
	ds_read_b128 v[214:217], v141 offset:16384
	ds_read_b128 v[218:221], v141 offset:17408
	ds_read_b128 v[222:225], v141 offset:18432
	ds_read_b128 v[226:229], v141 offset:19456
	ds_read_b128 v[230:233], v141 offset:20480
	ds_read_b128 v[234:237], v141 offset:21504
	ds_read_b128 v[238:241], v141 offset:22528
	ds_read_b128 v[242:245], v141 offset:23552
	s_add_u32 s16, s16, 0x20080
	s_addc_u32 s17, s17, 0
	s_mov_b32 m0, s60
	s_nop 0
	global_load_lds_dwordx4 v135, s[16:17]
	s_mov_b32 m0, s61
	s_nop 0
	global_load_lds_dwordx4 v137, s[16:17]
	s_waitcnt vmcnt(8)
	s_waitcnt lgkmcnt(0)
	s_barrier
	v_mfma_f32_16x16x32_bf16 v[124:127], v[128:131], v[166:169], v[124:127]
	v_mfma_f32_16x16x32_bf16 v[120:123], v[150:153], v[166:169], v[120:123]
	v_mfma_f32_16x16x32_bf16 v[108:111], v[128:131], v[182:185], v[108:111]
	v_mfma_f32_16x16x32_bf16 v[104:107], v[150:153], v[182:185], v[104:107]
	v_mfma_f32_16x16x32_bf16 v[92:95], v[128:131], v[190:193], v[92:95]
	v_mfma_f32_16x16x32_bf16 v[88:91], v[150:153], v[190:193], v[88:91]
	v_mfma_f32_16x16x32_bf16 v[76:79], v[128:131], v[198:201], v[76:79]
	v_mfma_f32_16x16x32_bf16 v[72:75], v[150:153], v[198:201], v[72:75]
	v_mfma_f32_16x16x32_bf16 v[60:63], v[128:131], v[214:217], v[60:63]
	v_mfma_f32_16x16x32_bf16 v[56:59], v[150:153], v[214:217], v[56:59]
	v_mfma_f32_16x16x32_bf16 v[44:47], v[128:131], v[222:225], v[44:47]
	v_mfma_f32_16x16x32_bf16 v[40:43], v[150:153], v[222:225], v[40:43]
	v_mfma_f32_16x16x32_bf16 v[28:31], v[128:131], v[230:233], v[28:31]
	v_mfma_f32_16x16x32_bf16 v[24:27], v[150:153], v[230:233], v[24:27]
	v_mfma_f32_16x16x32_bf16 v[12:15], v[128:131], v[238:241], v[12:15]
	v_mfma_f32_16x16x32_bf16 v[8:11], v[150:153], v[238:241], v[8:11]
	v_mfma_f32_16x16x32_bf16 v[124:127], v[146:149], v[178:181], v[124:127]
	v_mfma_f32_16x16x32_bf16 v[120:123], v[154:157], v[178:181], v[120:123]
	v_mfma_f32_16x16x32_bf16 v[108:111], v[146:149], v[186:189], v[108:111]
	v_mfma_f32_16x16x32_bf16 v[104:107], v[154:157], v[186:189], v[104:107]
	v_mfma_f32_16x16x32_bf16 v[92:95], v[146:149], v[194:197], v[92:95]
	v_mfma_f32_16x16x32_bf16 v[88:91], v[154:157], v[194:197], v[88:91]
	v_mfma_f32_16x16x32_bf16 v[76:79], v[146:149], v[202:205], v[76:79]
	v_mfma_f32_16x16x32_bf16 v[72:75], v[154:157], v[202:205], v[72:75]
	v_mfma_f32_16x16x32_bf16 v[60:63], v[146:149], v[218:221], v[60:63]
	v_mfma_f32_16x16x32_bf16 v[56:59], v[154:157], v[218:221], v[56:59]
	v_mfma_f32_16x16x32_bf16 v[44:47], v[146:149], v[226:229], v[44:47]
	v_mfma_f32_16x16x32_bf16 v[40:43], v[154:157], v[226:229], v[40:43]
	v_mfma_f32_16x16x32_bf16 v[28:31], v[146:149], v[234:237], v[28:31]
	v_mfma_f32_16x16x32_bf16 v[24:27], v[154:157], v[234:237], v[24:27]
	v_mfma_f32_16x16x32_bf16 v[12:15], v[146:149], v[242:245], v[12:15]
	v_mfma_f32_16x16x32_bf16 v[8:11], v[154:157], v[242:245], v[8:11]
	s_barrier
	ds_read_b128 v[128:131], v142
	ds_read_b128 v[146:149], v142 offset:1024
	ds_read_b128 v[150:153], v142 offset:2048
	ds_read_b128 v[154:157], v142 offset:3072
	s_mov_b32 m0, s47
	s_nop 0
	global_load_lds_dwordx4 v135, s[82:83]
	s_mov_b32 m0, s48
	s_nop 0
	global_load_lds_dwordx4 v137, s[82:83]
	s_mov_b32 m0, s37
	s_nop 0
	global_load_lds_dwordx4 v134, s[42:43]
	s_mov_b32 m0, s49
	s_nop 0
	global_load_lds_dwordx4 v136, s[42:43]
	s_add_u32 s16, s42, 0x20000
	s_addc_u32 s17, s43, 0
	s_mov_b32 m0, s50
	s_nop 0
	global_load_lds_dwordx4 v134, s[16:17]
	s_mov_b32 m0, s51
	s_nop 0
	global_load_lds_dwordx4 v136, s[16:17]
	s_waitcnt vmcnt(8)
	s_waitcnt lgkmcnt(0)
	s_barrier
	v_mfma_f32_16x16x32_bf16 v[116:119], v[128:131], v[166:169], v[116:119]
	v_mfma_f32_16x16x32_bf16 v[112:115], v[150:153], v[166:169], v[112:115]
	v_mfma_f32_16x16x32_bf16 v[100:103], v[128:131], v[182:185], v[100:103]
	v_mfma_f32_16x16x32_bf16 v[96:99], v[150:153], v[182:185], v[96:99]
	v_mfma_f32_16x16x32_bf16 v[84:87], v[128:131], v[190:193], v[84:87]
	v_mfma_f32_16x16x32_bf16 v[80:83], v[150:153], v[190:193], v[80:83]
	v_mfma_f32_16x16x32_bf16 v[68:71], v[128:131], v[198:201], v[68:71]
	v_mfma_f32_16x16x32_bf16 v[64:67], v[150:153], v[198:201], v[64:67]
	v_mfma_f32_16x16x32_bf16 v[52:55], v[128:131], v[214:217], v[52:55]
	v_mfma_f32_16x16x32_bf16 v[48:51], v[150:153], v[214:217], v[48:51]
	v_mfma_f32_16x16x32_bf16 v[36:39], v[128:131], v[222:225], v[36:39]
	v_mfma_f32_16x16x32_bf16 v[32:35], v[150:153], v[222:225], v[32:35]
	v_mfma_f32_16x16x32_bf16 v[20:23], v[128:131], v[230:233], v[20:23]
	v_mfma_f32_16x16x32_bf16 v[16:19], v[150:153], v[230:233], v[16:19]
	v_mfma_f32_16x16x32_bf16 v[4:7], v[128:131], v[238:241], v[4:7]
	v_mfma_f32_16x16x32_bf16 v[0:3], v[150:153], v[238:241], v[0:3]
	v_mfma_f32_16x16x32_bf16 v[116:119], v[146:149], v[178:181], v[116:119]
	v_mfma_f32_16x16x32_bf16 v[112:115], v[154:157], v[178:181], v[112:115]
	v_mfma_f32_16x16x32_bf16 v[100:103], v[146:149], v[186:189], v[100:103]
	v_mfma_f32_16x16x32_bf16 v[96:99], v[154:157], v[186:189], v[96:99]
	v_mfma_f32_16x16x32_bf16 v[84:87], v[146:149], v[194:197], v[84:87]
	v_mfma_f32_16x16x32_bf16 v[80:83], v[154:157], v[194:197], v[80:83]
	v_mfma_f32_16x16x32_bf16 v[68:71], v[146:149], v[202:205], v[68:71]
	v_mfma_f32_16x16x32_bf16 v[64:67], v[154:157], v[202:205], v[64:67]
	v_mfma_f32_16x16x32_bf16 v[52:55], v[146:149], v[218:221], v[52:55]
	v_mfma_f32_16x16x32_bf16 v[48:51], v[154:157], v[218:221], v[48:51]
	v_mfma_f32_16x16x32_bf16 v[36:39], v[146:149], v[226:229], v[36:39]
	v_mfma_f32_16x16x32_bf16 v[32:35], v[154:157], v[226:229], v[32:35]
	v_mfma_f32_16x16x32_bf16 v[20:23], v[146:149], v[234:237], v[20:23]
	v_mfma_f32_16x16x32_bf16 v[16:19], v[154:157], v[234:237], v[16:19]
	v_mfma_f32_16x16x32_bf16 v[4:7], v[146:149], v[242:245], v[4:7]
	v_mfma_f32_16x16x32_bf16 v[0:3], v[154:157], v[242:245], v[0:3]
	s_barrier
; #define PG8_STAGE(bufoff, gbase, voff) do { _Pragma("unroll") for (int _i = 0; _i < 2; ++_i) { \
;         const unsigned _m0 = ldsu + (unsigned)(bufoff) + ldsw + (unsigned)(_i * 8192); \
;         asm volatile("s_mov_b32 m0, %2\n\ts_nop 0\n\tglobal_load_lds_dwordx4 %0, %1" :: "v"((voff)[_i]), "s"((const char*)(gbase)), "s"(_m0) : "memory"); } } while (0)
; #define PG8_LDA(dst, b, h) do { _Pragma("unroll") for (int m = 0; m < 4; ++m) _Pragma("unroll") for (int k = 0; k < 2; ++k) dst[m][k] = *(const LAS bf16x8*)(lds + PG8_SA(b, h) + aoff + m * 2048 + k * 1024); } while (0)
; #define PG8_LDB(dst, b, h) do { _Pragma("unroll") for (int n = 0; n < 2; ++n) _Pragma("unroll") for (int k = 0; k < 2; ++k) dst[n][k] = *(const LAS bf16x8*)(lds + bbase[b][h] + n * 2048 + k * 1024); } while (0)
; #define PG8_WAIT_V(n) asm volatile("s_waitcnt vmcnt(" #n ")" ::: "memory")
; #define PG8_WAIT_L(n) asm volatile("s_waitcnt lgkmcnt(" #n ")" ::: "memory")
; #define PG8_BAR __builtin_amdgcn_s_barrier()
; #define PG8_SCHED __builtin_amdgcn_sched_barrier(0)
; template <class Epi>
; __device__ __forceinline__ void gemm_phase(LAS unsigned char* lds, const Gemm g, const StaticOrder& S, const Epi& E) {
;     ...
;             PG8_LDB(B0, 1, 0); PG8_SCHED; PG8_LDA(At, 1, 0); PG8_LDA(At2, 1, 1); PG8_STAGE(PG8_SB(0, 1), b2 + hstepB, voffB);
;             PG8_WAIT_V(8); PG8_WAIT_L(0); PG8_BAR; PG8_MMA2B(0, At, At2, B0); PG8_BAR; PG8_SCHED;
;             PG8_LDB(B0, 1, 1); PG8_STAGE(PG8_SB(1, 0), b3, voffB); PG8_STAGE(PG8_SA(1, 0), a3, voffA); PG8_STAGE(PG8_SA(1, 1), a3 + hstepA, voffA);
;             PG8_WAIT_V(8); PG8_WAIT_L(0); PG8_BAR; PG8_MMA2B(1, At, At2, B0); PG8_BAR; PG8_SCHED;
	ds_read_b128 v[128:131], v143
	ds_read_b128 v[146:149], v143 offset:1024
	ds_read_b128 v[150:153], v143 offset:2048
	ds_read_b128 v[154:157], v143 offset:3072
	ds_read_b128 v[166:169], v141 offset:32768
	ds_read_b128 v[178:181], v141 offset:33792
	ds_read_b128 v[182:185], v141 offset:34816
	ds_read_b128 v[186:189], v141 offset:35840
	ds_read_b128 v[190:193], v141 offset:36864
	ds_read_b128 v[194:197], v141 offset:37888
	ds_read_b128 v[198:201], v141 offset:38912
	ds_read_b128 v[202:205], v141 offset:39936
	ds_read_b128 v[214:217], v141 offset:49152
	ds_read_b128 v[218:221], v141 offset:50176
	ds_read_b128 v[222:225], v141 offset:51200
	ds_read_b128 v[226:229], v141 offset:52224
	ds_read_b128 v[230:233], v141 offset:53248
	ds_read_b128 v[234:237], v141 offset:54272
	ds_read_b128 v[238:241], v141 offset:55296
	ds_read_b128 v[242:245], v141 offset:56320
	s_add_u32 s16, s82, 0x20000
	s_addc_u32 s17, s83, 0
	s_mov_b32 m0, s52
	s_nop 0
	global_load_lds_dwordx4 v135, s[16:17]
	s_mov_b32 m0, s53
	s_nop 0
	global_load_lds_dwordx4 v137, s[16:17]
	s_waitcnt vmcnt(8)
	s_waitcnt lgkmcnt(0)
	s_barrier
	v_mfma_f32_16x16x32_bf16 v[124:127], v[128:131], v[166:169], v[124:127]
	v_mfma_f32_16x16x32_bf16 v[120:123], v[150:153], v[166:169], v[120:123]
	v_mfma_f32_16x16x32_bf16 v[108:111], v[128:131], v[182:185], v[108:111]
	v_mfma_f32_16x16x32_bf16 v[104:107], v[150:153], v[182:185], v[104:107]
	v_mfma_f32_16x16x32_bf16 v[92:95], v[128:131], v[190:193], v[92:95]
	v_mfma_f32_16x16x32_bf16 v[88:91], v[150:153], v[190:193], v[88:91]
	v_mfma_f32_16x16x32_bf16 v[76:79], v[128:131], v[198:201], v[76:79]
	v_mfma_f32_16x16x32_bf16 v[72:75], v[150:153], v[198:201], v[72:75]
	v_mfma_f32_16x16x32_bf16 v[60:63], v[128:131], v[214:217], v[60:63]
	v_mfma_f32_16x16x32_bf16 v[56:59], v[150:153], v[214:217], v[56:59]
	v_mfma_f32_16x16x32_bf16 v[44:47], v[128:131], v[222:225], v[44:47]
	v_mfma_f32_16x16x32_bf16 v[40:43], v[150:153], v[222:225], v[40:43]
	v_mfma_f32_16x16x32_bf16 v[28:31], v[128:131], v[230:233], v[28:31]
	v_mfma_f32_16x16x32_bf16 v[24:27], v[150:153], v[230:233], v[24:27]
	v_mfma_f32_16x16x32_bf16 v[12:15], v[128:131], v[238:241], v[12:15]
	v_mfma_f32_16x16x32_bf16 v[8:11], v[150:153], v[238:241], v[8:11]
	v_mfma_f32_16x16x32_bf16 v[124:127], v[146:149], v[178:181], v[124:127]
	v_mfma_f32_16x16x32_bf16 v[120:123], v[154:157], v[178:181], v[120:123]
	v_mfma_f32_16x16x32_bf16 v[108:111], v[146:149], v[186:189], v[108:111]
	v_mfma_f32_16x16x32_bf16 v[104:107], v[154:157], v[186:189], v[104:107]
	v_mfma_f32_16x16x32_bf16 v[92:95], v[146:149], v[194:197], v[92:95]
	v_mfma_f32_16x16x32_bf16 v[88:91], v[154:157], v[194:197], v[88:91]
	v_mfma_f32_16x16x32_bf16 v[76:79], v[146:149], v[202:205], v[76:79]
	v_mfma_f32_16x16x32_bf16 v[72:75], v[154:157], v[202:205], v[72:75]
	v_mfma_f32_16x16x32_bf16 v[60:63], v[146:149], v[218:221], v[60:63]
	v_mfma_f32_16x16x32_bf16 v[56:59], v[154:157], v[218:221], v[56:59]
	v_mfma_f32_16x16x32_bf16 v[44:47], v[146:149], v[226:229], v[44:47]
	v_mfma_f32_16x16x32_bf16 v[40:43], v[154:157], v[226:229], v[40:43]
	v_mfma_f32_16x16x32_bf16 v[28:31], v[146:149], v[234:237], v[28:31]
	v_mfma_f32_16x16x32_bf16 v[24:27], v[154:157], v[234:237], v[24:27]
	v_mfma_f32_16x16x32_bf16 v[12:15], v[146:149], v[242:245], v[12:15]
	v_mfma_f32_16x16x32_bf16 v[8:11], v[154:157], v[242:245], v[8:11]
	s_barrier
	s_add_u32 s16, s82, 0x80
	ds_read_b128 v[128:131], v144
	ds_read_b128 v[146:149], v144 offset:1024
	ds_read_b128 v[150:153], v144 offset:2048
	ds_read_b128 v[154:157], v144 offset:3072
	s_addc_u32 s17, s83, 0
	s_mov_b32 m0, s54
	s_nop 0
	global_load_lds_dwordx4 v135, s[16:17]
	s_mov_b32 m0, s55
	s_nop 0
	global_load_lds_dwordx4 v137, s[16:17]
	s_mov_b32 m0, s56
	s_nop 0
	global_load_lds_dwordx4 v134, s[80:81]
	s_mov_b32 m0, s57
	s_nop 0
	global_load_lds_dwordx4 v136, s[80:81]
	s_add_u32 s16, s42, 0x20080
	s_addc_u32 s17, s43, 0
	s_mov_b32 m0, s58
	s_nop 0
	global_load_lds_dwordx4 v134, s[16:17]
	s_mov_b32 m0, s59
	s_nop 0
	global_load_lds_dwordx4 v136, s[16:17]
	s_waitcnt vmcnt(8)
	s_waitcnt lgkmcnt(0)
	s_barrier
	v_mfma_f32_16x16x32_bf16 v[116:119], v[128:131], v[166:169], v[116:119]
	v_mfma_f32_16x16x32_bf16 v[112:115], v[150:153], v[166:169], v[112:115]
	v_mfma_f32_16x16x32_bf16 v[100:103], v[128:131], v[182:185], v[100:103]
	v_mfma_f32_16x16x32_bf16 v[96:99], v[150:153], v[182:185], v[96:99]
	v_mfma_f32_16x16x32_bf16 v[84:87], v[128:131], v[190:193], v[84:87]
	v_mfma_f32_16x16x32_bf16 v[80:83], v[150:153], v[190:193], v[80:83]
	v_mfma_f32_16x16x32_bf16 v[68:71], v[128:131], v[198:201], v[68:71]
	v_mfma_f32_16x16x32_bf16 v[64:67], v[150:153], v[198:201], v[64:67]
	v_mfma_f32_16x16x32_bf16 v[52:55], v[128:131], v[214:217], v[52:55]
	v_mfma_f32_16x16x32_bf16 v[48:51], v[150:153], v[214:217], v[48:51]
	v_mfma_f32_16x16x32_bf16 v[36:39], v[128:131], v[222:225], v[36:39]
	v_mfma_f32_16x16x32_bf16 v[32:35], v[150:153], v[222:225], v[32:35]
	v_mfma_f32_16x16x32_bf16 v[20:23], v[128:131], v[230:233], v[20:23]
	v_mfma_f32_16x16x32_bf16 v[16:19], v[150:153], v[230:233], v[16:19]
	v_mfma_f32_16x16x32_bf16 v[4:7], v[128:131], v[238:241], v[4:7]
	v_mfma_f32_16x16x32_bf16 v[0:3], v[150:153], v[238:241], v[0:3]
	v_mfma_f32_16x16x32_bf16 v[116:119], v[146:149], v[178:181], v[116:119]
	v_mfma_f32_16x16x32_bf16 v[112:115], v[154:157], v[178:181], v[112:115]
	v_mfma_f32_16x16x32_bf16 v[100:103], v[146:149], v[186:189], v[100:103]
	v_mfma_f32_16x16x32_bf16 v[96:99], v[154:157], v[186:189], v[96:99]
	v_mfma_f32_16x16x32_bf16 v[84:87], v[146:149], v[194:197], v[84:87]
	v_mfma_f32_16x16x32_bf16 v[80:83], v[154:157], v[194:197], v[80:83]
	v_mfma_f32_16x16x32_bf16 v[68:71], v[146:149], v[202:205], v[68:71]
	v_mfma_f32_16x16x32_bf16 v[64:67], v[154:157], v[202:205], v[64:67]
	v_mfma_f32_16x16x32_bf16 v[52:55], v[146:149], v[218:221], v[52:55]
	v_mfma_f32_16x16x32_bf16 v[48:51], v[154:157], v[218:221], v[48:51]
	v_mfma_f32_16x16x32_bf16 v[36:39], v[146:149], v[226:229], v[36:39]
	v_mfma_f32_16x16x32_bf16 v[32:35], v[154:157], v[226:229], v[32:35]
	v_mfma_f32_16x16x32_bf16 v[20:23], v[146:149], v[234:237], v[20:23]
	v_mfma_f32_16x16x32_bf16 v[16:19], v[154:157], v[234:237], v[16:19]
	v_mfma_f32_16x16x32_bf16 v[4:7], v[146:149], v[242:245], v[4:7]
	v_mfma_f32_16x16x32_bf16 v[0:3], v[154:157], v[242:245], v[0:3]
	s_barrier
	s_add_i32 s68, s68, 2
	s_add_u32 s67, s67, 0x100
	s_addc_u32 s84, s84, 0
	s_cmp_gt_u32 s68, 5
	s_mov_b64 s[16:17], s[38:39]
	s_cbranch_scc0 .LBB0_870
	s_and_b64 vcc, exec, s[4:5]
	s_cbranch_vccz .LBB0_873
	s_barrier

; #define PG8_STAGE(bufoff, gbase, voff) do { _Pragma("unroll") for (int _i = 0; _i < 2; ++_i) { \
;         const unsigned _m0 = ldsu + (unsigned)(bufoff) + ldsw + (unsigned)(_i * 8192); \
;         asm volatile("s_mov_b32 m0, %2\n\ts_nop 0\n\tglobal_load_lds_dwordx4 %0, %1" :: "v"((voff)[_i]), "s"((const char*)(gbase)), "s"(_m0) : "memory"); } } while (0)
; #define PG8_LDA(dst, b, h) do { _Pragma("unroll") for (int m = 0; m < 4; ++m) _Pragma("unroll") for (int k = 0; k < 2; ++k) dst[m][k] = *(const LAS bf16x8*)(lds + PG8_SA(b, h) + aoff + m * 2048 + k * 1024); } while (0)
; #define PG8_LDB(dst, b, h) do { _Pragma("unroll") for (int n = 0; n < 2; ++n) _Pragma("unroll") for (int k = 0; k < 2; ++k) dst[n][k] = *(const LAS bf16x8*)(lds + bbase[b][h] + n * 2048 + k * 1024); } while (0)
; #define PG8_WAIT_V(n) asm volatile("s_waitcnt vmcnt(" #n ")" ::: "memory")
; #define PG8_WAIT_L(n) asm volatile("s_waitcnt lgkmcnt(" #n ")" ::: "memory")
; #define PG8_BAR __builtin_amdgcn_s_barrier()
; #define PG8_SCHED __builtin_amdgcn_sched_barrier(0)
; template <class Epi>
; __device__ __forceinline__ void gemm_phase(LAS unsigned char* lds, const Gemm g, const StaticOrder& S, const Epi& E) {
;     ...
;         for (int t = 0; t < nt; t += 2) {
;             const bool last = (t == nt - 2);
;             const char* a2 = last ? nA : cA + (size_t)(t + 2) * kstep; const char* b2 = last ? nB : cB + (size_t)(t + 2) * kstep;
;             const char* a3 = a2 + kstep; const char* b3 = b2 + kstep;
;             const char* b1 = cB + (size_t)(t + 1) * kstep;
;             PG8_LDB(B0, 0, 0); PG8_SCHED; PG8_LDA(At, 0, 0); PG8_LDA(At2, 0, 1); PG8_STAGE(PG8_SB(1, 1), b1 + hstepB, voffB);
;             PG8_WAIT_V(8); PG8_WAIT_L(0); PG8_BAR; PG8_MMA2B(0, At, At2, B0); PG8_BAR; PG8_SCHED;
;             PG8_LDB(B0, 0, 1); PG8_STAGE(PG8_SB(0, 0), b2, voffB); PG8_STAGE(PG8_SA(0, 0), a2, voffA); PG8_STAGE(PG8_SA(0, 1), a2 + hstepA, voffA);
;             PG8_WAIT_V(8); PG8_WAIT_L(0); PG8_BAR; PG8_MMA2B(1, At, At2, B0); PG8_BAR; PG8_SCHED;
.LBB0_943:
	ds_read_b128 v[128:131], v138
	ds_read_b128 v[144:147], v138 offset:1024
	ds_read_b128 v[148:151], v138 offset:2048
	ds_read_b128 v[152:155], v138 offset:3072
	s_cmp_eq_u32 s68, 12
	s_cselect_b32 s38, s66, s84
	s_cselect_b32 s39, s13, s85
	s_cselect_b32 s82, s67, s86
	s_cselect_b32 s83, s5, s87
	s_add_u32 s42, s38, 0x80
	s_addc_u32 s43, s39, 0
	s_add_u32 s80, s82, 0x80
	s_addc_u32 s81, s83, 0
	ds_read_b128 v[156:159], v139
	ds_read_b128 v[166:169], v139 offset:1024
	ds_read_b128 v[178:181], v139 offset:2048
	ds_read_b128 v[182:185], v139 offset:3072
	ds_read_b128 v[186:189], v139 offset:4096
	ds_read_b128 v[190:193], v139 offset:5120
	ds_read_b128 v[194:197], v139 offset:6144
	ds_read_b128 v[198:201], v139 offset:7168
	ds_read_b128 v[202:205], v139 offset:16384
	ds_read_b128 v[214:217], v139 offset:17408
	ds_read_b128 v[218:221], v139 offset:18432
	ds_read_b128 v[222:225], v139 offset:19456
	ds_read_b128 v[226:229], v139 offset:20480
	ds_read_b128 v[230:233], v139 offset:21504
	ds_read_b128 v[234:237], v139 offset:22528
	ds_read_b128 v[238:241], v139 offset:23552
	s_mov_b32 m0, s61
	s_nop 0
	global_load_lds_dwordx4 v133, s[6:7]
	s_mov_b32 m0, s63
	s_nop 0
	global_load_lds_dwordx4 v135, s[6:7]
	s_waitcnt vmcnt(8)
	s_waitcnt lgkmcnt(0)
	s_barrier
	v_mfma_f32_16x16x32_bf16 v[124:127], v[128:131], v[156:159], v[124:127]
	v_mfma_f32_16x16x32_bf16 v[120:123], v[148:151], v[156:159], v[120:123]
	v_mfma_f32_16x16x32_bf16 v[108:111], v[128:131], v[178:181], v[108:111]
	v_mfma_f32_16x16x32_bf16 v[104:107], v[148:151], v[178:181], v[104:107]
	v_mfma_f32_16x16x32_bf16 v[92:95], v[128:131], v[186:189], v[92:95]
	v_mfma_f32_16x16x32_bf16 v[88:91], v[148:151], v[186:189], v[88:91]
	v_mfma_f32_16x16x32_bf16 v[76:79], v[128:131], v[194:197], v[76:79]
	v_mfma_f32_16x16x32_bf16 v[72:75], v[148:151], v[194:197], v[72:75]
	v_mfma_f32_16x16x32_bf16 v[60:63], v[128:131], v[202:205], v[60:63]
	v_mfma_f32_16x16x32_bf16 v[56:59], v[148:151], v[202:205], v[56:59]
	v_mfma_f32_16x16x32_bf16 v[44:47], v[128:131], v[218:221], v[44:47]
	v_mfma_f32_16x16x32_bf16 v[40:43], v[148:151], v[218:221], v[40:43]
	v_mfma_f32_16x16x32_bf16 v[28:31], v[128:131], v[226:229], v[28:31]
	v_mfma_f32_16x16x32_bf16 v[24:27], v[148:151], v[226:229], v[24:27]
	v_mfma_f32_16x16x32_bf16 v[12:15], v[128:131], v[234:237], v[12:15]
	v_mfma_f32_16x16x32_bf16 v[8:11], v[148:151], v[234:237], v[8:11]
	v_mfma_f32_16x16x32_bf16 v[124:127], v[144:147], v[166:169], v[124:127]
	v_mfma_f32_16x16x32_bf16 v[120:123], v[152:155], v[166:169], v[120:123]
	v_mfma_f32_16x16x32_bf16 v[108:111], v[144:147], v[182:185], v[108:111]
	v_mfma_f32_16x16x32_bf16 v[104:107], v[152:155], v[182:185], v[104:107]
	v_mfma_f32_16x16x32_bf16 v[92:95], v[144:147], v[190:193], v[92:95]
	v_mfma_f32_16x16x32_bf16 v[88:91], v[152:155], v[190:193], v[88:91]
	v_mfma_f32_16x16x32_bf16 v[76:79], v[144:147], v[198:201], v[76:79]
	v_mfma_f32_16x16x32_bf16 v[72:75], v[152:155], v[198:201], v[72:75]
	v_mfma_f32_16x16x32_bf16 v[60:63], v[144:147], v[214:217], v[60:63]
	v_mfma_f32_16x16x32_bf16 v[56:59], v[152:155], v[214:217], v[56:59]
	v_mfma_f32_16x16x32_bf16 v[44:47], v[144:147], v[222:225], v[44:47]
	v_mfma_f32_16x16x32_bf16 v[40:43], v[152:155], v[222:225], v[40:43]
	v_mfma_f32_16x16x32_bf16 v[28:31], v[144:147], v[230:233], v[28:31]
	v_mfma_f32_16x16x32_bf16 v[24:27], v[152:155], v[230:233], v[24:27]
	v_mfma_f32_16x16x32_bf16 v[12:15], v[144:147], v[238:241], v[12:15]
	v_mfma_f32_16x16x32_bf16 v[8:11], v[152:155], v[238:241], v[8:11]
	s_barrier
	ds_read_b128 v[128:131], v140
	ds_read_b128 v[144:147], v140 offset:1024
	ds_read_b128 v[148:151], v140 offset:2048
	ds_read_b128 v[152:155], v140 offset:3072
	s_mov_b32 m0, s48
	s_nop 0
	global_load_lds_dwordx4 v133, s[82:83]
	s_mov_b32 m0, s49
	s_nop 0
	global_load_lds_dwordx4 v135, s[82:83]
	s_mov_b32 m0, s47
	s_nop 0
	global_load_lds_dwordx4 v132, s[38:39]
	s_mov_b32 m0, s50
	s_nop 0
	global_load_lds_dwordx4 v134, s[38:39]
	s_add_u32 s88, s38, 0x40000
	s_addc_u32 s89, s39, 0
	s_mov_b32 m0, s51
	s_nop 0
	global_load_lds_dwordx4 v132, s[88:89]
	s_mov_b32 m0, s52
	s_nop 0
	global_load_lds_dwordx4 v134, s[88:89]
	s_waitcnt vmcnt(8)
	s_waitcnt lgkmcnt(0)
	s_barrier
	v_mfma_f32_16x16x32_bf16 v[116:119], v[128:131], v[156:159], v[116:119]
	v_mfma_f32_16x16x32_bf16 v[112:115], v[148:151], v[156:159], v[112:115]
	v_mfma_f32_16x16x32_bf16 v[100:103], v[128:131], v[178:181], v[100:103]
	v_mfma_f32_16x16x32_bf16 v[96:99], v[148:151], v[178:181], v[96:99]
	v_mfma_f32_16x16x32_bf16 v[84:87], v[128:131], v[186:189], v[84:87]
	v_mfma_f32_16x16x32_bf16 v[80:83], v[148:151], v[186:189], v[80:83]
	v_mfma_f32_16x16x32_bf16 v[68:71], v[128:131], v[194:197], v[68:71]
	v_mfma_f32_16x16x32_bf16 v[64:67], v[148:151], v[194:197], v[64:67]
	v_mfma_f32_16x16x32_bf16 v[52:55], v[128:131], v[202:205], v[52:55]
	v_mfma_f32_16x16x32_bf16 v[48:51], v[148:151], v[202:205], v[48:51]
	v_mfma_f32_16x16x32_bf16 v[36:39], v[128:131], v[218:221], v[36:39]
	v_mfma_f32_16x16x32_bf16 v[32:35], v[148:151], v[218:221], v[32:35]
	v_mfma_f32_16x16x32_bf16 v[20:23], v[128:131], v[226:229], v[20:23]
	v_mfma_f32_16x16x32_bf16 v[16:19], v[148:151], v[226:229], v[16:19]
	v_mfma_f32_16x16x32_bf16 v[4:7], v[128:131], v[234:237], v[4:7]
	v_mfma_f32_16x16x32_bf16 v[0:3], v[148:151], v[234:237], v[0:3]
	v_mfma_f32_16x16x32_bf16 v[116:119], v[144:147], v[166:169], v[116:119]
	v_mfma_f32_16x16x32_bf16 v[112:115], v[152:155], v[166:169], v[112:115]
	v_mfma_f32_16x16x32_bf16 v[100:103], v[144:147], v[182:185], v[100:103]
	v_mfma_f32_16x16x32_bf16 v[96:99], v[152:155], v[182:185], v[96:99]
	v_mfma_f32_16x16x32_bf16 v[84:87], v[144:147], v[190:193], v[84:87]
	v_mfma_f32_16x16x32_bf16 v[80:83], v[152:155], v[190:193], v[80:83]
	v_mfma_f32_16x16x32_bf16 v[68:71], v[144:147], v[198:201], v[68:71]
	v_mfma_f32_16x16x32_bf16 v[64:67], v[152:155], v[198:201], v[64:67]
	v_mfma_f32_16x16x32_bf16 v[52:55], v[144:147], v[214:217], v[52:55]
	v_mfma_f32_16x16x32_bf16 v[48:51], v[152:155], v[214:217], v[48:51]
	v_mfma_f32_16x16x32_bf16 v[36:39], v[144:147], v[222:225], v[36:39]
	v_mfma_f32_16x16x32_bf16 v[32:35], v[152:155], v[222:225], v[32:35]
	v_mfma_f32_16x16x32_bf16 v[20:23], v[144:147], v[230:233], v[20:23]
	v_mfma_f32_16x16x32_bf16 v[16:19], v[152:155], v[230:233], v[16:19]
	v_mfma_f32_16x16x32_bf16 v[4:7], v[144:147], v[238:241], v[4:7]
	v_mfma_f32_16x16x32_bf16 v[0:3], v[152:155], v[238:241], v[0:3]
	s_barrier
; #define PG8_STAGE(bufoff, gbase, voff) do { _Pragma("unroll") for (int _i = 0; _i < 2; ++_i) { \
;         const unsigned _m0 = ldsu + (unsigned)(bufoff) + ldsw + (unsigned)(_i * 8192); \
;         asm volatile("s_mov_b32 m0, %2\n\ts_nop 0\n\tglobal_load_lds_dwordx4 %0, %1" :: "v"((voff)[_i]), "s"((const char*)(gbase)), "s"(_m0) : "memory"); } } while (0)
; #define PG8_LDA(dst, b, h) do { _Pragma("unroll") for (int m = 0; m < 4; ++m) _Pragma("unroll") for (int k = 0; k < 2; ++k) dst[m][k] = *(const LAS bf16x8*)(lds + PG8_SA(b, h) + aoff + m * 2048 + k * 1024); } while (0)
; #define PG8_LDB(dst, b, h) do { _Pragma("unroll") for (int n = 0; n < 2; ++n) _Pragma("unroll") for (int k = 0; k < 2; ++k) dst[n][k] = *(const LAS bf16x8*)(lds + bbase[b][h] + n * 2048 + k * 1024); } while (0)
; #define PG8_WAIT_V(n) asm volatile("s_waitcnt vmcnt(" #n ")" ::: "memory")
; #define PG8_WAIT_L(n) asm volatile("s_waitcnt lgkmcnt(" #n ")" ::: "memory")
; #define PG8_BAR __builtin_amdgcn_s_barrier()
; #define PG8_SCHED __builtin_amdgcn_sched_barrier(0)
; template <class Epi>
; __device__ __forceinline__ void gemm_phase(LAS unsigned char* lds, const Gemm g, const StaticOrder& S, const Epi& E) {
;     ...
;             PG8_LDB(B0, 1, 0); PG8_SCHED; PG8_LDA(At, 1, 0); PG8_LDA(At2, 1, 1); PG8_STAGE(PG8_SB(0, 1), b2 + hstepB, voffB);
;             PG8_WAIT_V(8); PG8_WAIT_L(0); PG8_BAR; PG8_MMA2B(0, At, At2, B0); PG8_BAR; PG8_SCHED;
;             PG8_LDB(B0, 1, 1); PG8_STAGE(PG8_SB(1, 0), b3, voffB); PG8_STAGE(PG8_SA(1, 0), a3, voffA); PG8_STAGE(PG8_SA(1, 1), a3 + hstepA, voffA);
;             PG8_WAIT_V(8); PG8_WAIT_L(0); PG8_BAR; PG8_MMA2B(1, At, At2, B0); PG8_BAR; PG8_SCHED;
	ds_read_b128 v[128:131], v141
	ds_read_b128 v[144:147], v141 offset:1024
	ds_read_b128 v[148:151], v141 offset:2048
	ds_read_b128 v[152:155], v141 offset:3072
	ds_read_b128 v[156:159], v139 offset:32768
	ds_read_b128 v[166:169], v139 offset:33792
	ds_read_b128 v[178:181], v139 offset:34816
	ds_read_b128 v[182:185], v139 offset:35840
	ds_read_b128 v[186:189], v139 offset:36864
	ds_read_b128 v[190:193], v139 offset:37888
	ds_read_b128 v[194:197], v139 offset:38912
	ds_read_b128 v[198:201], v139 offset:39936
	ds_read_b128 v[202:205], v139 offset:49152
	ds_read_b128 v[214:217], v139 offset:50176
	ds_read_b128 v[218:221], v139 offset:51200
	ds_read_b128 v[222:225], v139 offset:52224
	ds_read_b128 v[226:229], v139 offset:53248
	ds_read_b128 v[230:233], v139 offset:54272
	ds_read_b128 v[234:237], v139 offset:55296
	ds_read_b128 v[238:241], v139 offset:56320
	s_add_u32 s82, s82, 0x40000
	s_addc_u32 s83, s83, 0
	s_mov_b32 m0, s53
	s_nop 0
	global_load_lds_dwordx4 v133, s[82:83]
	s_mov_b32 m0, s54
	s_nop 0
	global_load_lds_dwordx4 v135, s[82:83]
	s_waitcnt vmcnt(8)
	s_waitcnt lgkmcnt(0)
	s_barrier
	v_mfma_f32_16x16x32_bf16 v[124:127], v[128:131], v[156:159], v[124:127]
	v_mfma_f32_16x16x32_bf16 v[120:123], v[148:151], v[156:159], v[120:123]
	v_mfma_f32_16x16x32_bf16 v[108:111], v[128:131], v[178:181], v[108:111]
	v_mfma_f32_16x16x32_bf16 v[104:107], v[148:151], v[178:181], v[104:107]
	v_mfma_f32_16x16x32_bf16 v[92:95], v[128:131], v[186:189], v[92:95]
	v_mfma_f32_16x16x32_bf16 v[88:91], v[148:151], v[186:189], v[88:91]
	v_mfma_f32_16x16x32_bf16 v[76:79], v[128:131], v[194:197], v[76:79]
	v_mfma_f32_16x16x32_bf16 v[72:75], v[148:151], v[194:197], v[72:75]
	v_mfma_f32_16x16x32_bf16 v[60:63], v[128:131], v[202:205], v[60:63]
	v_mfma_f32_16x16x32_bf16 v[56:59], v[148:151], v[202:205], v[56:59]
	v_mfma_f32_16x16x32_bf16 v[44:47], v[128:131], v[218:221], v[44:47]
	v_mfma_f32_16x16x32_bf16 v[40:43], v[148:151], v[218:221], v[40:43]
	v_mfma_f32_16x16x32_bf16 v[28:31], v[128:131], v[226:229], v[28:31]
	v_mfma_f32_16x16x32_bf16 v[24:27], v[148:151], v[226:229], v[24:27]
	v_mfma_f32_16x16x32_bf16 v[12:15], v[128:131], v[234:237], v[12:15]
	v_mfma_f32_16x16x32_bf16 v[8:11], v[148:151], v[234:237], v[8:11]
	v_mfma_f32_16x16x32_bf16 v[124:127], v[144:147], v[166:169], v[124:127]
	v_mfma_f32_16x16x32_bf16 v[120:123], v[152:155], v[166:169], v[120:123]
	v_mfma_f32_16x16x32_bf16 v[108:111], v[144:147], v[182:185], v[108:111]
	v_mfma_f32_16x16x32_bf16 v[104:107], v[152:155], v[182:185], v[104:107]
	v_mfma_f32_16x16x32_bf16 v[92:95], v[144:147], v[190:193], v[92:95]
	v_mfma_f32_16x16x32_bf16 v[88:91], v[152:155], v[190:193], v[88:91]
	v_mfma_f32_16x16x32_bf16 v[76:79], v[144:147], v[198:201], v[76:79]
	v_mfma_f32_16x16x32_bf16 v[72:75], v[152:155], v[198:201], v[72:75]
	v_mfma_f32_16x16x32_bf16 v[60:63], v[144:147], v[214:217], v[60:63]
	v_mfma_f32_16x16x32_bf16 v[56:59], v[152:155], v[214:217], v[56:59]
	v_mfma_f32_16x16x32_bf16 v[44:47], v[144:147], v[222:225], v[44:47]
	v_mfma_f32_16x16x32_bf16 v[40:43], v[152:155], v[222:225], v[40:43]
	v_mfma_f32_16x16x32_bf16 v[28:31], v[144:147], v[230:233], v[28:31]
	v_mfma_f32_16x16x32_bf16 v[24:27], v[152:155], v[230:233], v[24:27]
	v_mfma_f32_16x16x32_bf16 v[12:15], v[144:147], v[238:241], v[12:15]
	v_mfma_f32_16x16x32_bf16 v[8:11], v[152:155], v[238:241], v[8:11]
	s_barrier
	ds_read_b128 v[128:131], v142
	ds_read_b128 v[144:147], v142 offset:1024
	ds_read_b128 v[148:151], v142 offset:2048
	ds_read_b128 v[152:155], v142 offset:3072
	s_mov_b32 m0, s55
	s_nop 0
	global_load_lds_dwordx4 v133, s[80:81]
	s_mov_b32 m0, s56
	s_nop 0
	global_load_lds_dwordx4 v135, s[80:81]
	s_mov_b32 m0, s57
	s_nop 0
	global_load_lds_dwordx4 v132, s[42:43]
	s_mov_b32 m0, s58
	s_nop 0
	global_load_lds_dwordx4 v134, s[42:43]
	s_add_u32 s38, s38, 0x40080
	s_addc_u32 s39, s39, 0
	s_mov_b32 m0, s59
	s_nop 0
	global_load_lds_dwordx4 v132, s[38:39]
	s_mov_b32 m0, s60
	s_nop 0
	global_load_lds_dwordx4 v134, s[38:39]
	s_waitcnt vmcnt(8)
	s_waitcnt lgkmcnt(0)
	s_barrier
	v_mfma_f32_16x16x32_bf16 v[116:119], v[128:131], v[156:159], v[116:119]
	v_mfma_f32_16x16x32_bf16 v[112:115], v[148:151], v[156:159], v[112:115]
	v_mfma_f32_16x16x32_bf16 v[100:103], v[128:131], v[178:181], v[100:103]
	v_mfma_f32_16x16x32_bf16 v[96:99], v[148:151], v[178:181], v[96:99]
	v_mfma_f32_16x16x32_bf16 v[84:87], v[128:131], v[186:189], v[84:87]
	v_mfma_f32_16x16x32_bf16 v[80:83], v[148:151], v[186:189], v[80:83]
	v_mfma_f32_16x16x32_bf16 v[68:71], v[128:131], v[194:197], v[68:71]
	v_mfma_f32_16x16x32_bf16 v[64:67], v[148:151], v[194:197], v[64:67]
	v_mfma_f32_16x16x32_bf16 v[52:55], v[128:131], v[202:205], v[52:55]
	v_mfma_f32_16x16x32_bf16 v[48:51], v[148:151], v[202:205], v[48:51]
	v_mfma_f32_16x16x32_bf16 v[36:39], v[128:131], v[218:221], v[36:39]
	v_mfma_f32_16x16x32_bf16 v[32:35], v[148:151], v[218:221], v[32:35]
	v_mfma_f32_16x16x32_bf16 v[20:23], v[128:131], v[226:229], v[20:23]
	v_mfma_f32_16x16x32_bf16 v[16:19], v[148:151], v[226:229], v[16:19]
	v_mfma_f32_16x16x32_bf16 v[4:7], v[128:131], v[234:237], v[4:7]
	v_mfma_f32_16x16x32_bf16 v[0:3], v[148:151], v[234:237], v[0:3]
	v_mfma_f32_16x16x32_bf16 v[116:119], v[144:147], v[166:169], v[116:119]
	v_mfma_f32_16x16x32_bf16 v[112:115], v[152:155], v[166:169], v[112:115]
	v_mfma_f32_16x16x32_bf16 v[100:103], v[144:147], v[182:185], v[100:103]
	v_mfma_f32_16x16x32_bf16 v[96:99], v[152:155], v[182:185], v[96:99]
	v_mfma_f32_16x16x32_bf16 v[84:87], v[144:147], v[190:193], v[84:87]
	v_mfma_f32_16x16x32_bf16 v[80:83], v[152:155], v[190:193], v[80:83]
	v_mfma_f32_16x16x32_bf16 v[68:71], v[144:147], v[198:201], v[68:71]
	v_mfma_f32_16x16x32_bf16 v[64:67], v[152:155], v[198:201], v[64:67]
	v_mfma_f32_16x16x32_bf16 v[52:55], v[144:147], v[214:217], v[52:55]
	v_mfma_f32_16x16x32_bf16 v[48:51], v[152:155], v[214:217], v[48:51]
	v_mfma_f32_16x16x32_bf16 v[36:39], v[144:147], v[222:225], v[36:39]
	v_mfma_f32_16x16x32_bf16 v[32:35], v[152:155], v[222:225], v[32:35]
	v_mfma_f32_16x16x32_bf16 v[20:23], v[144:147], v[230:233], v[20:23]
	v_mfma_f32_16x16x32_bf16 v[16:19], v[152:155], v[230:233], v[16:19]
	v_mfma_f32_16x16x32_bf16 v[4:7], v[144:147], v[238:241], v[4:7]
	v_mfma_f32_16x16x32_bf16 v[0:3], v[152:155], v[238:241], v[0:3]
	s_barrier
	s_add_i32 s68, s68, 2
	s_add_u32 s6, s6, 0x100
	s_addc_u32 s7, s7, 0
	s_add_u32 s84, s84, 0x100
	s_addc_u32 s85, s85, 0
	s_add_u32 s86, s86, 0x100
	s_addc_u32 s87, s87, 0
	s_cmp_gt_u32 s68, 13
	s_cbranch_scc0 .LBB0_943
	s_and_b64 vcc, exec, s[2:3]
	s_cbranch_vccz .LBB0_946
	s_barrier

; #define PG8_STAGE(bufoff, gbase, voff) do { _Pragma("unroll") for (int _i = 0; _i < 2; ++_i) { \
;         const unsigned _m0 = ldsu + (unsigned)(bufoff) + ldsw + (unsigned)(_i * 8192); \
;         asm volatile("s_mov_b32 m0, %2\n\ts_nop 0\n\tglobal_load_lds_dwordx4 %0, %1" :: "v"((voff)[_i]), "s"((const char*)(gbase)), "s"(_m0) : "memory"); } } while (0)
; #define PG8_LDA(dst, b, h) do { _Pragma("unroll") for (int m = 0; m < 4; ++m) _Pragma("unroll") for (int k = 0; k < 2; ++k) dst[m][k] = *(const LAS bf16x8*)(lds + PG8_SA(b, h) + aoff + m * 2048 + k * 1024); } while (0)
; #define PG8_LDB(dst, b, h) do { _Pragma("unroll") for (int n = 0; n < 2; ++n) _Pragma("unroll") for (int k = 0; k < 2; ++k) dst[n][k] = *(const LAS bf16x8*)(lds + bbase[b][h] + n * 2048 + k * 1024); } while (0)
; #define PG8_WAIT_V(n) asm volatile("s_waitcnt vmcnt(" #n ")" ::: "memory")
; #define PG8_WAIT_L(n) asm volatile("s_waitcnt lgkmcnt(" #n ")" ::: "memory")
; #define PG8_BAR __builtin_amdgcn_s_barrier()
; #define PG8_SCHED __builtin_amdgcn_sched_barrier(0)
; template <class Epi>
; __device__ __forceinline__ void gemm_phase(LAS unsigned char* lds, const Gemm g, const StaticOrder& S, const Epi& E) {
;     ...
;         for (int t = 0; t < nt; t += 2) {
;             const bool last = (t == nt - 2);
;             const char* a2 = last ? nA : cA + (size_t)(t + 2) * kstep; const char* b2 = last ? nB : cB + (size_t)(t + 2) * kstep;
;             const char* a3 = a2 + kstep; const char* b3 = b2 + kstep;
;             const char* b1 = cB + (size_t)(t + 1) * kstep;
;             PG8_LDB(B0, 0, 0); PG8_SCHED; PG8_LDA(At, 0, 0); PG8_LDA(At2, 0, 1); PG8_STAGE(PG8_SB(1, 1), b1 + hstepB, voffB);
;             PG8_WAIT_V(8); PG8_WAIT_L(0); PG8_BAR; PG8_MMA2B(0, At, At2, B0); PG8_BAR; PG8_SCHED;
;             PG8_LDB(B0, 0, 1); PG8_STAGE(PG8_SB(0, 0), b2, voffB); PG8_STAGE(PG8_SA(0, 0), a2, voffA); PG8_STAGE(PG8_SA(0, 1), a2 + hstepA, voffA);
;             PG8_WAIT_V(8); PG8_WAIT_L(0); PG8_BAR; PG8_MMA2B(1, At, At2, B0); PG8_BAR; PG8_SCHED;
.LBB0_1027:
	ds_read_b128 v[68:71], v220
	ds_read_b128 v[84:87], v220 offset:1024
	ds_read_b128 v[88:91], v220 offset:2048
	ds_read_b128 v[92:95], v220 offset:3072
	s_add_u32 s12, s10, 0x100
	s_addc_u32 s13, s11, 0
	s_cmp_eq_u32 s69, 12
	s_cselect_b32 s14, s97, vcc_hi
	s_cselect_b32 s15, s7, s68
	s_cselect_b32 s84, vcc_lo, s12
	s_cselect_b32 s85, s39, s13
	s_add_u32 s16, s14, 0x80
	s_addc_u32 s17, s15, 0
	ds_read_b128 v[96:99], v221
	ds_read_b128 v[100:103], v221 offset:1024
	ds_read_b128 v[152:155], v221 offset:2048
	ds_read_b128 v[156:159], v221 offset:3072
	ds_read_b128 v[166:169], v221 offset:4096
	ds_read_b128 v[178:181], v221 offset:5120
	ds_read_b128 v[182:185], v221 offset:6144
	ds_read_b128 v[186:189], v221 offset:7168
	ds_read_b128 v[190:193], v221 offset:16384
	ds_read_b128 v[194:197], v221 offset:17408
	ds_read_b128 v[198:201], v221 offset:18432
	ds_read_b128 v[202:205], v221 offset:19456
	ds_read_b128 v[226:229], v221 offset:20480
	ds_read_b128 v[230:233], v221 offset:21504
	ds_read_b128 v[234:237], v221 offset:22528
	ds_read_b128 v[238:241], v221 offset:23552
	s_add_u32 s10, s10, 0x40080
	s_addc_u32 s11, s11, 0
	s_mov_b32 m0, s58
	s_nop 0
	global_load_lds_dwordx4 v217, s[10:11]
	s_mov_b32 m0, s60
	s_nop 0
	global_load_lds_dwordx4 v219, s[10:11]
	s_waitcnt vmcnt(8)
	s_waitcnt lgkmcnt(0)
	s_barrier
	v_mfma_f32_16x16x32_bf16 v[80:83], v[68:71], v[96:99], v[80:83]
	v_mfma_f32_16x16x32_bf16 v[76:79], v[88:91], v[96:99], v[76:79]
	v_mfma_f32_16x16x32_bf16 v[148:151], v[68:71], v[152:155], v[148:151]
	v_mfma_f32_16x16x32_bf16 v[52:55], v[88:91], v[152:155], v[52:55]
	v_mfma_f32_16x16x32_bf16 v[144:147], v[68:71], v[166:169], v[144:147]
	v_mfma_f32_16x16x32_bf16 v[48:51], v[88:91], v[166:169], v[48:51]
	v_mfma_f32_16x16x32_bf16 v[136:139], v[68:71], v[182:185], v[136:139]
	v_mfma_f32_16x16x32_bf16 v[40:43], v[88:91], v[182:185], v[40:43]
	v_mfma_f32_16x16x32_bf16 v[124:127], v[68:71], v[190:193], v[124:127]
	v_mfma_f32_16x16x32_bf16 v[28:31], v[88:91], v[190:193], v[28:31]
	v_mfma_f32_16x16x32_bf16 v[120:123], v[68:71], v[198:201], v[120:123]
	v_mfma_f32_16x16x32_bf16 v[24:27], v[88:91], v[198:201], v[24:27]
	v_mfma_f32_16x16x32_bf16 v[112:115], v[68:71], v[226:229], v[112:115]
	v_mfma_f32_16x16x32_bf16 v[16:19], v[88:91], v[226:229], v[16:19]
	v_mfma_f32_16x16x32_bf16 v[64:67], v[68:71], v[234:237], v[64:67]
	v_mfma_f32_16x16x32_bf16 v[4:7], v[88:91], v[234:237], v[4:7]
	v_mfma_f32_16x16x32_bf16 v[80:83], v[84:87], v[100:103], v[80:83]
	v_mfma_f32_16x16x32_bf16 v[76:79], v[92:95], v[100:103], v[76:79]
	v_mfma_f32_16x16x32_bf16 v[148:151], v[84:87], v[156:159], v[148:151]
	v_mfma_f32_16x16x32_bf16 v[52:55], v[92:95], v[156:159], v[52:55]
	v_mfma_f32_16x16x32_bf16 v[144:147], v[84:87], v[178:181], v[144:147]
	v_mfma_f32_16x16x32_bf16 v[48:51], v[92:95], v[178:181], v[48:51]
	v_mfma_f32_16x16x32_bf16 v[136:139], v[84:87], v[186:189], v[136:139]
	v_mfma_f32_16x16x32_bf16 v[40:43], v[92:95], v[186:189], v[40:43]
	v_mfma_f32_16x16x32_bf16 v[124:127], v[84:87], v[194:197], v[124:127]
	v_mfma_f32_16x16x32_bf16 v[28:31], v[92:95], v[194:197], v[28:31]
	v_mfma_f32_16x16x32_bf16 v[120:123], v[84:87], v[202:205], v[120:123]
	v_mfma_f32_16x16x32_bf16 v[24:27], v[92:95], v[202:205], v[24:27]
	v_mfma_f32_16x16x32_bf16 v[112:115], v[84:87], v[230:233], v[112:115]
	v_mfma_f32_16x16x32_bf16 v[16:19], v[92:95], v[230:233], v[16:19]
	v_mfma_f32_16x16x32_bf16 v[64:67], v[84:87], v[238:241], v[64:67]
	v_mfma_f32_16x16x32_bf16 v[4:7], v[92:95], v[238:241], v[4:7]
	s_barrier
	ds_read_b128 v[68:71], v222
	ds_read_b128 v[84:87], v222 offset:1024
	ds_read_b128 v[88:91], v222 offset:2048
	ds_read_b128 v[92:95], v222 offset:3072
	s_mov_b32 m0, s48
	s_nop 0
	global_load_lds_dwordx4 v217, s[84:85]
	s_mov_b32 m0, s49
	s_nop 0
	global_load_lds_dwordx4 v219, s[84:85]
	s_mov_b32 m0, s47
	s_nop 0
	global_load_lds_dwordx4 v216, s[14:15]
	s_mov_b32 m0, s50
	s_nop 0
	global_load_lds_dwordx4 v218, s[14:15]
	s_add_u32 s10, s14, 0x40000
	s_addc_u32 s11, s15, 0
	s_mov_b32 m0, s51
	s_nop 0
	global_load_lds_dwordx4 v216, s[10:11]
	s_mov_b32 m0, s52
	s_nop 0
	global_load_lds_dwordx4 v218, s[10:11]
	s_waitcnt vmcnt(8)
	s_waitcnt lgkmcnt(0)
	s_barrier
	v_mfma_f32_16x16x32_bf16 v[72:75], v[68:71], v[96:99], v[72:75]
	v_mfma_f32_16x16x32_bf16 v[56:59], v[88:91], v[96:99], v[56:59]
	v_mfma_f32_16x16x32_bf16 v[44:47], v[88:91], v[152:155], v[44:47]
	v_mfma_f32_16x16x32_bf16 v[36:39], v[88:91], v[166:169], v[36:39]
	v_mfma_f32_16x16x32_bf16 v[128:131], v[68:71], v[182:185], v[128:131]
	v_mfma_f32_16x16x32_bf16 v[32:35], v[88:91], v[182:185], v[32:35]
	v_mfma_f32_16x16x32_bf16 v[116:119], v[68:71], v[190:193], v[116:119]
	v_mfma_f32_16x16x32_bf16 v[20:23], v[88:91], v[190:193], v[20:23]
	v_mfma_f32_16x16x32_bf16 v[108:111], v[68:71], v[198:201], v[108:111]
	v_mfma_f32_16x16x32_bf16 v[12:15], v[88:91], v[198:201], v[12:15]
	v_mfma_f32_16x16x32_bf16 v[104:107], v[68:71], v[226:229], v[104:107]
	v_mfma_f32_16x16x32_bf16 v[8:11], v[88:91], v[226:229], v[8:11]
	v_mfma_f32_16x16x32_bf16 v[60:63], v[68:71], v[234:237], v[60:63]
	v_mfma_f32_16x16x32_bf16 v[0:3], v[88:91], v[234:237], v[0:3]
	v_mfma_f32_16x16x32_bf16 v[72:75], v[84:87], v[100:103], v[72:75]
	v_mfma_f32_16x16x32_bf16 v[56:59], v[92:95], v[100:103], v[56:59]
	v_mfma_f32_16x16x32_bf16 v[96:99], v[68:71], v[152:155], v[140:143]
	v_mfma_f32_16x16x32_bf16 v[44:47], v[92:95], v[156:159], v[44:47]
	v_mfma_f32_16x16x32_bf16 v[100:103], v[68:71], v[166:169], v[132:135]
	v_mfma_f32_16x16x32_bf16 v[36:39], v[92:95], v[178:181], v[36:39]
	v_mfma_f32_16x16x32_bf16 v[128:131], v[84:87], v[186:189], v[128:131]
	v_mfma_f32_16x16x32_bf16 v[32:35], v[92:95], v[186:189], v[32:35]
	v_mfma_f32_16x16x32_bf16 v[116:119], v[84:87], v[194:197], v[116:119]
	v_mfma_f32_16x16x32_bf16 v[20:23], v[92:95], v[194:197], v[20:23]
	v_mfma_f32_16x16x32_bf16 v[108:111], v[84:87], v[202:205], v[108:111]
	v_mfma_f32_16x16x32_bf16 v[12:15], v[92:95], v[202:205], v[12:15]
	v_mfma_f32_16x16x32_bf16 v[104:107], v[84:87], v[230:233], v[104:107]
	v_mfma_f32_16x16x32_bf16 v[8:11], v[92:95], v[230:233], v[8:11]
	v_mfma_f32_16x16x32_bf16 v[60:63], v[84:87], v[238:241], v[60:63]
	v_mfma_f32_16x16x32_bf16 v[0:3], v[92:95], v[238:241], v[0:3]
	v_mfma_f32_16x16x32_bf16 v[96:99], v[84:87], v[156:159], v[96:99]
	v_mfma_f32_16x16x32_bf16 v[100:103], v[84:87], v[178:181], v[100:103]
	s_barrier
; #define PG8_STAGE(bufoff, gbase, voff) do { _Pragma("unroll") for (int _i = 0; _i < 2; ++_i) { \
;         const unsigned _m0 = ldsu + (unsigned)(bufoff) + ldsw + (unsigned)(_i * 8192); \
;         asm volatile("s_mov_b32 m0, %2\n\ts_nop 0\n\tglobal_load_lds_dwordx4 %0, %1" :: "v"((voff)[_i]), "s"((const char*)(gbase)), "s"(_m0) : "memory"); } } while (0)
; #define PG8_LDA(dst, b, h) do { _Pragma("unroll") for (int m = 0; m < 4; ++m) _Pragma("unroll") for (int k = 0; k < 2; ++k) dst[m][k] = *(const LAS bf16x8*)(lds + PG8_SA(b, h) + aoff + m * 2048 + k * 1024); } while (0)
; #define PG8_LDB(dst, b, h) do { _Pragma("unroll") for (int n = 0; n < 2; ++n) _Pragma("unroll") for (int k = 0; k < 2; ++k) dst[n][k] = *(const LAS bf16x8*)(lds + bbase[b][h] + n * 2048 + k * 1024); } while (0)
; #define PG8_WAIT_V(n) asm volatile("s_waitcnt vmcnt(" #n ")" ::: "memory")
; #define PG8_WAIT_L(n) asm volatile("s_waitcnt lgkmcnt(" #n ")" ::: "memory")
; #define PG8_BAR __builtin_amdgcn_s_barrier()
; #define PG8_SCHED __builtin_amdgcn_sched_barrier(0)
; template <class Epi>
; __device__ __forceinline__ void gemm_phase(LAS unsigned char* lds, const Gemm g, const StaticOrder& S, const Epi& E) {
;     ...
;             PG8_LDB(B0, 1, 0); PG8_SCHED; PG8_LDA(At, 1, 0); PG8_LDA(At2, 1, 1); PG8_STAGE(PG8_SB(0, 1), b2 + hstepB, voffB);
;             PG8_WAIT_V(8); PG8_WAIT_L(0); PG8_BAR; PG8_MMA2B(0, At, At2, B0); PG8_BAR; PG8_SCHED;
;             PG8_LDB(B0, 1, 1); PG8_STAGE(PG8_SB(1, 0), b3, voffB); PG8_STAGE(PG8_SA(1, 0), a3, voffA); PG8_STAGE(PG8_SA(1, 1), a3 + hstepA, voffA);
;             PG8_WAIT_V(8); PG8_WAIT_L(0); PG8_BAR; PG8_MMA2B(1, At, At2, B0); PG8_BAR; PG8_SCHED;
;         }
;         if (wr == 0) PG8_BAR;
;     __device__ __forceinline__ void operator()(f32x4 (&acc)[2][2][4][2], const Unit& u, int wr, int wc, int fr, int fq) const {
;     ...
;           if (wr == 0) { const float* sp = ssq + ((size_t)u.pm * 256 + t) * 16; const f32x4 a = *(const f32x4*)sp, b = *(const f32x4*)(sp + 4), c = *(const f32x4*)(sp + 8), d = *(const f32x4*)(sp + 12);
;               const f32x4 q = (a + b) + (c + d); rsL[t] = rsqrtf(((q[0] + q[1]) + (q[2] + q[3])) * (1.0f / 1024.0f) + EPS); }
	ds_read_b128 v[68:71], v223
	ds_read_b128 v[84:87], v223 offset:1024
	ds_read_b128 v[88:91], v223 offset:2048
	ds_read_b128 v[92:95], v223 offset:3072
	ds_read_b128 v[132:135], v221 offset:32768
	ds_read_b128 v[140:143], v221 offset:33792
	ds_read_b128 v[152:155], v221 offset:34816
	ds_read_b128 v[156:159], v221 offset:35840
	ds_read_b128 v[166:169], v221 offset:36864
	ds_read_b128 v[178:181], v221 offset:37888
	ds_read_b128 v[182:185], v221 offset:38912
	ds_read_b128 v[186:189], v221 offset:39936
	ds_read_b128 v[190:193], v221 offset:49152
	ds_read_b128 v[194:197], v221 offset:50176
	ds_read_b128 v[198:201], v221 offset:51200
	ds_read_b128 v[202:205], v221 offset:52224
	ds_read_b128 v[226:229], v221 offset:53248
	ds_read_b128 v[230:233], v221 offset:54272
	ds_read_b128 v[234:237], v221 offset:55296
	ds_read_b128 v[238:241], v221 offset:56320
	s_add_u32 s10, s84, 0x40000
	s_addc_u32 s11, s85, 0
	s_mov_b32 m0, s53
	s_nop 0
	global_load_lds_dwordx4 v217, s[10:11]
	s_mov_b32 m0, s54
	s_nop 0
	global_load_lds_dwordx4 v219, s[10:11]
	s_waitcnt vmcnt(8)
	s_waitcnt lgkmcnt(0)
	s_barrier
	v_mfma_f32_16x16x32_bf16 v[80:83], v[68:71], v[132:135], v[80:83]
	v_mfma_f32_16x16x32_bf16 v[76:79], v[88:91], v[132:135], v[76:79]
	v_mfma_f32_16x16x32_bf16 v[148:151], v[68:71], v[152:155], v[148:151]
	v_mfma_f32_16x16x32_bf16 v[52:55], v[88:91], v[152:155], v[52:55]
	v_mfma_f32_16x16x32_bf16 v[144:147], v[68:71], v[166:169], v[144:147]
	v_mfma_f32_16x16x32_bf16 v[48:51], v[88:91], v[166:169], v[48:51]
	v_mfma_f32_16x16x32_bf16 v[136:139], v[68:71], v[182:185], v[136:139]
	v_mfma_f32_16x16x32_bf16 v[40:43], v[88:91], v[182:185], v[40:43]
	v_mfma_f32_16x16x32_bf16 v[124:127], v[68:71], v[190:193], v[124:127]
	v_mfma_f32_16x16x32_bf16 v[28:31], v[88:91], v[190:193], v[28:31]
	v_mfma_f32_16x16x32_bf16 v[120:123], v[68:71], v[198:201], v[120:123]
	v_mfma_f32_16x16x32_bf16 v[24:27], v[88:91], v[198:201], v[24:27]
	v_mfma_f32_16x16x32_bf16 v[112:115], v[68:71], v[226:229], v[112:115]
	v_mfma_f32_16x16x32_bf16 v[16:19], v[88:91], v[226:229], v[16:19]
	v_mfma_f32_16x16x32_bf16 v[64:67], v[68:71], v[234:237], v[64:67]
	v_mfma_f32_16x16x32_bf16 v[4:7], v[88:91], v[234:237], v[4:7]
	v_mfma_f32_16x16x32_bf16 v[80:83], v[84:87], v[140:143], v[80:83]
	v_mfma_f32_16x16x32_bf16 v[76:79], v[92:95], v[140:143], v[76:79]
	v_mfma_f32_16x16x32_bf16 v[148:151], v[84:87], v[156:159], v[148:151]
	v_mfma_f32_16x16x32_bf16 v[52:55], v[92:95], v[156:159], v[52:55]
	v_mfma_f32_16x16x32_bf16 v[144:147], v[84:87], v[178:181], v[144:147]
	v_mfma_f32_16x16x32_bf16 v[48:51], v[92:95], v[178:181], v[48:51]
	v_mfma_f32_16x16x32_bf16 v[136:139], v[84:87], v[186:189], v[136:139]
	v_mfma_f32_16x16x32_bf16 v[40:43], v[92:95], v[186:189], v[40:43]
	v_mfma_f32_16x16x32_bf16 v[124:127], v[84:87], v[194:197], v[124:127]
	v_mfma_f32_16x16x32_bf16 v[28:31], v[92:95], v[194:197], v[28:31]
	v_mfma_f32_16x16x32_bf16 v[120:123], v[84:87], v[202:205], v[120:123]
	v_mfma_f32_16x16x32_bf16 v[24:27], v[92:95], v[202:205], v[24:27]
	v_mfma_f32_16x16x32_bf16 v[112:115], v[84:87], v[230:233], v[112:115]
	v_mfma_f32_16x16x32_bf16 v[16:19], v[92:95], v[230:233], v[16:19]
	v_mfma_f32_16x16x32_bf16 v[64:67], v[84:87], v[238:241], v[64:67]
	v_mfma_f32_16x16x32_bf16 v[4:7], v[92:95], v[238:241], v[4:7]
	s_barrier
	s_add_u32 s10, s84, 0x80
	ds_read_b128 v[68:71], v224
	ds_read_b128 v[84:87], v224 offset:1024
	ds_read_b128 v[88:91], v224 offset:2048
	ds_read_b128 v[92:95], v224 offset:3072
	s_addc_u32 s11, s85, 0
	s_mov_b32 m0, s88
	s_nop 0
	global_load_lds_dwordx4 v217, s[10:11]
	s_mov_b32 m0, s89
	s_nop 0
	global_load_lds_dwordx4 v219, s[10:11]
	s_mov_b32 m0, s95
	s_nop 0
	global_load_lds_dwordx4 v216, s[16:17]
	s_mov_b32 m0, s37
	s_nop 0
	global_load_lds_dwordx4 v218, s[16:17]
	s_add_u32 s10, s14, 0x40080
	s_addc_u32 s11, s15, 0
	s_mov_b32 m0, s56
	s_nop 0
	global_load_lds_dwordx4 v216, s[10:11]
	s_mov_b32 m0, s57
	s_nop 0
	global_load_lds_dwordx4 v218, s[10:11]
	s_waitcnt vmcnt(8)
	s_waitcnt lgkmcnt(0)
	s_barrier
	v_mfma_f32_16x16x32_bf16 v[72:75], v[68:71], v[132:135], v[72:75]
	v_mfma_f32_16x16x32_bf16 v[56:59], v[88:91], v[132:135], v[56:59]
	v_mfma_f32_16x16x32_bf16 v[96:99], v[68:71], v[152:155], v[96:99]
	v_mfma_f32_16x16x32_bf16 v[72:75], v[84:87], v[140:143], v[72:75]
	v_mfma_f32_16x16x32_bf16 v[56:59], v[92:95], v[140:143], v[56:59]
	v_mfma_f32_16x16x32_bf16 v[140:143], v[84:87], v[156:159], v[96:99]
	v_mfma_f32_16x16x32_bf16 v[96:99], v[68:71], v[166:169], v[100:103]
	v_mfma_f32_16x16x32_bf16 v[132:135], v[84:87], v[178:181], v[96:99]
	v_mfma_f32_16x16x32_bf16 v[96:99], v[68:71], v[182:185], v[128:131]
	v_mfma_f32_16x16x32_bf16 v[128:131], v[84:87], v[186:189], v[96:99]
	v_mfma_f32_16x16x32_bf16 v[96:99], v[68:71], v[190:193], v[116:119]
	v_mfma_f32_16x16x32_bf16 v[116:119], v[84:87], v[194:197], v[96:99]
	v_mfma_f32_16x16x32_bf16 v[96:99], v[68:71], v[198:201], v[108:111]
	v_mfma_f32_16x16x32_bf16 v[44:47], v[88:91], v[152:155], v[44:47]
	v_mfma_f32_16x16x32_bf16 v[36:39], v[88:91], v[166:169], v[36:39]
	v_mfma_f32_16x16x32_bf16 v[32:35], v[88:91], v[182:185], v[32:35]
	v_mfma_f32_16x16x32_bf16 v[20:23], v[88:91], v[190:193], v[20:23]
	v_mfma_f32_16x16x32_bf16 v[108:111], v[84:87], v[202:205], v[96:99]
	v_mfma_f32_16x16x32_bf16 v[12:15], v[88:91], v[198:201], v[12:15]
	v_mfma_f32_16x16x32_bf16 v[96:99], v[68:71], v[226:229], v[104:107]
	v_mfma_f32_16x16x32_bf16 v[8:11], v[88:91], v[226:229], v[8:11]
	v_mfma_f32_16x16x32_bf16 v[60:63], v[68:71], v[234:237], v[60:63]
	v_mfma_f32_16x16x32_bf16 v[0:3], v[88:91], v[234:237], v[0:3]
	v_mfma_f32_16x16x32_bf16 v[44:47], v[92:95], v[156:159], v[44:47]
	v_mfma_f32_16x16x32_bf16 v[36:39], v[92:95], v[178:181], v[36:39]
	v_mfma_f32_16x16x32_bf16 v[32:35], v[92:95], v[186:189], v[32:35]
	v_mfma_f32_16x16x32_bf16 v[20:23], v[92:95], v[194:197], v[20:23]
	v_mfma_f32_16x16x32_bf16 v[12:15], v[92:95], v[202:205], v[12:15]
	v_mfma_f32_16x16x32_bf16 v[104:107], v[84:87], v[230:233], v[96:99]
	v_mfma_f32_16x16x32_bf16 v[8:11], v[92:95], v[230:233], v[8:11]
	v_mfma_f32_16x16x32_bf16 v[60:63], v[84:87], v[238:241], v[60:63]
	v_mfma_f32_16x16x32_bf16 v[0:3], v[92:95], v[238:241], v[0:3]
	s_barrier
	s_add_i32 s69, s69, 2
	s_add_u32 vcc_hi, vcc_hi, 0x100
	s_addc_u32 s68, s68, 0
	s_cmp_gt_u32 s69, 13
	s_mov_b64 s[10:11], s[12:13]
	s_cbranch_scc0 .LBB0_1027
	s_and_b64 vcc, exec, s[90:91]
	s_cbranch_vccz .LBB0_1030
	v_lshlrev_b32_e32 v68, 4, v215
	v_add3_u32 v68, v214, s59, v68
	s_ashr_i32 s97, s96, 31
	s_lshl_b64 s[12:13], s[96:97], 14
	v_ashrrev_i32_e32 v69, 31, v68
	s_add_u32 s12, s18, s12
	s_addc_u32 s13, s19, s13
	v_lshlrev_b64 v[70:71], 6, v[68:69]
	v_lshl_add_u64 v[70:71], s[12:13], 0, v[70:71]
	global_load_dwordx4 v[86:89], v[70:71], off
	global_load_dwordx4 v[90:93], v[70:71], off offset:16
	global_load_dwordx4 v[94:97], v[70:71], off offset:32
	global_load_dwordx4 v[98:101], v[70:71], off offset:48
	s_barrier

; #define PG8_STAGE(bufoff, gbase, voff) do { _Pragma("unroll") for (int _i = 0; _i < 2; ++_i) { \
;         const unsigned _m0 = ldsu + (unsigned)(bufoff) + ldsw + (unsigned)(_i * 8192); \
;         asm volatile("s_mov_b32 m0, %2\n\ts_nop 0\n\tglobal_load_lds_dwordx4 %0, %1" :: "v"((voff)[_i]), "s"((const char*)(gbase)), "s"(_m0) : "memory"); } } while (0)
; #define PG8_LDA(dst, b, h) do { _Pragma("unroll") for (int m = 0; m < 4; ++m) _Pragma("unroll") for (int k = 0; k < 2; ++k) dst[m][k] = *(const LAS bf16x8*)(lds + PG8_SA(b, h) + aoff + m * 2048 + k * 1024); } while (0)
; #define PG8_LDB(dst, b, h) do { _Pragma("unroll") for (int n = 0; n < 2; ++n) _Pragma("unroll") for (int k = 0; k < 2; ++k) dst[n][k] = *(const LAS bf16x8*)(lds + bbase[b][h] + n * 2048 + k * 1024); } while (0)
; #define PG8_WAIT_V(n) asm volatile("s_waitcnt vmcnt(" #n ")" ::: "memory")
; #define PG8_WAIT_L(n) asm volatile("s_waitcnt lgkmcnt(" #n ")" ::: "memory")
; #define PG8_BAR __builtin_amdgcn_s_barrier()
; #define PG8_SCHED __builtin_amdgcn_sched_barrier(0)
; template <class Epi>
; __device__ __forceinline__ void gemm_phase(LAS unsigned char* lds, const Gemm g, const StaticOrder& S, const Epi& E) {
;     ...
;         for (int t = 0; t < nt; t += 2) {
;             const bool last = (t == nt - 2);
;             const char* a2 = last ? nA : cA + (size_t)(t + 2) * kstep; const char* b2 = last ? nB : cB + (size_t)(t + 2) * kstep;
;             const char* a3 = a2 + kstep; const char* b3 = b2 + kstep;
;             const char* b1 = cB + (size_t)(t + 1) * kstep;
;             PG8_LDB(B0, 0, 0); PG8_SCHED; PG8_LDA(At, 0, 0); PG8_LDA(At2, 0, 1); PG8_STAGE(PG8_SB(1, 1), b1 + hstepB, voffB);
;             PG8_WAIT_V(8); PG8_WAIT_L(0); PG8_BAR; PG8_MMA2B(0, At, At2, B0); PG8_BAR; PG8_SCHED;
;             PG8_LDB(B0, 0, 1); PG8_STAGE(PG8_SB(0, 0), b2, voffB); PG8_STAGE(PG8_SA(0, 0), a2, voffA); PG8_STAGE(PG8_SA(0, 1), a2 + hstepA, voffA);
;             PG8_WAIT_V(8); PG8_WAIT_L(0); PG8_BAR; PG8_MMA2B(1, At, At2, B0); PG8_BAR; PG8_SCHED;
.LBB0_1140:
	ds_read_b128 v[128:131], v138
	ds_read_b128 v[144:147], v138 offset:1024
	ds_read_b128 v[148:151], v138 offset:2048
	ds_read_b128 v[152:155], v138 offset:3072
	s_cmp_eq_u32 s68, 40
	s_cselect_b32 s14, s4, s80
	s_cselect_b32 s15, s5, s81
	s_cselect_b32 s42, s10, s82
	s_cselect_b32 s43, s11, s83
	s_add_u32 s16, s14, 0x80
	s_addc_u32 s17, s15, 0
	s_add_u32 s38, s42, 0x80
	s_addc_u32 s39, s43, 0
	ds_read_b128 v[156:159], v139
	ds_read_b128 v[166:169], v139 offset:1024
	ds_read_b128 v[178:181], v139 offset:2048
	ds_read_b128 v[182:185], v139 offset:3072
	ds_read_b128 v[186:189], v139 offset:4096
	ds_read_b128 v[190:193], v139 offset:5120
	ds_read_b128 v[194:197], v139 offset:6144
	ds_read_b128 v[198:201], v139 offset:7168
	ds_read_b128 v[202:205], v139 offset:16384
	ds_read_b128 v[214:217], v139 offset:17408
	ds_read_b128 v[218:221], v139 offset:18432
	ds_read_b128 v[222:225], v139 offset:19456
	ds_read_b128 v[226:229], v139 offset:20480
	ds_read_b128 v[230:233], v139 offset:21504
	ds_read_b128 v[234:237], v139 offset:22528
	ds_read_b128 v[238:241], v139 offset:23552
	s_mov_b32 m0, s61
	s_nop 0
	global_load_lds_dwordx4 v133, s[12:13]
	s_mov_b32 m0, s63
	s_nop 0
	global_load_lds_dwordx4 v135, s[12:13]
	s_waitcnt vmcnt(8)
	s_waitcnt lgkmcnt(0)
	s_barrier
	v_mfma_f32_16x16x32_bf16 v[124:127], v[128:131], v[156:159], v[124:127]
	v_mfma_f32_16x16x32_bf16 v[120:123], v[148:151], v[156:159], v[120:123]
	v_mfma_f32_16x16x32_bf16 v[108:111], v[128:131], v[178:181], v[108:111]
	v_mfma_f32_16x16x32_bf16 v[104:107], v[148:151], v[178:181], v[104:107]
	v_mfma_f32_16x16x32_bf16 v[92:95], v[128:131], v[186:189], v[92:95]
	v_mfma_f32_16x16x32_bf16 v[88:91], v[148:151], v[186:189], v[88:91]
	v_mfma_f32_16x16x32_bf16 v[76:79], v[128:131], v[194:197], v[76:79]
	v_mfma_f32_16x16x32_bf16 v[72:75], v[148:151], v[194:197], v[72:75]
	v_mfma_f32_16x16x32_bf16 v[60:63], v[128:131], v[202:205], v[60:63]
	v_mfma_f32_16x16x32_bf16 v[56:59], v[148:151], v[202:205], v[56:59]
	v_mfma_f32_16x16x32_bf16 v[44:47], v[128:131], v[218:221], v[44:47]
	v_mfma_f32_16x16x32_bf16 v[40:43], v[148:151], v[218:221], v[40:43]
	v_mfma_f32_16x16x32_bf16 v[28:31], v[128:131], v[226:229], v[28:31]
	v_mfma_f32_16x16x32_bf16 v[24:27], v[148:151], v[226:229], v[24:27]
	v_mfma_f32_16x16x32_bf16 v[12:15], v[128:131], v[234:237], v[12:15]
	v_mfma_f32_16x16x32_bf16 v[8:11], v[148:151], v[234:237], v[8:11]
	v_mfma_f32_16x16x32_bf16 v[124:127], v[144:147], v[166:169], v[124:127]
	v_mfma_f32_16x16x32_bf16 v[120:123], v[152:155], v[166:169], v[120:123]
	v_mfma_f32_16x16x32_bf16 v[108:111], v[144:147], v[182:185], v[108:111]
	v_mfma_f32_16x16x32_bf16 v[104:107], v[152:155], v[182:185], v[104:107]
	v_mfma_f32_16x16x32_bf16 v[92:95], v[144:147], v[190:193], v[92:95]
	v_mfma_f32_16x16x32_bf16 v[88:91], v[152:155], v[190:193], v[88:91]
	v_mfma_f32_16x16x32_bf16 v[76:79], v[144:147], v[198:201], v[76:79]
	v_mfma_f32_16x16x32_bf16 v[72:75], v[152:155], v[198:201], v[72:75]
	v_mfma_f32_16x16x32_bf16 v[60:63], v[144:147], v[214:217], v[60:63]
	v_mfma_f32_16x16x32_bf16 v[56:59], v[152:155], v[214:217], v[56:59]
	v_mfma_f32_16x16x32_bf16 v[44:47], v[144:147], v[222:225], v[44:47]
	v_mfma_f32_16x16x32_bf16 v[40:43], v[152:155], v[222:225], v[40:43]
	v_mfma_f32_16x16x32_bf16 v[28:31], v[144:147], v[230:233], v[28:31]
	v_mfma_f32_16x16x32_bf16 v[24:27], v[152:155], v[230:233], v[24:27]
	v_mfma_f32_16x16x32_bf16 v[12:15], v[144:147], v[238:241], v[12:15]
	v_mfma_f32_16x16x32_bf16 v[8:11], v[152:155], v[238:241], v[8:11]
	s_barrier
	ds_read_b128 v[128:131], v140
	ds_read_b128 v[144:147], v140 offset:1024
	ds_read_b128 v[148:151], v140 offset:2048
	ds_read_b128 v[152:155], v140 offset:3072
	s_mov_b32 m0, s48
	s_nop 0
	global_load_lds_dwordx4 v133, s[42:43]
	s_mov_b32 m0, s49
	s_nop 0
	global_load_lds_dwordx4 v135, s[42:43]
	s_mov_b32 m0, s47
	s_nop 0
	global_load_lds_dwordx4 v132, s[14:15]
	s_mov_b32 m0, s50
	s_nop 0
	global_load_lds_dwordx4 v134, s[14:15]
	s_add_u32 s84, s14, 0xb0000
	s_addc_u32 s85, s15, 0
	s_mov_b32 m0, s51
	s_nop 0
	global_load_lds_dwordx4 v132, s[84:85]
	s_mov_b32 m0, s52
	s_nop 0
	global_load_lds_dwordx4 v134, s[84:85]
	s_waitcnt vmcnt(8)
	s_waitcnt lgkmcnt(0)
	s_barrier
	v_mfma_f32_16x16x32_bf16 v[116:119], v[128:131], v[156:159], v[116:119]
	v_mfma_f32_16x16x32_bf16 v[112:115], v[148:151], v[156:159], v[112:115]
	v_mfma_f32_16x16x32_bf16 v[100:103], v[128:131], v[178:181], v[100:103]
	v_mfma_f32_16x16x32_bf16 v[96:99], v[148:151], v[178:181], v[96:99]
	v_mfma_f32_16x16x32_bf16 v[84:87], v[128:131], v[186:189], v[84:87]
	v_mfma_f32_16x16x32_bf16 v[80:83], v[148:151], v[186:189], v[80:83]
	v_mfma_f32_16x16x32_bf16 v[68:71], v[128:131], v[194:197], v[68:71]
	v_mfma_f32_16x16x32_bf16 v[64:67], v[148:151], v[194:197], v[64:67]
	v_mfma_f32_16x16x32_bf16 v[52:55], v[128:131], v[202:205], v[52:55]
	v_mfma_f32_16x16x32_bf16 v[48:51], v[148:151], v[202:205], v[48:51]
	v_mfma_f32_16x16x32_bf16 v[36:39], v[128:131], v[218:221], v[36:39]
	v_mfma_f32_16x16x32_bf16 v[32:35], v[148:151], v[218:221], v[32:35]
	v_mfma_f32_16x16x32_bf16 v[20:23], v[128:131], v[226:229], v[20:23]
	v_mfma_f32_16x16x32_bf16 v[16:19], v[148:151], v[226:229], v[16:19]
	v_mfma_f32_16x16x32_bf16 v[4:7], v[128:131], v[234:237], v[4:7]
	v_mfma_f32_16x16x32_bf16 v[0:3], v[148:151], v[234:237], v[0:3]
	v_mfma_f32_16x16x32_bf16 v[116:119], v[144:147], v[166:169], v[116:119]
	v_mfma_f32_16x16x32_bf16 v[112:115], v[152:155], v[166:169], v[112:115]
	v_mfma_f32_16x16x32_bf16 v[100:103], v[144:147], v[182:185], v[100:103]
	v_mfma_f32_16x16x32_bf16 v[96:99], v[152:155], v[182:185], v[96:99]
	v_mfma_f32_16x16x32_bf16 v[84:87], v[144:147], v[190:193], v[84:87]
	v_mfma_f32_16x16x32_bf16 v[80:83], v[152:155], v[190:193], v[80:83]
	v_mfma_f32_16x16x32_bf16 v[68:71], v[144:147], v[198:201], v[68:71]
	v_mfma_f32_16x16x32_bf16 v[64:67], v[152:155], v[198:201], v[64:67]
	v_mfma_f32_16x16x32_bf16 v[52:55], v[144:147], v[214:217], v[52:55]
	v_mfma_f32_16x16x32_bf16 v[48:51], v[152:155], v[214:217], v[48:51]
	v_mfma_f32_16x16x32_bf16 v[36:39], v[144:147], v[222:225], v[36:39]
	v_mfma_f32_16x16x32_bf16 v[32:35], v[152:155], v[222:225], v[32:35]
	v_mfma_f32_16x16x32_bf16 v[20:23], v[144:147], v[230:233], v[20:23]
	v_mfma_f32_16x16x32_bf16 v[16:19], v[152:155], v[230:233], v[16:19]
	v_mfma_f32_16x16x32_bf16 v[4:7], v[144:147], v[238:241], v[4:7]
	v_mfma_f32_16x16x32_bf16 v[0:3], v[152:155], v[238:241], v[0:3]
	s_barrier
; #define PG8_STAGE(bufoff, gbase, voff) do { _Pragma("unroll") for (int _i = 0; _i < 2; ++_i) { \
;         const unsigned _m0 = ldsu + (unsigned)(bufoff) + ldsw + (unsigned)(_i * 8192); \
;         asm volatile("s_mov_b32 m0, %2\n\ts_nop 0\n\tglobal_load_lds_dwordx4 %0, %1" :: "v"((voff)[_i]), "s"((const char*)(gbase)), "s"(_m0) : "memory"); } } while (0)
; #define PG8_LDA(dst, b, h) do { _Pragma("unroll") for (int m = 0; m < 4; ++m) _Pragma("unroll") for (int k = 0; k < 2; ++k) dst[m][k] = *(const LAS bf16x8*)(lds + PG8_SA(b, h) + aoff + m * 2048 + k * 1024); } while (0)
; #define PG8_LDB(dst, b, h) do { _Pragma("unroll") for (int n = 0; n < 2; ++n) _Pragma("unroll") for (int k = 0; k < 2; ++k) dst[n][k] = *(const LAS bf16x8*)(lds + bbase[b][h] + n * 2048 + k * 1024); } while (0)
; #define PG8_WAIT_V(n) asm volatile("s_waitcnt vmcnt(" #n ")" ::: "memory")
; #define PG8_WAIT_L(n) asm volatile("s_waitcnt lgkmcnt(" #n ")" ::: "memory")
; #define PG8_BAR __builtin_amdgcn_s_barrier()
; #define PG8_SCHED __builtin_amdgcn_sched_barrier(0)
; template <class Epi>
; __device__ __forceinline__ void gemm_phase(LAS unsigned char* lds, const Gemm g, const StaticOrder& S, const Epi& E) {
;     ...
;             PG8_LDB(B0, 1, 0); PG8_SCHED; PG8_LDA(At, 1, 0); PG8_LDA(At2, 1, 1); PG8_STAGE(PG8_SB(0, 1), b2 + hstepB, voffB);
;             PG8_WAIT_V(8); PG8_WAIT_L(0); PG8_BAR; PG8_MMA2B(0, At, At2, B0); PG8_BAR; PG8_SCHED;
;             PG8_LDB(B0, 1, 1); PG8_STAGE(PG8_SB(1, 0), b3, voffB); PG8_STAGE(PG8_SA(1, 0), a3, voffA); PG8_STAGE(PG8_SA(1, 1), a3 + hstepA, voffA);
;             PG8_WAIT_V(8); PG8_WAIT_L(0); PG8_BAR; PG8_MMA2B(1, At, At2, B0); PG8_BAR; PG8_SCHED;
	ds_read_b128 v[128:131], v141
	ds_read_b128 v[144:147], v141 offset:1024
	ds_read_b128 v[148:151], v141 offset:2048
	ds_read_b128 v[152:155], v141 offset:3072
	ds_read_b128 v[156:159], v139 offset:32768
	ds_read_b128 v[166:169], v139 offset:33792
	ds_read_b128 v[178:181], v139 offset:34816
	ds_read_b128 v[182:185], v139 offset:35840
	ds_read_b128 v[186:189], v139 offset:36864
	ds_read_b128 v[190:193], v139 offset:37888
	ds_read_b128 v[194:197], v139 offset:38912
	ds_read_b128 v[198:201], v139 offset:39936
	ds_read_b128 v[202:205], v139 offset:49152
	ds_read_b128 v[214:217], v139 offset:50176
	ds_read_b128 v[218:221], v139 offset:51200
	ds_read_b128 v[222:225], v139 offset:52224
	ds_read_b128 v[226:229], v139 offset:53248
	ds_read_b128 v[230:233], v139 offset:54272
	ds_read_b128 v[234:237], v139 offset:55296
	ds_read_b128 v[238:241], v139 offset:56320
	s_add_u32 s42, s42, 0xb0000
	s_addc_u32 s43, s43, 0
	s_mov_b32 m0, s53
	s_nop 0
	global_load_lds_dwordx4 v133, s[42:43]
	s_mov_b32 m0, s54
	s_nop 0
	global_load_lds_dwordx4 v135, s[42:43]
	s_waitcnt vmcnt(8)
	s_waitcnt lgkmcnt(0)
	s_barrier
	v_mfma_f32_16x16x32_bf16 v[124:127], v[128:131], v[156:159], v[124:127]
	v_mfma_f32_16x16x32_bf16 v[120:123], v[148:151], v[156:159], v[120:123]
	v_mfma_f32_16x16x32_bf16 v[108:111], v[128:131], v[178:181], v[108:111]
	v_mfma_f32_16x16x32_bf16 v[104:107], v[148:151], v[178:181], v[104:107]
	v_mfma_f32_16x16x32_bf16 v[92:95], v[128:131], v[186:189], v[92:95]
	v_mfma_f32_16x16x32_bf16 v[88:91], v[148:151], v[186:189], v[88:91]
	v_mfma_f32_16x16x32_bf16 v[76:79], v[128:131], v[194:197], v[76:79]
	v_mfma_f32_16x16x32_bf16 v[72:75], v[148:151], v[194:197], v[72:75]
	v_mfma_f32_16x16x32_bf16 v[60:63], v[128:131], v[202:205], v[60:63]
	v_mfma_f32_16x16x32_bf16 v[56:59], v[148:151], v[202:205], v[56:59]
	v_mfma_f32_16x16x32_bf16 v[44:47], v[128:131], v[218:221], v[44:47]
	v_mfma_f32_16x16x32_bf16 v[40:43], v[148:151], v[218:221], v[40:43]
	v_mfma_f32_16x16x32_bf16 v[28:31], v[128:131], v[226:229], v[28:31]
	v_mfma_f32_16x16x32_bf16 v[24:27], v[148:151], v[226:229], v[24:27]
	v_mfma_f32_16x16x32_bf16 v[12:15], v[128:131], v[234:237], v[12:15]
	v_mfma_f32_16x16x32_bf16 v[8:11], v[148:151], v[234:237], v[8:11]
	v_mfma_f32_16x16x32_bf16 v[124:127], v[144:147], v[166:169], v[124:127]
	v_mfma_f32_16x16x32_bf16 v[120:123], v[152:155], v[166:169], v[120:123]
	v_mfma_f32_16x16x32_bf16 v[108:111], v[144:147], v[182:185], v[108:111]
	v_mfma_f32_16x16x32_bf16 v[104:107], v[152:155], v[182:185], v[104:107]
	v_mfma_f32_16x16x32_bf16 v[92:95], v[144:147], v[190:193], v[92:95]
	v_mfma_f32_16x16x32_bf16 v[88:91], v[152:155], v[190:193], v[88:91]
	v_mfma_f32_16x16x32_bf16 v[76:79], v[144:147], v[198:201], v[76:79]
	v_mfma_f32_16x16x32_bf16 v[72:75], v[152:155], v[198:201], v[72:75]
	v_mfma_f32_16x16x32_bf16 v[60:63], v[144:147], v[214:217], v[60:63]
	v_mfma_f32_16x16x32_bf16 v[56:59], v[152:155], v[214:217], v[56:59]
	v_mfma_f32_16x16x32_bf16 v[44:47], v[144:147], v[222:225], v[44:47]
	v_mfma_f32_16x16x32_bf16 v[40:43], v[152:155], v[222:225], v[40:43]
	v_mfma_f32_16x16x32_bf16 v[28:31], v[144:147], v[230:233], v[28:31]
	v_mfma_f32_16x16x32_bf16 v[24:27], v[152:155], v[230:233], v[24:27]
	v_mfma_f32_16x16x32_bf16 v[12:15], v[144:147], v[238:241], v[12:15]
	v_mfma_f32_16x16x32_bf16 v[8:11], v[152:155], v[238:241], v[8:11]
	s_barrier
	ds_read_b128 v[128:131], v142
	ds_read_b128 v[144:147], v142 offset:1024
	ds_read_b128 v[148:151], v142 offset:2048
	ds_read_b128 v[152:155], v142 offset:3072
	s_mov_b32 m0, s55
	s_nop 0
	global_load_lds_dwordx4 v133, s[38:39]
	s_mov_b32 m0, s56
	s_nop 0
	global_load_lds_dwordx4 v135, s[38:39]
	s_mov_b32 m0, s57
	s_nop 0
	global_load_lds_dwordx4 v132, s[16:17]
	s_mov_b32 m0, s58
	s_nop 0
	global_load_lds_dwordx4 v134, s[16:17]
	s_add_u32 s14, s14, 0xb0080
	s_addc_u32 s15, s15, 0
	s_mov_b32 m0, s59
	s_nop 0
	global_load_lds_dwordx4 v132, s[14:15]
	s_mov_b32 m0, s60
	s_nop 0
	global_load_lds_dwordx4 v134, s[14:15]
	s_waitcnt vmcnt(8)
	s_waitcnt lgkmcnt(0)
	s_barrier
	v_mfma_f32_16x16x32_bf16 v[116:119], v[128:131], v[156:159], v[116:119]
	v_mfma_f32_16x16x32_bf16 v[112:115], v[148:151], v[156:159], v[112:115]
	v_mfma_f32_16x16x32_bf16 v[100:103], v[128:131], v[178:181], v[100:103]
	v_mfma_f32_16x16x32_bf16 v[96:99], v[148:151], v[178:181], v[96:99]
	v_mfma_f32_16x16x32_bf16 v[84:87], v[128:131], v[186:189], v[84:87]
	v_mfma_f32_16x16x32_bf16 v[80:83], v[148:151], v[186:189], v[80:83]
	v_mfma_f32_16x16x32_bf16 v[68:71], v[128:131], v[194:197], v[68:71]
	v_mfma_f32_16x16x32_bf16 v[64:67], v[148:151], v[194:197], v[64:67]
	v_mfma_f32_16x16x32_bf16 v[52:55], v[128:131], v[202:205], v[52:55]
	v_mfma_f32_16x16x32_bf16 v[48:51], v[148:151], v[202:205], v[48:51]
	v_mfma_f32_16x16x32_bf16 v[36:39], v[128:131], v[218:221], v[36:39]
	v_mfma_f32_16x16x32_bf16 v[32:35], v[148:151], v[218:221], v[32:35]
	v_mfma_f32_16x16x32_bf16 v[20:23], v[128:131], v[226:229], v[20:23]
	v_mfma_f32_16x16x32_bf16 v[16:19], v[148:151], v[226:229], v[16:19]
	v_mfma_f32_16x16x32_bf16 v[4:7], v[128:131], v[234:237], v[4:7]
	v_mfma_f32_16x16x32_bf16 v[0:3], v[148:151], v[234:237], v[0:3]
	v_mfma_f32_16x16x32_bf16 v[116:119], v[144:147], v[166:169], v[116:119]
	v_mfma_f32_16x16x32_bf16 v[112:115], v[152:155], v[166:169], v[112:115]
	v_mfma_f32_16x16x32_bf16 v[100:103], v[144:147], v[182:185], v[100:103]
	v_mfma_f32_16x16x32_bf16 v[96:99], v[152:155], v[182:185], v[96:99]
	v_mfma_f32_16x16x32_bf16 v[84:87], v[144:147], v[190:193], v[84:87]
	v_mfma_f32_16x16x32_bf16 v[80:83], v[152:155], v[190:193], v[80:83]
	v_mfma_f32_16x16x32_bf16 v[68:71], v[144:147], v[198:201], v[68:71]
	v_mfma_f32_16x16x32_bf16 v[64:67], v[152:155], v[198:201], v[64:67]
	v_mfma_f32_16x16x32_bf16 v[52:55], v[144:147], v[214:217], v[52:55]
	v_mfma_f32_16x16x32_bf16 v[48:51], v[152:155], v[214:217], v[48:51]
	v_mfma_f32_16x16x32_bf16 v[36:39], v[144:147], v[222:225], v[36:39]
	v_mfma_f32_16x16x32_bf16 v[32:35], v[152:155], v[222:225], v[32:35]
	v_mfma_f32_16x16x32_bf16 v[20:23], v[144:147], v[230:233], v[20:23]
	v_mfma_f32_16x16x32_bf16 v[16:19], v[152:155], v[230:233], v[16:19]
	v_mfma_f32_16x16x32_bf16 v[4:7], v[144:147], v[238:241], v[4:7]
	v_mfma_f32_16x16x32_bf16 v[0:3], v[152:155], v[238:241], v[0:3]
	s_barrier
	s_add_i32 s68, s68, 2
	s_add_u32 s12, s12, 0x100
	s_addc_u32 s13, s13, 0
	s_add_u32 s80, s80, 0x100
	s_addc_u32 s81, s81, 0
	s_add_u32 s82, s82, 0x100
	s_addc_u32 s83, s83, 0
	s_cmp_gt_u32 s68, 41
	s_cbranch_scc0 .LBB0_1140
	s_and_b64 vcc, exec, s[2:3]
	s_cbranch_vccz .LBB0_1143
	s_barrier
